# on top of v14: the already-satisfied lgkmcnt(0) of the B1/At-only compute intervals moved before the opening barrier (24 sites)
# speedup vs baseline: 1.0018x; 1.0018x over previous
; #define PG8_STAGE(bufoff, gbase) do { _Pragma("unroll") for (int _i = 0; _i < 2; ++_i) \
;         __builtin_amdgcn_global_load_lds((const unsigned*)((const char*)(gbase) + voff[_i]), (LAS unsigned*)(lds + (bufoff) + ldsw + _i * 8192), 16, 0, 0); } while (0)
; #define PG8_LDA(dst, b, h) do { _Pragma("unroll") for (int m = 0; m < 4; ++m) _Pragma("unroll") for (int k = 0; k < 2; ++k) dst[m][k] = *(const LAS bf16x8*)(lds + PG8_SA(b, h) + aoff + m * 2048 + k * 1024); } while (0)
; #define PG8_LDB(dst, b, h) do { _Pragma("unroll") for (int n = 0; n < 2; ++n) _Pragma("unroll") for (int k = 0; k < 2; ++k) dst[n][k] = *(const LAS bf16x8*)(lds + PG8_SB(b, h) + boff + n * 2048 + k * 1024); } while (0)
; #define PG8_MMA(ai, bj, At, Bt) do { __builtin_amdgcn_s_setprio(1); _Pragma("unroll") for (int m = 0; m < 4; ++m) _Pragma("unroll") for (int n = 0; n < 2; ++n) _Pragma("unroll") for (int k = 0; k < 2; ++k) \
;         acc[ai][bj][m][n] = __builtin_amdgcn_mfma_f32_16x16x32_bf16(Bt[n][k], At[m][k], acc[ai][bj][m][n], 0, 0, 0); __builtin_amdgcn_s_setprio(0); } while (0)
; #define PG8_WAIT_L(n) asm volatile("s_waitcnt lgkmcnt(" #n ")" ::: "memory")
; #define PG8_BAR __builtin_amdgcn_s_barrier()
; #define PG8_SCHED __builtin_amdgcn_sched_barrier(0)
; template <class Epi>
; DI void gemm_phase(LAS unsigned char* lds, const Gemm g, const StaticOrder& S, const Epi& E) {
;     ...
;         for (int t = 0; t < nt; t += 2) {
;             const bool last = (t == nt - 2);
;             const char* a1 = cA + (size_t)(t + 1) * kstep;
;             const char* a2 = last ? nA : cA + (size_t)(t + 2) * kstep; const char* b2 = last ? nB : cB + (size_t)(t + 2) * kstep;
;             const char* a3 = a2 + kstep; const char* b3 = b2 + kstep;
;             PG8_LDB(B0, 0, 0); PG8_SCHED; PG8_LDA(At, 0, 0); PG8_STAGE(PG8_SA(1, 1), a1 + hstep);
;             PG8_WAIT_L(8); PG8_BAR; PG8_WAIT_L(0); PG8_MMA(0, 0, At, B0); PG8_BAR; PG8_SCHED;
;             PG8_LDB(B1, 0, 1); PG8_STAGE(PG8_SB(0, 0), b2);
;             PG8_BAR; PG8_WAIT_L(0); PG8_MMA(0, 1, At, B1); PG8_BAR;
;             PG8_LDA(At, 0, 1); PG8_STAGE(PG8_SA(0, 0), a2);
;             PG8_BAR; PG8_WAIT_L(0); PG8_MMA(1, 0, At, B0); PG8_BAR; PG8_SCHED;
.LBB0_37:
	s_add_u32 s20, s18, 0xfff80080
	s_addc_u32 s21, s19, -1
	s_add_i32 s39, 0, 0x10000
	v_add_u32_e32 v150, s39, v135
	ds_read_b128 v[138:141], v150
	ds_read_b128 v[142:145], v150 offset:1024
	ds_read_b128 v[146:149], v150 offset:2048
	ds_read_b128 v[150:153], v150 offset:3072
	s_cmp_eq_u32 s38, 28
	s_cselect_b32 s23, s4, s21
	s_cselect_b32 s22, s5, s20
	s_cselect_b32 s21, s9, s37
	s_cselect_b32 s20, s11, s33
	v_lshl_add_u64 v[154:155], s[18:19], 0, v[130:131]
	s_add_i32 m0, s28, 0xc000
	ds_read_b128 v[186:189], v137
	ds_read_b128 v[190:193], v137 offset:1024
	ds_read_b128 v[194:197], v137 offset:2048
	ds_read_b128 v[198:201], v137 offset:3072
	ds_read_b128 v[202:205], v137 offset:4096
	ds_read_b128 v[206:209], v137 offset:5120
	ds_read_b128 v[210:213], v137 offset:6144
	ds_read_b128 v[214:217], v137 offset:7168
	global_load_lds_dwordx4 v[154:155], off
	v_lshl_add_u64 v[154:155], s[18:19], 0, v[132:133]
	s_add_i32 m0, s28, 0xe000
	s_nop 0
	global_load_lds_dwordx4 v[154:155], off
	s_waitcnt lgkmcnt(8)
	s_setprio 1
	s_barrier
	s_waitcnt lgkmcnt(0)
	v_mfma_f32_16x16x32_bf16 v[124:127], v[138:141], v[186:189], v[124:127]
	v_mfma_f32_16x16x32_bf16 v[120:123], v[146:149], v[186:189], v[120:123]
	v_mfma_f32_16x16x32_bf16 v[108:111], v[138:141], v[194:197], v[108:111]
	v_mfma_f32_16x16x32_bf16 v[104:107], v[146:149], v[194:197], v[104:107]
	v_mfma_f32_16x16x32_bf16 v[92:95], v[138:141], v[202:205], v[92:95]
	v_mfma_f32_16x16x32_bf16 v[88:91], v[146:149], v[202:205], v[88:91]
	v_mfma_f32_16x16x32_bf16 v[76:79], v[138:141], v[210:213], v[76:79]
	v_mfma_f32_16x16x32_bf16 v[72:75], v[146:149], v[210:213], v[72:75]
	v_mfma_f32_16x16x32_bf16 v[124:127], v[142:145], v[190:193], v[124:127]
	v_mfma_f32_16x16x32_bf16 v[120:123], v[150:153], v[190:193], v[120:123]
	v_mfma_f32_16x16x32_bf16 v[108:111], v[142:145], v[198:201], v[108:111]
	v_mfma_f32_16x16x32_bf16 v[104:107], v[150:153], v[198:201], v[104:107]
	v_mfma_f32_16x16x32_bf16 v[92:95], v[142:145], v[206:209], v[92:95]
	v_mfma_f32_16x16x32_bf16 v[88:91], v[150:153], v[206:209], v[88:91]
	v_mfma_f32_16x16x32_bf16 v[76:79], v[142:145], v[214:217], v[76:79]
	v_mfma_f32_16x16x32_bf16 v[72:75], v[150:153], v[214:217], v[72:75]
	s_setprio 0
	s_barrier
	s_add_i32 s42, 0, 0x14000
	v_add_u32_e32 v154, s42, v135
	s_add_i32 s39, s39, s27
	ds_read_b128 v[226:229], v154
	ds_read_b128 v[230:233], v154 offset:1024
	ds_read_b128 v[234:237], v154 offset:2048
	ds_read_b128 v[238:241], v154 offset:3072
	v_lshl_add_u64 v[154:155], s[20:21], 0, v[158:159]
	s_mov_b32 m0, s39
	v_lshl_add_u64 v[218:219], s[20:21], 0, v[128:129]
	global_load_lds_dwordx4 v[154:155], off
	s_add_i32 m0, s39, 0x2000
	s_nop 0
	global_load_lds_dwordx4 v[218:219], off
	s_waitcnt lgkmcnt(0)
	s_setprio 1
	s_barrier
	v_mfma_f32_16x16x32_bf16 v[116:119], v[226:229], v[186:189], v[116:119]
	v_mfma_f32_16x16x32_bf16 v[112:115], v[234:237], v[186:189], v[112:115]
	v_mfma_f32_16x16x32_bf16 v[100:103], v[226:229], v[194:197], v[100:103]
	v_mfma_f32_16x16x32_bf16 v[96:99], v[234:237], v[194:197], v[96:99]
	v_mfma_f32_16x16x32_bf16 v[84:87], v[226:229], v[202:205], v[84:87]
	v_mfma_f32_16x16x32_bf16 v[80:83], v[234:237], v[202:205], v[80:83]
	v_mfma_f32_16x16x32_bf16 v[68:71], v[226:229], v[210:213], v[68:71]
	v_mfma_f32_16x16x32_bf16 v[64:67], v[234:237], v[210:213], v[64:67]
	v_mfma_f32_16x16x32_bf16 v[116:119], v[230:233], v[190:193], v[116:119]
	v_mfma_f32_16x16x32_bf16 v[112:115], v[238:241], v[190:193], v[112:115]
	v_mfma_f32_16x16x32_bf16 v[100:103], v[230:233], v[198:201], v[100:103]
	v_mfma_f32_16x16x32_bf16 v[96:99], v[238:241], v[198:201], v[96:99]
	v_mfma_f32_16x16x32_bf16 v[84:87], v[230:233], v[206:209], v[84:87]
	v_mfma_f32_16x16x32_bf16 v[80:83], v[238:241], v[206:209], v[80:83]
	v_mfma_f32_16x16x32_bf16 v[68:71], v[230:233], v[214:217], v[68:71]
	v_mfma_f32_16x16x32_bf16 v[64:67], v[238:241], v[214:217], v[64:67]
	s_setprio 0
	s_mov_b32 m0, s28
	v_lshl_add_u64 v[220:221], s[22:23], 0, v[158:159]
	s_barrier
	ds_read_b128 v[186:189], v137 offset:16384
	ds_read_b128 v[190:193], v137 offset:17408
	ds_read_b128 v[194:197], v137 offset:18432
	ds_read_b128 v[198:201], v137 offset:19456
	ds_read_b128 v[202:205], v137 offset:20480
	ds_read_b128 v[206:209], v137 offset:21504
	ds_read_b128 v[210:213], v137 offset:22528
	ds_read_b128 v[214:217], v137 offset:23552
	global_load_lds_dwordx4 v[220:221], off
	v_lshl_add_u64 v[242:243], s[22:23], 0, v[128:129]
	s_mov_b32 m0, s29
	s_nop 0
	global_load_lds_dwordx4 v[242:243], off
	s_waitcnt lgkmcnt(0)
	s_setprio 1
	s_barrier
	v_mfma_f32_16x16x32_bf16 v[60:63], v[138:141], v[186:189], v[60:63]
	v_mfma_f32_16x16x32_bf16 v[56:59], v[146:149], v[186:189], v[56:59]
	v_mfma_f32_16x16x32_bf16 v[44:47], v[138:141], v[194:197], v[44:47]
	v_mfma_f32_16x16x32_bf16 v[40:43], v[146:149], v[194:197], v[40:43]
	v_mfma_f32_16x16x32_bf16 v[28:31], v[138:141], v[202:205], v[28:31]
	v_mfma_f32_16x16x32_bf16 v[24:27], v[146:149], v[202:205], v[24:27]
	v_mfma_f32_16x16x32_bf16 v[12:15], v[138:141], v[210:213], v[12:15]
	v_mfma_f32_16x16x32_bf16 v[8:11], v[146:149], v[210:213], v[8:11]
	v_mfma_f32_16x16x32_bf16 v[60:63], v[142:145], v[190:193], v[60:63]
	v_mfma_f32_16x16x32_bf16 v[56:59], v[150:153], v[190:193], v[56:59]
	v_mfma_f32_16x16x32_bf16 v[44:47], v[142:145], v[198:201], v[44:47]
	v_mfma_f32_16x16x32_bf16 v[40:43], v[150:153], v[198:201], v[40:43]
	v_mfma_f32_16x16x32_bf16 v[28:31], v[142:145], v[206:209], v[28:31]
	v_mfma_f32_16x16x32_bf16 v[24:27], v[150:153], v[206:209], v[24:27]
	v_mfma_f32_16x16x32_bf16 v[12:15], v[142:145], v[214:217], v[12:15]
	v_mfma_f32_16x16x32_bf16 v[8:11], v[150:153], v[214:217], v[8:11]
	s_setprio 0
	s_barrier
; #define PG8_STAGE(bufoff, gbase) do { _Pragma("unroll") for (int _i = 0; _i < 2; ++_i) \
;         __builtin_amdgcn_global_load_lds((const unsigned*)((const char*)(gbase) + voff[_i]), (LAS unsigned*)(lds + (bufoff) + ldsw + _i * 8192), 16, 0, 0); } while (0)
; #define PG8_LDA(dst, b, h) do { _Pragma("unroll") for (int m = 0; m < 4; ++m) _Pragma("unroll") for (int k = 0; k < 2; ++k) dst[m][k] = *(const LAS bf16x8*)(lds + PG8_SA(b, h) + aoff + m * 2048 + k * 1024); } while (0)
; #define PG8_LDB(dst, b, h) do { _Pragma("unroll") for (int n = 0; n < 2; ++n) _Pragma("unroll") for (int k = 0; k < 2; ++k) dst[n][k] = *(const LAS bf16x8*)(lds + PG8_SB(b, h) + boff + n * 2048 + k * 1024); } while (0)
; #define PG8_MMA(ai, bj, At, Bt) do { __builtin_amdgcn_s_setprio(1); _Pragma("unroll") for (int m = 0; m < 4; ++m) _Pragma("unroll") for (int n = 0; n < 2; ++n) _Pragma("unroll") for (int k = 0; k < 2; ++k) \
;         acc[ai][bj][m][n] = __builtin_amdgcn_mfma_f32_16x16x32_bf16(Bt[n][k], At[m][k], acc[ai][bj][m][n], 0, 0, 0); __builtin_amdgcn_s_setprio(0); } while (0)
; #define PG8_WAIT_V(n) asm volatile("s_waitcnt vmcnt(" #n ")" ::: "memory")
; #define PG8_WAIT_L(n) asm volatile("s_waitcnt lgkmcnt(" #n ")" ::: "memory")
; #define PG8_BAR __builtin_amdgcn_s_barrier()
; #define PG8_SCHED __builtin_amdgcn_sched_barrier(0)
; template <class Epi>
; DI void gemm_phase(LAS unsigned char* lds, const Gemm g, const StaticOrder& S, const Epi& E) {
;     ...
;             PG8_STAGE(PG8_SB(0, 1), b2 + hstep);
;             PG8_WAIT_V(6); PG8_BAR; PG8_MMA(1, 1, At, B1); PG8_BAR;
;             PG8_LDB(B0, 1, 0); PG8_SCHED; PG8_LDA(At, 1, 0); PG8_STAGE(PG8_SA(0, 1), a2 + hstep);
;             PG8_WAIT_L(8); PG8_BAR; PG8_WAIT_L(0); PG8_MMA(0, 0, At, B0); PG8_BAR; PG8_SCHED;
;             PG8_LDB(B1, 1, 1); PG8_STAGE(PG8_SB(1, 0), b3);
;             PG8_BAR; PG8_WAIT_L(0); PG8_MMA(0, 1, At, B1); PG8_BAR;
;             PG8_LDA(At, 1, 1); PG8_STAGE(PG8_SA(1, 0), a3);
;             PG8_BAR; PG8_WAIT_L(0); PG8_MMA(1, 0, At, B0); PG8_BAR; PG8_SCHED;
	s_add_u32 s40, s20, 0x80000
	s_addc_u32 s41, s21, 0
	s_add_i32 s39, s42, s27
	v_lshl_add_u64 v[138:139], s[40:41], 0, v[158:159]
	s_mov_b32 m0, s39
	s_nop 0
	global_load_lds_dwordx4 v[138:139], off
	v_lshl_add_u64 v[138:139], s[40:41], 0, v[128:129]
	s_add_i32 m0, s39, 0x2000
	s_nop 0
	global_load_lds_dwordx4 v[138:139], off
	s_waitcnt vmcnt(6)
	s_setprio 1
	s_barrier
	v_mfma_f32_16x16x32_bf16 v[52:55], v[226:229], v[186:189], v[52:55]
	v_mfma_f32_16x16x32_bf16 v[48:51], v[234:237], v[186:189], v[48:51]
	v_mfma_f32_16x16x32_bf16 v[36:39], v[226:229], v[194:197], v[36:39]
	v_mfma_f32_16x16x32_bf16 v[32:35], v[234:237], v[194:197], v[32:35]
	v_mfma_f32_16x16x32_bf16 v[20:23], v[226:229], v[202:205], v[20:23]
	v_mfma_f32_16x16x32_bf16 v[16:19], v[234:237], v[202:205], v[16:19]
	v_mfma_f32_16x16x32_bf16 v[4:7], v[226:229], v[210:213], v[4:7]
	v_mfma_f32_16x16x32_bf16 v[0:3], v[234:237], v[210:213], v[0:3]
	v_mfma_f32_16x16x32_bf16 v[52:55], v[230:233], v[190:193], v[52:55]
	v_mfma_f32_16x16x32_bf16 v[48:51], v[238:241], v[190:193], v[48:51]
	v_mfma_f32_16x16x32_bf16 v[36:39], v[230:233], v[198:201], v[36:39]
	v_mfma_f32_16x16x32_bf16 v[32:35], v[238:241], v[198:201], v[32:35]
	v_mfma_f32_16x16x32_bf16 v[20:23], v[230:233], v[206:209], v[20:23]
	v_mfma_f32_16x16x32_bf16 v[16:19], v[238:241], v[206:209], v[16:19]
	v_mfma_f32_16x16x32_bf16 v[4:7], v[230:233], v[214:217], v[4:7]
	v_mfma_f32_16x16x32_bf16 v[0:3], v[238:241], v[214:217], v[0:3]
	s_setprio 0
	s_add_i32 s39, 0, 0x18000
	v_add_u32_e32 v150, s39, v135
	s_barrier
	ds_read_b128 v[138:141], v150
	ds_read_b128 v[142:145], v150 offset:1024
	ds_read_b128 v[146:149], v150 offset:2048
	ds_read_b128 v[150:153], v150 offset:3072
	s_add_u32 s22, s22, 0x80000
	s_addc_u32 s23, s23, 0
	s_mov_b32 m0, s30
	v_lshl_add_u64 v[226:227], s[22:23], 0, v[158:159]
	ds_read_b128 v[186:189], v137 offset:32768
	ds_read_b128 v[190:193], v137 offset:33792
	ds_read_b128 v[194:197], v137 offset:34816
	ds_read_b128 v[198:201], v137 offset:35840
	ds_read_b128 v[202:205], v137 offset:36864
	ds_read_b128 v[206:209], v137 offset:37888
	ds_read_b128 v[210:213], v137 offset:38912
	ds_read_b128 v[214:217], v137 offset:39936
	global_load_lds_dwordx4 v[226:227], off
	v_lshl_add_u64 v[226:227], s[22:23], 0, v[128:129]
	s_mov_b32 m0, s31
	s_nop 0
	global_load_lds_dwordx4 v[226:227], off
	s_waitcnt lgkmcnt(8)
	s_setprio 1
	s_barrier
	s_waitcnt lgkmcnt(0)
	v_mfma_f32_16x16x32_bf16 v[124:127], v[138:141], v[186:189], v[124:127]
	v_mfma_f32_16x16x32_bf16 v[120:123], v[146:149], v[186:189], v[120:123]
	v_mfma_f32_16x16x32_bf16 v[108:111], v[138:141], v[194:197], v[108:111]
	v_mfma_f32_16x16x32_bf16 v[104:107], v[146:149], v[194:197], v[104:107]
	v_mfma_f32_16x16x32_bf16 v[92:95], v[138:141], v[202:205], v[92:95]
	v_mfma_f32_16x16x32_bf16 v[88:91], v[146:149], v[202:205], v[88:91]
	v_mfma_f32_16x16x32_bf16 v[76:79], v[138:141], v[210:213], v[76:79]
	v_mfma_f32_16x16x32_bf16 v[72:75], v[146:149], v[210:213], v[72:75]
	v_mfma_f32_16x16x32_bf16 v[124:127], v[142:145], v[190:193], v[124:127]
	v_mfma_f32_16x16x32_bf16 v[120:123], v[150:153], v[190:193], v[120:123]
	v_mfma_f32_16x16x32_bf16 v[108:111], v[142:145], v[198:201], v[108:111]
	v_mfma_f32_16x16x32_bf16 v[104:107], v[150:153], v[198:201], v[104:107]
	v_mfma_f32_16x16x32_bf16 v[92:95], v[142:145], v[206:209], v[92:95]
	v_mfma_f32_16x16x32_bf16 v[88:91], v[150:153], v[206:209], v[88:91]
	v_mfma_f32_16x16x32_bf16 v[76:79], v[142:145], v[214:217], v[76:79]
	v_mfma_f32_16x16x32_bf16 v[72:75], v[150:153], v[214:217], v[72:75]
	s_setprio 0
	s_barrier
	s_add_i32 s22, 0, 0x1c000
	s_add_i32 s23, s39, s27
	v_add_u32_e32 v225, s22, v135
	v_lshl_add_u64 v[154:155], v[154:155], 0, s[94:95]
	s_mov_b32 m0, s23
	ds_read_b128 v[226:229], v225
	ds_read_b128 v[230:233], v225 offset:1024
	ds_read_b128 v[234:237], v225 offset:2048
	ds_read_b128 v[238:241], v225 offset:3072
	global_load_lds_dwordx4 v[154:155], off
	v_lshl_add_u64 v[154:155], v[218:219], 0, s[94:95]
	s_add_i32 m0, s23, 0x2000
	s_nop 0
	global_load_lds_dwordx4 v[154:155], off
	s_waitcnt lgkmcnt(0)
	s_setprio 1
	s_barrier
	v_mfma_f32_16x16x32_bf16 v[116:119], v[226:229], v[186:189], v[116:119]
	v_mfma_f32_16x16x32_bf16 v[112:115], v[234:237], v[186:189], v[112:115]
	v_mfma_f32_16x16x32_bf16 v[100:103], v[226:229], v[194:197], v[100:103]
	v_mfma_f32_16x16x32_bf16 v[96:99], v[234:237], v[194:197], v[96:99]
	v_mfma_f32_16x16x32_bf16 v[84:87], v[226:229], v[202:205], v[84:87]
	v_mfma_f32_16x16x32_bf16 v[80:83], v[234:237], v[202:205], v[80:83]
	v_mfma_f32_16x16x32_bf16 v[68:71], v[226:229], v[210:213], v[68:71]
	v_mfma_f32_16x16x32_bf16 v[64:67], v[234:237], v[210:213], v[64:67]
	v_mfma_f32_16x16x32_bf16 v[116:119], v[230:233], v[190:193], v[116:119]
	v_mfma_f32_16x16x32_bf16 v[112:115], v[238:241], v[190:193], v[112:115]
	v_mfma_f32_16x16x32_bf16 v[100:103], v[230:233], v[198:201], v[100:103]
	v_mfma_f32_16x16x32_bf16 v[96:99], v[238:241], v[198:201], v[96:99]
	v_mfma_f32_16x16x32_bf16 v[84:87], v[230:233], v[206:209], v[84:87]
	v_mfma_f32_16x16x32_bf16 v[80:83], v[238:241], v[206:209], v[80:83]
	v_mfma_f32_16x16x32_bf16 v[68:71], v[230:233], v[214:217], v[68:71]
	v_mfma_f32_16x16x32_bf16 v[64:67], v[238:241], v[214:217], v[64:67]
	s_setprio 0
	s_mov_b32 m0, s34
	v_lshl_add_u64 v[154:155], v[220:221], 0, s[94:95]
	s_barrier
	ds_read_b128 v[186:189], v137 offset:49152
	ds_read_b128 v[190:193], v137 offset:50176
	ds_read_b128 v[194:197], v137 offset:51200
	ds_read_b128 v[198:201], v137 offset:52224
	ds_read_b128 v[202:205], v137 offset:53248
	ds_read_b128 v[206:209], v137 offset:54272
	ds_read_b128 v[210:213], v137 offset:55296
	ds_read_b128 v[214:217], v137 offset:56320
	global_load_lds_dwordx4 v[154:155], off
	v_lshl_add_u64 v[154:155], v[242:243], 0, s[94:95]
	s_mov_b32 m0, s35
	s_nop 0
	global_load_lds_dwordx4 v[154:155], off
	s_waitcnt lgkmcnt(0)
	s_setprio 1
	s_barrier
; #define PG8_STAGE(bufoff, gbase) do { _Pragma("unroll") for (int _i = 0; _i < 2; ++_i) \
;         __builtin_amdgcn_global_load_lds((const unsigned*)((const char*)(gbase) + voff[_i]), (LAS unsigned*)(lds + (bufoff) + ldsw + _i * 8192), 16, 0, 0); } while (0)
; #define PG8_MMA(ai, bj, At, Bt) do { __builtin_amdgcn_s_setprio(1); _Pragma("unroll") for (int m = 0; m < 4; ++m) _Pragma("unroll") for (int n = 0; n < 2; ++n) _Pragma("unroll") for (int k = 0; k < 2; ++k) \
;         acc[ai][bj][m][n] = __builtin_amdgcn_mfma_f32_16x16x32_bf16(Bt[n][k], At[m][k], acc[ai][bj][m][n], 0, 0, 0); __builtin_amdgcn_s_setprio(0); } while (0)
; #define PG8_WAIT_V(n) asm volatile("s_waitcnt vmcnt(" #n ")" ::: "memory")
; #define PG8_WAIT_L(n) asm volatile("s_waitcnt lgkmcnt(" #n ")" ::: "memory")
; #define PG8_BAR __builtin_amdgcn_s_barrier()
; #define PG8_SCHED __builtin_amdgcn_sched_barrier(0)
; template <class Epi>
; DI void gemm_phase(LAS unsigned char* lds, const Gemm g, const StaticOrder& S, const Epi& E) {
;     ...
;             PG8_BAR; PG8_WAIT_L(0); PG8_MMA(1, 0, At, B0); PG8_BAR; PG8_SCHED;
;             PG8_STAGE(PG8_SB(1, 1), b3 + hstep);
;             PG8_WAIT_V(6); PG8_BAR; PG8_MMA(1, 1, At, B1); PG8_BAR;
;     DI void operator()(const f32x4 (&acc)[2][2][4][2], const Unit& u, int wr, int wc, int fr, int fq) const {
;         const int row0 = u.pm * BM + wr * 64 + fr, col0 = u.pn * HALF + wc * 32 + 8 * fq;
; #pragma unroll
;         for (int ai = 0; ai < 2; ++ai)
; #pragma unroll
;             for (int m = 0; m < 4; ++m) { float hv[8];
; #pragma unroll
;                 for (int n = 0; n < 2; ++n)
; #pragma unroll
;                     for (int e = 0; e < 4; ++e) { const float gt = acc[ai][0][m][n][e], up = acc[ai][1][m][n][e];
;                         hv[n * 4 + e] = gt * __builtin_amdgcn_rcpf(1.f + __builtin_amdgcn_exp2f(-1.4426950408889634f * gt)) * up; }
;                 *(u32x4*)(H + (size_t)(row0 + ai * HALF + m * 16) * DFF + col0) = (u32x4){pk(hv[0], hv[1]), pk(hv[2], hv[3]), pk(hv[4], hv[5]), pk(hv[6], hv[7])}; }
	v_mfma_f32_16x16x32_bf16 v[60:63], v[138:141], v[186:189], v[60:63]
	v_mfma_f32_16x16x32_bf16 v[56:59], v[146:149], v[186:189], v[56:59]
	v_mfma_f32_16x16x32_bf16 v[44:47], v[138:141], v[194:197], v[44:47]
	v_mfma_f32_16x16x32_bf16 v[40:43], v[146:149], v[194:197], v[40:43]
	v_mfma_f32_16x16x32_bf16 v[28:31], v[138:141], v[202:205], v[28:31]
	v_mfma_f32_16x16x32_bf16 v[24:27], v[146:149], v[202:205], v[24:27]
	v_mfma_f32_16x16x32_bf16 v[12:15], v[138:141], v[210:213], v[12:15]
	v_mfma_f32_16x16x32_bf16 v[8:11], v[146:149], v[210:213], v[8:11]
	v_mfma_f32_16x16x32_bf16 v[60:63], v[142:145], v[190:193], v[60:63]
	v_mfma_f32_16x16x32_bf16 v[56:59], v[150:153], v[190:193], v[56:59]
	v_mfma_f32_16x16x32_bf16 v[44:47], v[142:145], v[198:201], v[44:47]
	v_mfma_f32_16x16x32_bf16 v[40:43], v[150:153], v[198:201], v[40:43]
	v_mfma_f32_16x16x32_bf16 v[28:31], v[142:145], v[206:209], v[28:31]
	v_mfma_f32_16x16x32_bf16 v[24:27], v[150:153], v[206:209], v[24:27]
	v_mfma_f32_16x16x32_bf16 v[12:15], v[142:145], v[214:217], v[12:15]
	v_mfma_f32_16x16x32_bf16 v[8:11], v[150:153], v[214:217], v[8:11]
	s_setprio 0
	s_barrier
	s_add_u32 s20, s20, 0x80080
	s_addc_u32 s21, s21, 0
	s_add_i32 s22, s22, s27
	v_lshl_add_u64 v[138:139], s[20:21], 0, v[158:159]
	s_mov_b32 m0, s22
	s_nop 0
	global_load_lds_dwordx4 v[138:139], off
	v_lshl_add_u64 v[138:139], s[20:21], 0, v[128:129]
	s_add_i32 m0, s22, 0x2000
	s_nop 0
	global_load_lds_dwordx4 v[138:139], off
	s_waitcnt vmcnt(6)
	s_setprio 1
	s_barrier
	v_mfma_f32_16x16x32_bf16 v[52:55], v[226:229], v[186:189], v[52:55]
	v_mfma_f32_16x16x32_bf16 v[48:51], v[234:237], v[186:189], v[48:51]
	v_mfma_f32_16x16x32_bf16 v[36:39], v[226:229], v[194:197], v[36:39]
	v_mfma_f32_16x16x32_bf16 v[32:35], v[234:237], v[194:197], v[32:35]
	v_mfma_f32_16x16x32_bf16 v[20:23], v[226:229], v[202:205], v[20:23]
	v_mfma_f32_16x16x32_bf16 v[16:19], v[234:237], v[202:205], v[16:19]
	v_mfma_f32_16x16x32_bf16 v[4:7], v[226:229], v[210:213], v[4:7]
	v_mfma_f32_16x16x32_bf16 v[0:3], v[234:237], v[210:213], v[0:3]
	v_mfma_f32_16x16x32_bf16 v[52:55], v[230:233], v[190:193], v[52:55]
	v_mfma_f32_16x16x32_bf16 v[48:51], v[238:241], v[190:193], v[48:51]
	v_mfma_f32_16x16x32_bf16 v[36:39], v[230:233], v[198:201], v[36:39]
	v_mfma_f32_16x16x32_bf16 v[32:35], v[238:241], v[198:201], v[32:35]
	v_mfma_f32_16x16x32_bf16 v[20:23], v[230:233], v[206:209], v[20:23]
	v_mfma_f32_16x16x32_bf16 v[16:19], v[238:241], v[206:209], v[16:19]
	v_mfma_f32_16x16x32_bf16 v[4:7], v[230:233], v[214:217], v[4:7]
	v_mfma_f32_16x16x32_bf16 v[0:3], v[238:241], v[214:217], v[0:3]
	s_setprio 0
	s_add_i32 s38, s38, 2
	s_add_u32 s18, s18, 0x100
	s_addc_u32 s19, s19, 0
	s_add_u32 s33, s33, 0x100
	s_addc_u32 s37, s37, 0
	s_cmp_gt_u32 s38, 29
	s_barrier
	s_cbranch_scc0 .LBB0_37
	v_mul_f32_e32 v139, 0xbfb8aa3b, v124
	v_exp_f32_e32 v139, v139
	v_lshl_or_b32 v140, s2, 7, v136
	v_lshl_add_u32 v138, s3, 8, v134
	v_ashrrev_i32_e32 v141, 31, v140
	v_add_f32_e32 v139, 1.0, v139
	v_rcp_f32_e32 v142, v139
	v_mul_f32_e32 v139, 0xbfb8aa3b, v125
	v_exp_f32_e32 v139, v139
	s_movk_i32 s4, 0x2c00
	s_and_b64 vcc, exec, s[6:7]
	s_mov_b64 s[20:21], s[16:17]
	v_add_f32_e32 v139, 1.0, v139
	v_rcp_f32_e32 v143, v139
	v_mul_f32_e32 v139, 0xbfb8aa3b, v126
	v_exp_f32_e32 v139, v139
	s_mov_b64 s[18:19], s[14:15]
	v_pk_mul_f32 v[124:125], v[124:125], v[142:143]
	v_add_f32_e32 v139, 1.0, v139
	v_rcp_f32_e32 v144, v139
	v_mul_f32_e32 v139, 0xbfb8aa3b, v127
	v_exp_f32_e32 v139, v139
	v_pk_mul_f32 v[116:117], v[124:125], v[116:117]
	v_add_f32_e32 v139, 1.0, v139
	v_rcp_f32_e32 v145, v139
	v_mul_f32_e32 v139, 0xbfb8aa3b, v120
	v_exp_f32_e32 v139, v139
	v_cvt_pk_bf16_f32 v116, v116, v117
	v_pk_mul_f32 v[124:125], v[126:127], v[144:145]
	v_add_f32_e32 v139, 1.0, v139
	v_rcp_f32_e32 v146, v139
	v_mul_f32_e32 v139, 0xbfb8aa3b, v121
	v_exp_f32_e32 v139, v139
	v_pk_mul_f32 v[118:119], v[124:125], v[118:119]
	v_add_f32_e32 v139, 1.0, v139
	v_rcp_f32_e32 v147, v139
	v_mul_f32_e32 v139, 0xbfb8aa3b, v122
	v_exp_f32_e32 v139, v139
	v_cvt_pk_bf16_f32 v117, v118, v119
	v_pk_mul_f32 v[118:119], v[120:121], v[146:147]
	v_add_f32_e32 v139, 1.0, v139
	v_rcp_f32_e32 v148, v139
	v_mul_f32_e32 v139, 0xbfb8aa3b, v123
	v_exp_f32_e32 v139, v139
	v_pk_mul_f32 v[112:113], v[118:119], v[112:113]
	v_add_f32_e32 v139, 1.0, v139
	v_rcp_f32_e32 v149, v139
	v_cvt_pk_bf16_f32 v118, v112, v113
	v_pk_mul_f32 v[112:113], v[122:123], v[148:149]
	s_nop 0
	v_pk_mul_f32 v[112:113], v[112:113], v[114:115]
	v_lshlrev_b64 v[114:115], 1, v[140:141]
	v_cvt_pk_bf16_f32 v119, v112, v113
	v_mov_b64_e32 v[112:113], s[54:55]
	v_mad_i64_i32 v[120:121], s[2:3], v138, s4, v[112:113]
	v_lshl_add_u64 v[120:121], v[120:121], 0, v[114:115]
	global_store_dwordx4 v[120:121], v[116:119], off
	v_mul_f32_e32 v120, 0xbfb8aa3b, v104
	v_mul_f32_e32 v121, 0xbfb8aa3b, v105
	v_mul_f32_e32 v116, 0xbfb8aa3b, v108
	v_mul_f32_e32 v117, 0xbfb8aa3b, v109
	v_exp_f32_e32 v116, v116
	v_exp_f32_e32 v117, v117
	v_mul_f32_e32 v118, 0xbfb8aa3b, v110
	v_mul_f32_e32 v119, 0xbfb8aa3b, v111
	v_exp_f32_e32 v118, v118
	v_exp_f32_e32 v119, v119
	v_exp_f32_e32 v120, v120
	v_exp_f32_e32 v121, v121
	v_add_f32_e32 v116, 1.0, v116
	v_add_f32_e32 v117, 1.0, v117
	v_mul_f32_e32 v122, 0xbfb8aa3b, v106
	v_mul_f32_e32 v123, 0xbfb8aa3b, v107
	v_rcp_f32_e32 v116, v116
	v_rcp_f32_e32 v117, v117
	v_add_f32_e32 v118, 1.0, v118
	v_add_f32_e32 v119, 1.0, v119
	v_exp_f32_e32 v122, v122
	v_exp_f32_e32 v123, v123
	v_rcp_f32_e32 v118, v118
	v_rcp_f32_e32 v119, v119
	v_add_f32_e32 v120, 1.0, v120
	v_add_f32_e32 v121, 1.0, v121
	v_rcp_f32_e32 v120, v120
	v_rcp_f32_e32 v121, v121
	v_add_f32_e32 v122, 1.0, v122
;     DI void operator()(const f32x4 (&acc)[2][2][4][2], const Unit& u, int wr, int wc, int fr, int fq) const {
;         const int row0 = u.pm * BM + wr * 64 + fr, col0 = u.pn * HALF + wc * 32 + 8 * fq;
; #pragma unroll
;         for (int ai = 0; ai < 2; ++ai)
; #pragma unroll
;             for (int m = 0; m < 4; ++m) { float hv[8];
; #pragma unroll
;                 for (int n = 0; n < 2; ++n)
; #pragma unroll
;                     for (int e = 0; e < 4; ++e) { const float gt = acc[ai][0][m][n][e], up = acc[ai][1][m][n][e];
;                         hv[n * 4 + e] = gt * __builtin_amdgcn_rcpf(1.f + __builtin_amdgcn_exp2f(-1.4426950408889634f * gt)) * up; }
;                 *(u32x4*)(H + (size_t)(row0 + ai * HALF + m * 16) * DFF + col0) = (u32x4){pk(hv[0], hv[1]), pk(hv[2], hv[3]), pk(hv[4], hv[5]), pk(hv[6], hv[7])}; }
	v_add_f32_e32 v123, 1.0, v123
	v_pk_mul_f32 v[108:109], v[108:109], v[116:117]
	v_rcp_f32_e32 v122, v122
	v_rcp_f32_e32 v123, v123
	v_pk_mul_f32 v[100:101], v[108:109], v[100:101]
	v_pk_mul_f32 v[108:109], v[110:111], v[118:119]
	v_cvt_pk_bf16_f32 v100, v100, v101
	v_pk_mul_f32 v[102:103], v[108:109], v[102:103]
	s_nop 0
	v_cvt_pk_bf16_f32 v101, v102, v103
	v_pk_mul_f32 v[102:103], v[104:105], v[120:121]
	s_nop 0
	v_pk_mul_f32 v[96:97], v[102:103], v[96:97]
	s_nop 0
	v_cvt_pk_bf16_f32 v102, v96, v97
	v_pk_mul_f32 v[96:97], v[106:107], v[122:123]
	s_nop 0
	v_pk_mul_f32 v[96:97], v[96:97], v[98:99]
	v_mul_f32_e32 v98, 0xbfb8aa3b, v94
	v_cvt_pk_bf16_f32 v103, v96, v97
	v_or_b32_e32 v96, 16, v138
	v_mad_i64_i32 v[96:97], s[2:3], v96, s4, v[112:113]
	v_lshl_add_u64 v[96:97], v[96:97], 0, v[114:115]
	global_store_dwordx4 v[96:97], v[100:103], off
	v_mul_f32_e32 v96, 0xbfb8aa3b, v92
	v_mul_f32_e32 v97, 0xbfb8aa3b, v93
	v_exp_f32_e32 v96, v96
	v_exp_f32_e32 v97, v97
	v_mul_f32_e32 v99, 0xbfb8aa3b, v95
	v_exp_f32_e32 v98, v98
	v_exp_f32_e32 v99, v99
	v_mul_f32_e32 v100, 0xbfb8aa3b, v88
	v_mul_f32_e32 v101, 0xbfb8aa3b, v89
	v_exp_f32_e32 v100, v100
	v_exp_f32_e32 v101, v101
	v_add_f32_e32 v96, 1.0, v96
	v_add_f32_e32 v97, 1.0, v97
	v_mul_f32_e32 v102, 0xbfb8aa3b, v90
	v_mul_f32_e32 v103, 0xbfb8aa3b, v91
	v_rcp_f32_e32 v96, v96
	v_rcp_f32_e32 v97, v97
	v_add_f32_e32 v98, 1.0, v98
	v_add_f32_e32 v99, 1.0, v99
	v_exp_f32_e32 v102, v102
	v_exp_f32_e32 v103, v103
	v_rcp_f32_e32 v98, v98
	v_rcp_f32_e32 v99, v99
	v_add_f32_e32 v100, 1.0, v100
	v_add_f32_e32 v101, 1.0, v101
	v_rcp_f32_e32 v100, v100
	v_rcp_f32_e32 v101, v101
	v_add_f32_e32 v102, 1.0, v102
	v_add_f32_e32 v103, 1.0, v103
	v_pk_mul_f32 v[92:93], v[92:93], v[96:97]
	v_rcp_f32_e32 v102, v102
	v_rcp_f32_e32 v103, v103
	v_pk_mul_f32 v[84:85], v[92:93], v[84:85]
	v_pk_mul_f32 v[92:93], v[94:95], v[98:99]
	v_cvt_pk_bf16_f32 v84, v84, v85
	v_pk_mul_f32 v[86:87], v[92:93], v[86:87]
	s_nop 0
	v_cvt_pk_bf16_f32 v85, v86, v87
	v_pk_mul_f32 v[86:87], v[88:89], v[100:101]
	s_nop 0
	v_pk_mul_f32 v[80:81], v[86:87], v[80:81]
	s_nop 0
	v_cvt_pk_bf16_f32 v86, v80, v81
	v_pk_mul_f32 v[80:81], v[90:91], v[102:103]
	s_nop 0
	v_pk_mul_f32 v[80:81], v[80:81], v[82:83]
	v_mul_f32_e32 v82, 0xbfb8aa3b, v78
	v_cvt_pk_bf16_f32 v87, v80, v81
	v_or_b32_e32 v80, 32, v138
	v_mad_i64_i32 v[80:81], s[2:3], v80, s4, v[112:113]
	v_lshl_add_u64 v[80:81], v[80:81], 0, v[114:115]
	global_store_dwordx4 v[80:81], v[84:87], off
	v_mul_f32_e32 v80, 0xbfb8aa3b, v76
	v_mul_f32_e32 v81, 0xbfb8aa3b, v77
	v_exp_f32_e32 v80, v80
	v_exp_f32_e32 v81, v81
	v_mul_f32_e32 v83, 0xbfb8aa3b, v79
	v_exp_f32_e32 v82, v82
	v_exp_f32_e32 v83, v83
	v_mul_f32_e32 v84, 0xbfb8aa3b, v72
	v_mul_f32_e32 v85, 0xbfb8aa3b, v73
	v_exp_f32_e32 v84, v84
	v_exp_f32_e32 v85, v85
	v_add_f32_e32 v80, 1.0, v80
	v_add_f32_e32 v81, 1.0, v81
	v_mul_f32_e32 v86, 0xbfb8aa3b, v74
	v_mul_f32_e32 v87, 0xbfb8aa3b, v75
	v_rcp_f32_e32 v80, v80
	v_rcp_f32_e32 v81, v81
	v_add_f32_e32 v82, 1.0, v82
	v_add_f32_e32 v83, 1.0, v83
	v_exp_f32_e32 v86, v86
	v_exp_f32_e32 v87, v87
	v_rcp_f32_e32 v82, v82
	v_rcp_f32_e32 v83, v83
	v_add_f32_e32 v84, 1.0, v84
	v_add_f32_e32 v85, 1.0, v85
	v_rcp_f32_e32 v84, v84
	v_rcp_f32_e32 v85, v85
	v_add_f32_e32 v86, 1.0, v86
	v_add_f32_e32 v87, 1.0, v87
	v_pk_mul_f32 v[76:77], v[76:77], v[80:81]
	v_rcp_f32_e32 v86, v86
	v_rcp_f32_e32 v87, v87
	v_pk_mul_f32 v[68:69], v[76:77], v[68:69]
	v_pk_mul_f32 v[76:77], v[78:79], v[82:83]
	v_cvt_pk_bf16_f32 v68, v68, v69
	v_pk_mul_f32 v[70:71], v[76:77], v[70:71]
	s_nop 0
	v_cvt_pk_bf16_f32 v69, v70, v71
	v_pk_mul_f32 v[70:71], v[72:73], v[84:85]
	v_add_u32_e32 v72, 0x80, v138
	v_pk_mul_f32 v[64:65], v[70:71], v[64:65]
	s_nop 0
	v_cvt_pk_bf16_f32 v70, v64, v65
	v_pk_mul_f32 v[64:65], v[74:75], v[86:87]
	s_nop 0
	v_pk_mul_f32 v[64:65], v[64:65], v[66:67]
	v_mul_f32_e32 v66, 0xbfb8aa3b, v62
	v_cvt_pk_bf16_f32 v71, v64, v65
	v_or_b32_e32 v64, 48, v138
	v_mad_i64_i32 v[64:65], s[2:3], v64, s4, v[112:113]
	v_lshl_add_u64 v[64:65], v[64:65], 0, v[114:115]
	global_store_dwordx4 v[64:65], v[68:71], off
	v_mul_f32_e32 v64, 0xbfb8aa3b, v60
	v_mul_f32_e32 v65, 0xbfb8aa3b, v61
	v_exp_f32_e32 v64, v64
	v_exp_f32_e32 v65, v65
	v_mul_f32_e32 v67, 0xbfb8aa3b, v63
	v_exp_f32_e32 v66, v66
	v_exp_f32_e32 v67, v67
	v_mul_f32_e32 v68, 0xbfb8aa3b, v56
	v_mul_f32_e32 v69, 0xbfb8aa3b, v57
	v_exp_f32_e32 v68, v68
	v_exp_f32_e32 v69, v69
	v_add_f32_e32 v64, 1.0, v64
	v_add_f32_e32 v65, 1.0, v65
	v_mul_f32_e32 v70, 0xbfb8aa3b, v58
	v_mul_f32_e32 v71, 0xbfb8aa3b, v59
	v_rcp_f32_e32 v64, v64
	v_rcp_f32_e32 v65, v65
	v_add_f32_e32 v66, 1.0, v66
	v_add_f32_e32 v67, 1.0, v67
	v_exp_f32_e32 v70, v70
	v_exp_f32_e32 v71, v71
	v_rcp_f32_e32 v66, v66
	v_rcp_f32_e32 v67, v67
	v_add_f32_e32 v68, 1.0, v68
	v_add_f32_e32 v69, 1.0, v69
	v_rcp_f32_e32 v68, v68
	v_rcp_f32_e32 v69, v69
	v_add_f32_e32 v70, 1.0, v70
	v_add_f32_e32 v71, 1.0, v71
	v_pk_mul_f32 v[60:61], v[60:61], v[64:65]
	v_rcp_f32_e32 v70, v70
	v_rcp_f32_e32 v71, v71
	v_pk_mul_f32 v[52:53], v[60:61], v[52:53]
	v_pk_mul_f32 v[60:61], v[62:63], v[66:67]
	v_cvt_pk_bf16_f32 v52, v52, v53
	v_pk_mul_f32 v[54:55], v[60:61], v[54:55]
	s_nop 0
	v_cvt_pk_bf16_f32 v53, v54, v55
	v_pk_mul_f32 v[54:55], v[56:57], v[68:69]
; #define PG8_WAIT_V(n) asm volatile("s_waitcnt vmcnt(" #n ")" ::: "memory")
; #define PG8_BAR __builtin_amdgcn_s_barrier()
; template <class Epi>
; DI void gemm_phase(LAS unsigned char* lds, const Gemm g, const StaticOrder& S, const Epi& E) {
;     ...
;         E(acc, cur, wr, wc, fr, fq);
;         if (!has_next) break;
; #pragma unroll
;         for (int a = 0; a < 2; ++a)
; #pragma unroll
;             for (int b = 0; b < 2; ++b)
; #pragma unroll
;                 for (int m = 0; m < 4; ++m)
; #pragma unroll
;                     for (int n = 0; n < 2; ++n) acc[a][b][m][n] = (f32x4){0.f, 0.f, 0.f, 0.f};
;         cur = nxt; cA = nA; cB = nB; ++ui;
;     }
;     PG8_WAIT_V(0);
;     if (wr == 0) PG8_BAR;
;     DI void operator()(const f32x4 (&acc)[2][2][4][2], const Unit& u, int wr, int wc, int fr, int fq) const {
;         const int row0 = u.pm * BM + wr * 64 + fr, col0 = u.pn * HALF + wc * 32 + 8 * fq;
; #pragma unroll
;         for (int ai = 0; ai < 2; ++ai)
; #pragma unroll
;             for (int m = 0; m < 4; ++m) { float hv[8];
; #pragma unroll
;                 for (int n = 0; n < 2; ++n)
; #pragma unroll
;                     for (int e = 0; e < 4; ++e) { const float gt = acc[ai][0][m][n][e], up = acc[ai][1][m][n][e];
;                         hv[n * 4 + e] = gt * __builtin_amdgcn_rcpf(1.f + __builtin_amdgcn_exp2f(-1.4426950408889634f * gt)) * up; }
;                 *(u32x4*)(H + (size_t)(row0 + ai * HALF + m * 16) * DFF + col0) = (u32x4){pk(hv[0], hv[1]), pk(hv[2], hv[3]), pk(hv[4], hv[5]), pk(hv[6], hv[7])}; }
	s_nop 0
	v_pk_mul_f32 v[48:49], v[54:55], v[48:49]
	s_nop 0
	v_cvt_pk_bf16_f32 v54, v48, v49
	v_pk_mul_f32 v[48:49], v[58:59], v[70:71]
	s_nop 0
	v_pk_mul_f32 v[48:49], v[48:49], v[50:51]
	v_mul_f32_e32 v50, 0xbfb8aa3b, v46
	v_cvt_pk_bf16_f32 v55, v48, v49
	v_mad_i64_i32 v[48:49], s[2:3], v72, s4, v[112:113]
	v_lshl_add_u64 v[48:49], v[48:49], 0, v[114:115]
	global_store_dwordx4 v[48:49], v[52:55], off
	v_mul_f32_e32 v48, 0xbfb8aa3b, v44
	v_mul_f32_e32 v49, 0xbfb8aa3b, v45
	v_exp_f32_e32 v48, v48
	v_exp_f32_e32 v49, v49
	v_mul_f32_e32 v51, 0xbfb8aa3b, v47
	v_exp_f32_e32 v50, v50
	v_exp_f32_e32 v51, v51
	v_mul_f32_e32 v52, 0xbfb8aa3b, v40
	v_mul_f32_e32 v53, 0xbfb8aa3b, v41
	v_exp_f32_e32 v52, v52
	v_exp_f32_e32 v53, v53
	v_add_f32_e32 v48, 1.0, v48
	v_add_f32_e32 v49, 1.0, v49
	v_mul_f32_e32 v54, 0xbfb8aa3b, v42
	v_mul_f32_e32 v55, 0xbfb8aa3b, v43
	v_rcp_f32_e32 v48, v48
	v_rcp_f32_e32 v49, v49
	v_add_f32_e32 v50, 1.0, v50
	v_add_f32_e32 v51, 1.0, v51
	v_exp_f32_e32 v54, v54
	v_exp_f32_e32 v55, v55
	v_rcp_f32_e32 v50, v50
	v_rcp_f32_e32 v51, v51
	v_add_f32_e32 v52, 1.0, v52
	v_add_f32_e32 v53, 1.0, v53
	v_rcp_f32_e32 v52, v52
	v_rcp_f32_e32 v53, v53
	v_add_f32_e32 v54, 1.0, v54
	v_add_f32_e32 v55, 1.0, v55
	v_pk_mul_f32 v[44:45], v[44:45], v[48:49]
	v_rcp_f32_e32 v54, v54
	v_rcp_f32_e32 v55, v55
	v_pk_mul_f32 v[36:37], v[44:45], v[36:37]
	v_pk_mul_f32 v[44:45], v[46:47], v[50:51]
	v_cvt_pk_bf16_f32 v36, v36, v37
	v_pk_mul_f32 v[38:39], v[44:45], v[38:39]
	s_nop 0
	v_cvt_pk_bf16_f32 v37, v38, v39
	v_pk_mul_f32 v[38:39], v[40:41], v[52:53]
	s_nop 0
	v_pk_mul_f32 v[32:33], v[38:39], v[32:33]
	s_nop 0
	v_cvt_pk_bf16_f32 v38, v32, v33
	v_pk_mul_f32 v[32:33], v[42:43], v[54:55]
	s_nop 0
	v_pk_mul_f32 v[32:33], v[32:33], v[34:35]
	v_mul_f32_e32 v34, 0xbfb8aa3b, v30
	v_cvt_pk_bf16_f32 v39, v32, v33
	v_add_u32_e32 v32, 0x90, v138
	v_mad_i64_i32 v[32:33], s[2:3], v32, s4, v[112:113]
	v_lshl_add_u64 v[32:33], v[32:33], 0, v[114:115]
	global_store_dwordx4 v[32:33], v[36:39], off
	v_mul_f32_e32 v32, 0xbfb8aa3b, v28
	v_mul_f32_e32 v33, 0xbfb8aa3b, v29
	v_exp_f32_e32 v32, v32
	v_exp_f32_e32 v33, v33
	v_mul_f32_e32 v35, 0xbfb8aa3b, v31
	v_exp_f32_e32 v34, v34
	v_exp_f32_e32 v35, v35
	v_mul_f32_e32 v36, 0xbfb8aa3b, v24
	v_mul_f32_e32 v37, 0xbfb8aa3b, v25
	v_exp_f32_e32 v36, v36
	v_exp_f32_e32 v37, v37
	v_add_f32_e32 v32, 1.0, v32
	v_add_f32_e32 v33, 1.0, v33
	v_mul_f32_e32 v38, 0xbfb8aa3b, v26
	v_mul_f32_e32 v39, 0xbfb8aa3b, v27
	v_rcp_f32_e32 v32, v32
	v_rcp_f32_e32 v33, v33
	v_add_f32_e32 v34, 1.0, v34
	v_add_f32_e32 v35, 1.0, v35
	v_exp_f32_e32 v38, v38
	v_exp_f32_e32 v39, v39
	v_rcp_f32_e32 v34, v34
	v_rcp_f32_e32 v35, v35
	v_add_f32_e32 v36, 1.0, v36
	v_add_f32_e32 v37, 1.0, v37
	v_rcp_f32_e32 v36, v36
	v_rcp_f32_e32 v37, v37
	v_add_f32_e32 v38, 1.0, v38
	v_add_f32_e32 v39, 1.0, v39
	v_pk_mul_f32 v[28:29], v[28:29], v[32:33]
	v_rcp_f32_e32 v38, v38
	v_rcp_f32_e32 v39, v39
	v_pk_mul_f32 v[20:21], v[28:29], v[20:21]
	v_pk_mul_f32 v[28:29], v[30:31], v[34:35]
	v_cvt_pk_bf16_f32 v20, v20, v21
	v_pk_mul_f32 v[22:23], v[28:29], v[22:23]
	s_nop 0
	v_cvt_pk_bf16_f32 v21, v22, v23
	v_pk_mul_f32 v[22:23], v[24:25], v[36:37]
	s_nop 0
	v_pk_mul_f32 v[16:17], v[22:23], v[16:17]
	s_nop 0
	v_cvt_pk_bf16_f32 v22, v16, v17
	v_pk_mul_f32 v[16:17], v[26:27], v[38:39]
	s_nop 0
	v_pk_mul_f32 v[16:17], v[16:17], v[18:19]
	v_mul_f32_e32 v18, 0xbfb8aa3b, v14
	v_cvt_pk_bf16_f32 v23, v16, v17
	v_add_u32_e32 v16, 0xa0, v138
	v_mad_i64_i32 v[16:17], s[2:3], v16, s4, v[112:113]
	v_lshl_add_u64 v[16:17], v[16:17], 0, v[114:115]
	global_store_dwordx4 v[16:17], v[20:23], off
	v_mul_f32_e32 v16, 0xbfb8aa3b, v12
	v_mul_f32_e32 v17, 0xbfb8aa3b, v13
	v_exp_f32_e32 v16, v16
	v_exp_f32_e32 v17, v17
	v_mul_f32_e32 v19, 0xbfb8aa3b, v15
	v_exp_f32_e32 v18, v18
	v_exp_f32_e32 v19, v19
	v_mul_f32_e32 v20, 0xbfb8aa3b, v8
	v_mul_f32_e32 v21, 0xbfb8aa3b, v9
	v_exp_f32_e32 v20, v20
	v_exp_f32_e32 v21, v21
	v_add_f32_e32 v16, 1.0, v16
	v_add_f32_e32 v17, 1.0, v17
	v_mul_f32_e32 v22, 0xbfb8aa3b, v10
	v_mul_f32_e32 v23, 0xbfb8aa3b, v11
	v_rcp_f32_e32 v16, v16
	v_rcp_f32_e32 v17, v17
	v_add_f32_e32 v18, 1.0, v18
	v_add_f32_e32 v19, 1.0, v19
	v_exp_f32_e32 v22, v22
	v_exp_f32_e32 v23, v23
	v_rcp_f32_e32 v18, v18
	v_rcp_f32_e32 v19, v19
	v_add_f32_e32 v20, 1.0, v20
	v_add_f32_e32 v21, 1.0, v21
	v_rcp_f32_e32 v20, v20
	v_rcp_f32_e32 v21, v21
	v_add_f32_e32 v22, 1.0, v22
	v_add_f32_e32 v23, 1.0, v23
	v_pk_mul_f32 v[12:13], v[12:13], v[16:17]
	v_rcp_f32_e32 v22, v22
	v_rcp_f32_e32 v23, v23
	v_pk_mul_f32 v[4:5], v[12:13], v[4:5]
	v_pk_mul_f32 v[12:13], v[14:15], v[18:19]
	v_cvt_pk_bf16_f32 v4, v4, v5
	v_pk_mul_f32 v[6:7], v[12:13], v[6:7]
	s_nop 0
	v_cvt_pk_bf16_f32 v5, v6, v7
	v_pk_mul_f32 v[6:7], v[8:9], v[20:21]
	s_nop 0
	v_pk_mul_f32 v[0:1], v[6:7], v[0:1]
	s_nop 0
	v_cvt_pk_bf16_f32 v6, v0, v1
	v_pk_mul_f32 v[0:1], v[10:11], v[22:23]
	s_nop 0
	v_pk_mul_f32 v[0:1], v[0:1], v[2:3]
	s_nop 0
	v_cvt_pk_bf16_f32 v7, v0, v1
	v_add_u32_e32 v0, 0xb0, v138
	v_mad_i64_i32 v[0:1], s[2:3], v0, s4, v[112:113]
	v_lshl_add_u64 v[0:1], v[0:1], 0, v[114:115]
	s_mov_b32 s2, s8
	s_mov_b32 s3, s10
	global_store_dwordx4 v[0:1], v[4:7], off
	s_cbranch_vccz .LBB0_34
	s_waitcnt vmcnt(0)
	s_cmpk_gt_u32 s24, 0xff
	s_cbranch_scc1 .LBB0_41
	s_barrier

; #define PG8_STAGE(bufoff, gbase) do { _Pragma("unroll") for (int _i = 0; _i < 2; ++_i) \
;         __builtin_amdgcn_global_load_lds((const unsigned*)((const char*)(gbase) + voff[_i]), (LAS unsigned*)(lds + (bufoff) + ldsw + _i * 8192), 16, 0, 0); } while (0)
; #define PG8_LDA(dst, b, h) do { _Pragma("unroll") for (int m = 0; m < 4; ++m) _Pragma("unroll") for (int k = 0; k < 2; ++k) dst[m][k] = *(const LAS bf16x8*)(lds + PG8_SA(b, h) + aoff + m * 2048 + k * 1024); } while (0)
; #define PG8_LDB(dst, b, h) do { _Pragma("unroll") for (int n = 0; n < 2; ++n) _Pragma("unroll") for (int k = 0; k < 2; ++k) dst[n][k] = *(const LAS bf16x8*)(lds + PG8_SB(b, h) + boff + n * 2048 + k * 1024); } while (0)
; #define PG8_MMA(ai, bj, At, Bt) do { __builtin_amdgcn_s_setprio(1); _Pragma("unroll") for (int m = 0; m < 4; ++m) _Pragma("unroll") for (int n = 0; n < 2; ++n) _Pragma("unroll") for (int k = 0; k < 2; ++k) \
;         acc[ai][bj][m][n] = __builtin_amdgcn_mfma_f32_16x16x32_bf16(Bt[n][k], At[m][k], acc[ai][bj][m][n], 0, 0, 0); __builtin_amdgcn_s_setprio(0); } while (0)
; #define PG8_WAIT_L(n) asm volatile("s_waitcnt lgkmcnt(" #n ")" ::: "memory")
; #define PG8_BAR __builtin_amdgcn_s_barrier()
; #define PG8_SCHED __builtin_amdgcn_sched_barrier(0)
; template <class Epi>
; DI void gemm_phase(LAS unsigned char* lds, const Gemm g, const StaticOrder& S, const Epi& E) {
;     ...
;         for (int t = 0; t < nt; t += 2) {
;             const bool last = (t == nt - 2);
;             const char* a1 = cA + (size_t)(t + 1) * kstep;
;             const char* a2 = last ? nA : cA + (size_t)(t + 2) * kstep; const char* b2 = last ? nB : cB + (size_t)(t + 2) * kstep;
;             const char* a3 = a2 + kstep; const char* b3 = b2 + kstep;
;             PG8_LDB(B0, 0, 0); PG8_SCHED; PG8_LDA(At, 0, 0); PG8_STAGE(PG8_SA(1, 1), a1 + hstep);
;             PG8_WAIT_L(8); PG8_BAR; PG8_WAIT_L(0); PG8_MMA(0, 0, At, B0); PG8_BAR; PG8_SCHED;
;             PG8_LDB(B1, 0, 1); PG8_STAGE(PG8_SB(0, 0), b2);
;             PG8_BAR; PG8_WAIT_L(0); PG8_MMA(0, 1, At, B1); PG8_BAR;
;             PG8_LDA(At, 0, 1); PG8_STAGE(PG8_SA(0, 0), a2);
;             PG8_BAR; PG8_WAIT_L(0); PG8_MMA(1, 0, At, B0); PG8_BAR; PG8_SCHED;
.LBB0_77:
	s_add_u32 s22, s20, 0x100
	s_addc_u32 s23, s21, 0
	s_add_i32 s43, 0, 0x10000
	v_add_u32_e32 v140, s43, v226
	ds_read_b128 v[128:131], v140
	ds_read_b128 v[132:135], v140 offset:1024
	ds_read_b128 v[136:139], v140 offset:2048
	ds_read_b128 v[140:143], v140 offset:3072
	s_cmp_eq_u32 s33, 32
	s_cselect_b32 s27, s9, s23
	s_cselect_b32 s26, s8, s22
	s_cselect_b32 s25, s11, s5
	s_cselect_b32 s24, s10, s4
	v_lshl_add_u64 v[214:215], s[20:21], 0, v[190:191]
	s_add_i32 m0, s34, 0xc000
	ds_read_b128 v[144:147], v228
	ds_read_b128 v[148:151], v228 offset:1024
	ds_read_b128 v[152:155], v228 offset:2048
	ds_read_b128 v[194:197], v228 offset:3072
	ds_read_b128 v[198:201], v228 offset:4096
	ds_read_b128 v[202:205], v228 offset:5120
	ds_read_b128 v[206:209], v228 offset:6144
	ds_read_b128 v[210:213], v228 offset:7168
	global_load_lds_dwordx4 v[214:215], off
	v_lshl_add_u64 v[214:215], s[20:21], 0, v[192:193]
	s_add_i32 m0, s34, 0xe000
	s_nop 0
	global_load_lds_dwordx4 v[214:215], off
	s_waitcnt lgkmcnt(8)
	s_setprio 1
	s_barrier
	s_waitcnt lgkmcnt(0)
	v_mfma_f32_16x16x32_bf16 v[124:127], v[128:131], v[144:147], v[124:127]
	v_mfma_f32_16x16x32_bf16 v[120:123], v[136:139], v[144:147], v[120:123]
	v_mfma_f32_16x16x32_bf16 v[116:119], v[128:131], v[152:155], v[116:119]
	v_mfma_f32_16x16x32_bf16 v[112:115], v[136:139], v[152:155], v[112:115]
	v_mfma_f32_16x16x32_bf16 v[108:111], v[128:131], v[198:201], v[108:111]
	v_mfma_f32_16x16x32_bf16 v[104:107], v[136:139], v[198:201], v[104:107]
	v_mfma_f32_16x16x32_bf16 v[100:103], v[128:131], v[206:209], v[100:103]
	v_mfma_f32_16x16x32_bf16 v[96:99], v[136:139], v[206:209], v[96:99]
	v_mfma_f32_16x16x32_bf16 v[124:127], v[132:135], v[148:151], v[124:127]
	v_mfma_f32_16x16x32_bf16 v[120:123], v[140:143], v[148:151], v[120:123]
	v_mfma_f32_16x16x32_bf16 v[116:119], v[132:135], v[194:197], v[116:119]
	v_mfma_f32_16x16x32_bf16 v[112:115], v[140:143], v[194:197], v[112:115]
	v_mfma_f32_16x16x32_bf16 v[108:111], v[132:135], v[202:205], v[108:111]
	v_mfma_f32_16x16x32_bf16 v[104:107], v[140:143], v[202:205], v[104:107]
	v_mfma_f32_16x16x32_bf16 v[100:103], v[132:135], v[210:213], v[100:103]
	v_mfma_f32_16x16x32_bf16 v[96:99], v[140:143], v[210:213], v[96:99]
	s_setprio 0
	s_barrier
	s_add_i32 s44, 0, 0x14000
	s_add_i32 s20, s43, s31
	v_add_u32_e32 v158, s44, v226
	v_lshl_add_u64 v[218:219], s[24:25], 0, v[188:189]
	s_mov_b32 m0, s20
	ds_read_b128 v[214:217], v158
	ds_read_b128 v[230:233], v158 offset:1024
	ds_read_b128 v[234:237], v158 offset:2048
	ds_read_b128 v[238:241], v158 offset:3072
	global_load_lds_dwordx4 v[218:219], off
	v_lshl_add_u64 v[220:221], s[24:25], 0, v[186:187]
	s_add_i32 m0, s20, 0x2000
	s_nop 0
	global_load_lds_dwordx4 v[220:221], off
	s_waitcnt lgkmcnt(0)
	s_setprio 1
	s_barrier
	v_mfma_f32_16x16x32_bf16 v[60:63], v[214:217], v[144:147], v[60:63]
	v_mfma_f32_16x16x32_bf16 v[56:59], v[234:237], v[144:147], v[56:59]
	v_mfma_f32_16x16x32_bf16 v[52:55], v[214:217], v[152:155], v[52:55]
	v_mfma_f32_16x16x32_bf16 v[48:51], v[234:237], v[152:155], v[48:51]
	v_mfma_f32_16x16x32_bf16 v[44:47], v[214:217], v[198:201], v[44:47]
	v_mfma_f32_16x16x32_bf16 v[40:43], v[234:237], v[198:201], v[40:43]
	v_mfma_f32_16x16x32_bf16 v[36:39], v[214:217], v[206:209], v[36:39]
	v_mfma_f32_16x16x32_bf16 v[32:35], v[234:237], v[206:209], v[32:35]
	v_mfma_f32_16x16x32_bf16 v[60:63], v[230:233], v[148:151], v[60:63]
	v_mfma_f32_16x16x32_bf16 v[56:59], v[238:241], v[148:151], v[56:59]
	v_mfma_f32_16x16x32_bf16 v[52:55], v[230:233], v[194:197], v[52:55]
	v_mfma_f32_16x16x32_bf16 v[48:51], v[238:241], v[194:197], v[48:51]
	v_mfma_f32_16x16x32_bf16 v[44:47], v[230:233], v[202:205], v[44:47]
	v_mfma_f32_16x16x32_bf16 v[40:43], v[238:241], v[202:205], v[40:43]
	v_mfma_f32_16x16x32_bf16 v[36:39], v[230:233], v[210:213], v[36:39]
	v_mfma_f32_16x16x32_bf16 v[32:35], v[238:241], v[210:213], v[32:35]
	s_setprio 0
	s_mov_b32 m0, s34
	v_lshl_add_u64 v[242:243], s[26:27], 0, v[188:189]
	s_barrier
	ds_read_b128 v[144:147], v228 offset:16384
	ds_read_b128 v[148:151], v228 offset:17408
	ds_read_b128 v[152:155], v228 offset:18432
	ds_read_b128 v[194:197], v228 offset:19456
	ds_read_b128 v[198:201], v228 offset:20480
	ds_read_b128 v[202:205], v228 offset:21504
	ds_read_b128 v[206:209], v228 offset:22528
	ds_read_b128 v[210:213], v228 offset:23552
	global_load_lds_dwordx4 v[242:243], off
	v_lshl_add_u64 v[244:245], s[26:27], 0, v[186:187]
	s_mov_b32 m0, s35
	s_nop 0
	global_load_lds_dwordx4 v[244:245], off
	s_waitcnt lgkmcnt(0)
	s_setprio 1
	s_barrier
	v_mfma_f32_16x16x32_bf16 v[92:95], v[128:131], v[144:147], v[92:95]
	v_mfma_f32_16x16x32_bf16 v[88:91], v[136:139], v[144:147], v[88:91]
	v_mfma_f32_16x16x32_bf16 v[84:87], v[128:131], v[152:155], v[84:87]
	v_mfma_f32_16x16x32_bf16 v[80:83], v[136:139], v[152:155], v[80:83]
	v_mfma_f32_16x16x32_bf16 v[76:79], v[128:131], v[198:201], v[76:79]
	v_mfma_f32_16x16x32_bf16 v[72:75], v[136:139], v[198:201], v[72:75]
	v_mfma_f32_16x16x32_bf16 v[68:71], v[128:131], v[206:209], v[68:71]
	v_mfma_f32_16x16x32_bf16 v[64:67], v[136:139], v[206:209], v[64:67]
	v_mfma_f32_16x16x32_bf16 v[92:95], v[132:135], v[148:151], v[92:95]
	v_mfma_f32_16x16x32_bf16 v[88:91], v[140:143], v[148:151], v[88:91]
	v_mfma_f32_16x16x32_bf16 v[84:87], v[132:135], v[194:197], v[84:87]
	v_mfma_f32_16x16x32_bf16 v[80:83], v[140:143], v[194:197], v[80:83]
	v_mfma_f32_16x16x32_bf16 v[76:79], v[132:135], v[202:205], v[76:79]
	v_mfma_f32_16x16x32_bf16 v[72:75], v[140:143], v[202:205], v[72:75]
	v_mfma_f32_16x16x32_bf16 v[68:71], v[132:135], v[210:213], v[68:71]
	v_mfma_f32_16x16x32_bf16 v[64:67], v[140:143], v[210:213], v[64:67]
	s_setprio 0
	s_barrier
; #define PG8_STAGE(bufoff, gbase) do { _Pragma("unroll") for (int _i = 0; _i < 2; ++_i) \
;         __builtin_amdgcn_global_load_lds((const unsigned*)((const char*)(gbase) + voff[_i]), (LAS unsigned*)(lds + (bufoff) + ldsw + _i * 8192), 16, 0, 0); } while (0)
; #define PG8_LDA(dst, b, h) do { _Pragma("unroll") for (int m = 0; m < 4; ++m) _Pragma("unroll") for (int k = 0; k < 2; ++k) dst[m][k] = *(const LAS bf16x8*)(lds + PG8_SA(b, h) + aoff + m * 2048 + k * 1024); } while (0)
; #define PG8_LDB(dst, b, h) do { _Pragma("unroll") for (int n = 0; n < 2; ++n) _Pragma("unroll") for (int k = 0; k < 2; ++k) dst[n][k] = *(const LAS bf16x8*)(lds + PG8_SB(b, h) + boff + n * 2048 + k * 1024); } while (0)
; #define PG8_MMA(ai, bj, At, Bt) do { __builtin_amdgcn_s_setprio(1); _Pragma("unroll") for (int m = 0; m < 4; ++m) _Pragma("unroll") for (int n = 0; n < 2; ++n) _Pragma("unroll") for (int k = 0; k < 2; ++k) \
;         acc[ai][bj][m][n] = __builtin_amdgcn_mfma_f32_16x16x32_bf16(Bt[n][k], At[m][k], acc[ai][bj][m][n], 0, 0, 0); __builtin_amdgcn_s_setprio(0); } while (0)
; #define PG8_WAIT_V(n) asm volatile("s_waitcnt vmcnt(" #n ")" ::: "memory")
; #define PG8_WAIT_L(n) asm volatile("s_waitcnt lgkmcnt(" #n ")" ::: "memory")
; #define PG8_BAR __builtin_amdgcn_s_barrier()
; #define PG8_SCHED __builtin_amdgcn_sched_barrier(0)
; template <class Epi>
; DI void gemm_phase(LAS unsigned char* lds, const Gemm g, const StaticOrder& S, const Epi& E) {
;     ...
;             PG8_STAGE(PG8_SB(0, 1), b2 + hstep);
;             PG8_WAIT_V(6); PG8_BAR; PG8_MMA(1, 1, At, B1); PG8_BAR;
;             PG8_LDB(B0, 1, 0); PG8_SCHED; PG8_LDA(At, 1, 0); PG8_STAGE(PG8_SA(0, 1), a2 + hstep);
;             PG8_WAIT_L(8); PG8_BAR; PG8_WAIT_L(0); PG8_MMA(0, 0, At, B0); PG8_BAR; PG8_SCHED;
;             PG8_LDB(B1, 1, 1); PG8_STAGE(PG8_SB(1, 0), b3);
;             PG8_BAR; PG8_WAIT_L(0); PG8_MMA(0, 1, At, B1); PG8_BAR;
;             PG8_LDA(At, 1, 1); PG8_STAGE(PG8_SA(1, 0), a3);
;             PG8_BAR; PG8_WAIT_L(0); PG8_MMA(1, 0, At, B0); PG8_BAR; PG8_SCHED;
	s_add_u32 s20, s24, 0x90000
	s_addc_u32 s21, s25, 0
	s_add_i32 s43, s44, s31
	v_lshl_add_u64 v[128:129], s[20:21], 0, v[188:189]
	s_mov_b32 m0, s43
	s_nop 0
	global_load_lds_dwordx4 v[128:129], off
	v_lshl_add_u64 v[128:129], s[20:21], 0, v[186:187]
	s_add_i32 m0, s43, 0x2000
	s_nop 0
	global_load_lds_dwordx4 v[128:129], off
	s_waitcnt vmcnt(6)
	s_setprio 1
	s_barrier
	v_mfma_f32_16x16x32_bf16 v[28:31], v[214:217], v[144:147], v[28:31]
	v_mfma_f32_16x16x32_bf16 v[24:27], v[234:237], v[144:147], v[24:27]
	v_mfma_f32_16x16x32_bf16 v[20:23], v[214:217], v[152:155], v[20:23]
	v_mfma_f32_16x16x32_bf16 v[16:19], v[234:237], v[152:155], v[16:19]
	v_mfma_f32_16x16x32_bf16 v[12:15], v[214:217], v[198:201], v[12:15]
	v_mfma_f32_16x16x32_bf16 v[8:11], v[234:237], v[198:201], v[8:11]
	v_mfma_f32_16x16x32_bf16 v[4:7], v[214:217], v[206:209], v[4:7]
	v_mfma_f32_16x16x32_bf16 v[0:3], v[234:237], v[206:209], v[0:3]
	v_mfma_f32_16x16x32_bf16 v[28:31], v[230:233], v[148:151], v[28:31]
	v_mfma_f32_16x16x32_bf16 v[24:27], v[238:241], v[148:151], v[24:27]
	v_mfma_f32_16x16x32_bf16 v[20:23], v[230:233], v[194:197], v[20:23]
	v_mfma_f32_16x16x32_bf16 v[16:19], v[238:241], v[194:197], v[16:19]
	v_mfma_f32_16x16x32_bf16 v[12:15], v[230:233], v[202:205], v[12:15]
	v_mfma_f32_16x16x32_bf16 v[8:11], v[238:241], v[202:205], v[8:11]
	v_mfma_f32_16x16x32_bf16 v[4:7], v[230:233], v[210:213], v[4:7]
	v_mfma_f32_16x16x32_bf16 v[0:3], v[238:241], v[210:213], v[0:3]
	s_setprio 0
	s_add_i32 s43, 0, 0x18000
	v_add_u32_e32 v140, s43, v226
	s_barrier
	ds_read_b128 v[128:131], v140
	ds_read_b128 v[132:135], v140 offset:1024
	ds_read_b128 v[136:139], v140 offset:2048
	ds_read_b128 v[140:143], v140 offset:3072
	s_add_u32 s20, s26, 0x90000
	s_addc_u32 s21, s27, 0
	s_mov_b32 m0, s36
	v_lshl_add_u64 v[214:215], s[20:21], 0, v[188:189]
	ds_read_b128 v[144:147], v228 offset:32768
	ds_read_b128 v[148:151], v228 offset:33792
	ds_read_b128 v[152:155], v228 offset:34816
	ds_read_b128 v[194:197], v228 offset:35840
	ds_read_b128 v[198:201], v228 offset:36864
	ds_read_b128 v[202:205], v228 offset:37888
	ds_read_b128 v[206:209], v228 offset:38912
	ds_read_b128 v[210:213], v228 offset:39936
	global_load_lds_dwordx4 v[214:215], off
	v_lshl_add_u64 v[214:215], s[20:21], 0, v[186:187]
	s_mov_b32 m0, s37
	s_nop 0
	global_load_lds_dwordx4 v[214:215], off
	s_waitcnt lgkmcnt(8)
	s_setprio 1
	s_barrier
	s_waitcnt lgkmcnt(0)
	v_mfma_f32_16x16x32_bf16 v[124:127], v[128:131], v[144:147], v[124:127]
	v_mfma_f32_16x16x32_bf16 v[120:123], v[136:139], v[144:147], v[120:123]
	v_mfma_f32_16x16x32_bf16 v[116:119], v[128:131], v[152:155], v[116:119]
	v_mfma_f32_16x16x32_bf16 v[112:115], v[136:139], v[152:155], v[112:115]
	v_mfma_f32_16x16x32_bf16 v[108:111], v[128:131], v[198:201], v[108:111]
	v_mfma_f32_16x16x32_bf16 v[104:107], v[136:139], v[198:201], v[104:107]
	v_mfma_f32_16x16x32_bf16 v[100:103], v[128:131], v[206:209], v[100:103]
	v_mfma_f32_16x16x32_bf16 v[96:99], v[136:139], v[206:209], v[96:99]
	v_mfma_f32_16x16x32_bf16 v[124:127], v[132:135], v[148:151], v[124:127]
	v_mfma_f32_16x16x32_bf16 v[120:123], v[140:143], v[148:151], v[120:123]
	v_mfma_f32_16x16x32_bf16 v[116:119], v[132:135], v[194:197], v[116:119]
	v_mfma_f32_16x16x32_bf16 v[112:115], v[140:143], v[194:197], v[112:115]
	v_mfma_f32_16x16x32_bf16 v[108:111], v[132:135], v[202:205], v[108:111]
	v_mfma_f32_16x16x32_bf16 v[104:107], v[140:143], v[202:205], v[104:107]
	v_mfma_f32_16x16x32_bf16 v[100:103], v[132:135], v[210:213], v[100:103]
	v_mfma_f32_16x16x32_bf16 v[96:99], v[140:143], v[210:213], v[96:99]
	s_setprio 0
	s_barrier
	s_add_i32 s26, 0, 0x1c000
	s_add_i32 s20, s43, s31
	v_add_u32_e32 v158, s26, v226
	v_lshl_add_u64 v[218:219], v[218:219], 0, s[94:95]
	s_mov_b32 m0, s20
	ds_read_b128 v[214:217], v158
	ds_read_b128 v[230:233], v158 offset:1024
	ds_read_b128 v[234:237], v158 offset:2048
	ds_read_b128 v[238:241], v158 offset:3072
	global_load_lds_dwordx4 v[218:219], off
	v_lshl_add_u64 v[218:219], v[220:221], 0, s[94:95]
	s_add_i32 m0, s20, 0x2000
	s_nop 0
	global_load_lds_dwordx4 v[218:219], off
	s_waitcnt lgkmcnt(0)
	s_setprio 1
	s_barrier
	v_mfma_f32_16x16x32_bf16 v[60:63], v[214:217], v[144:147], v[60:63]
	v_mfma_f32_16x16x32_bf16 v[56:59], v[234:237], v[144:147], v[56:59]
	v_mfma_f32_16x16x32_bf16 v[52:55], v[214:217], v[152:155], v[52:55]
	v_mfma_f32_16x16x32_bf16 v[48:51], v[234:237], v[152:155], v[48:51]
	v_mfma_f32_16x16x32_bf16 v[44:47], v[214:217], v[198:201], v[44:47]
	v_mfma_f32_16x16x32_bf16 v[40:43], v[234:237], v[198:201], v[40:43]
	v_mfma_f32_16x16x32_bf16 v[36:39], v[214:217], v[206:209], v[36:39]
	v_mfma_f32_16x16x32_bf16 v[32:35], v[234:237], v[206:209], v[32:35]
	v_mfma_f32_16x16x32_bf16 v[60:63], v[230:233], v[148:151], v[60:63]
	v_mfma_f32_16x16x32_bf16 v[56:59], v[238:241], v[148:151], v[56:59]
	v_mfma_f32_16x16x32_bf16 v[52:55], v[230:233], v[194:197], v[52:55]
	v_mfma_f32_16x16x32_bf16 v[48:51], v[238:241], v[194:197], v[48:51]
	v_mfma_f32_16x16x32_bf16 v[44:47], v[230:233], v[202:205], v[44:47]
	v_mfma_f32_16x16x32_bf16 v[40:43], v[238:241], v[202:205], v[40:43]
	v_mfma_f32_16x16x32_bf16 v[36:39], v[230:233], v[210:213], v[36:39]
	v_mfma_f32_16x16x32_bf16 v[32:35], v[238:241], v[210:213], v[32:35]
	s_setprio 0
	s_mov_b32 m0, s38
	v_lshl_add_u64 v[218:219], v[242:243], 0, s[94:95]
	s_barrier
	ds_read_b128 v[144:147], v228 offset:49152
	ds_read_b128 v[148:151], v228 offset:50176
	ds_read_b128 v[152:155], v228 offset:51200
	ds_read_b128 v[194:197], v228 offset:52224
	ds_read_b128 v[198:201], v228 offset:53248
	ds_read_b128 v[202:205], v228 offset:54272
	ds_read_b128 v[206:209], v228 offset:55296
	ds_read_b128 v[210:213], v228 offset:56320
	global_load_lds_dwordx4 v[218:219], off
	v_lshl_add_u64 v[218:219], v[244:245], 0, s[94:95]
	s_mov_b32 m0, s39
	s_nop 0
	global_load_lds_dwordx4 v[218:219], off
	s_waitcnt lgkmcnt(0)
	s_setprio 1
	s_barrier
; #define PG8_STAGE(bufoff, gbase) do { _Pragma("unroll") for (int _i = 0; _i < 2; ++_i) \
;         __builtin_amdgcn_global_load_lds((const unsigned*)((const char*)(gbase) + voff[_i]), (LAS unsigned*)(lds + (bufoff) + ldsw + _i * 8192), 16, 0, 0); } while (0)
; #define PG8_MMA(ai, bj, At, Bt) do { __builtin_amdgcn_s_setprio(1); _Pragma("unroll") for (int m = 0; m < 4; ++m) _Pragma("unroll") for (int n = 0; n < 2; ++n) _Pragma("unroll") for (int k = 0; k < 2; ++k) \
;         acc[ai][bj][m][n] = __builtin_amdgcn_mfma_f32_16x16x32_bf16(Bt[n][k], At[m][k], acc[ai][bj][m][n], 0, 0, 0); __builtin_amdgcn_s_setprio(0); } while (0)
; #define PG8_WAIT_V(n) asm volatile("s_waitcnt vmcnt(" #n ")" ::: "memory")
; #define PG8_WAIT_L(n) asm volatile("s_waitcnt lgkmcnt(" #n ")" ::: "memory")
; #define PG8_BAR __builtin_amdgcn_s_barrier()
; #define PG8_SCHED __builtin_amdgcn_sched_barrier(0)
; template <class Epi>
; DI void gemm_phase(LAS unsigned char* lds, const Gemm g, const StaticOrder& S, const Epi& E) {
;     ...
;             PG8_BAR; PG8_WAIT_L(0); PG8_MMA(1, 0, At, B0); PG8_BAR; PG8_SCHED;
;             PG8_STAGE(PG8_SB(1, 1), b3 + hstep);
;             PG8_WAIT_V(6); PG8_BAR; PG8_MMA(1, 1, At, B1); PG8_BAR;
;     template <bool LN> DI void run(const f32x4 (&acc)[2][2][4][2], const Unit& u, int wr, int wc, int fr, int fq) const {
;         const unsigned row0 = u.pm * BM + wr * 64 + fr, col0 = u.pn * BM + wc * 32 + 4 * fq;
;         f32x4 gv[2], bv[2];
;         load_gb<LN, 0>(col0, gv, bv);
;         batch<LN, 0, 0, 4>(acc, row0, col0, gv, bv);
	v_mfma_f32_16x16x32_bf16 v[92:95], v[128:131], v[144:147], v[92:95]
	v_mfma_f32_16x16x32_bf16 v[88:91], v[136:139], v[144:147], v[88:91]
	v_mfma_f32_16x16x32_bf16 v[84:87], v[128:131], v[152:155], v[84:87]
	v_mfma_f32_16x16x32_bf16 v[80:83], v[136:139], v[152:155], v[80:83]
	v_mfma_f32_16x16x32_bf16 v[76:79], v[128:131], v[198:201], v[76:79]
	v_mfma_f32_16x16x32_bf16 v[72:75], v[136:139], v[198:201], v[72:75]
	v_mfma_f32_16x16x32_bf16 v[68:71], v[128:131], v[206:209], v[68:71]
	v_mfma_f32_16x16x32_bf16 v[64:67], v[136:139], v[206:209], v[64:67]
	v_mfma_f32_16x16x32_bf16 v[92:95], v[132:135], v[148:151], v[92:95]
	v_mfma_f32_16x16x32_bf16 v[88:91], v[140:143], v[148:151], v[88:91]
	v_mfma_f32_16x16x32_bf16 v[84:87], v[132:135], v[194:197], v[84:87]
	v_mfma_f32_16x16x32_bf16 v[80:83], v[140:143], v[194:197], v[80:83]
	v_mfma_f32_16x16x32_bf16 v[76:79], v[132:135], v[202:205], v[76:79]
	v_mfma_f32_16x16x32_bf16 v[72:75], v[140:143], v[202:205], v[72:75]
	v_mfma_f32_16x16x32_bf16 v[68:71], v[132:135], v[210:213], v[68:71]
	v_mfma_f32_16x16x32_bf16 v[64:67], v[140:143], v[210:213], v[64:67]
	s_setprio 0
	s_barrier
	s_add_u32 s20, s24, 0x90080
	s_addc_u32 s21, s25, 0
	s_add_i32 s24, s26, s31
	v_lshl_add_u64 v[128:129], s[20:21], 0, v[188:189]
	s_mov_b32 m0, s24
	s_nop 0
	global_load_lds_dwordx4 v[128:129], off
	v_lshl_add_u64 v[128:129], s[20:21], 0, v[186:187]
	s_add_i32 m0, s24, 0x2000
	s_nop 0
	global_load_lds_dwordx4 v[128:129], off
	s_waitcnt vmcnt(6)
	s_setprio 1
	s_barrier
	v_mfma_f32_16x16x32_bf16 v[28:31], v[214:217], v[144:147], v[28:31]
	v_mfma_f32_16x16x32_bf16 v[24:27], v[234:237], v[144:147], v[24:27]
	v_mfma_f32_16x16x32_bf16 v[20:23], v[214:217], v[152:155], v[20:23]
	v_mfma_f32_16x16x32_bf16 v[16:19], v[234:237], v[152:155], v[16:19]
	v_mfma_f32_16x16x32_bf16 v[12:15], v[214:217], v[198:201], v[12:15]
	v_mfma_f32_16x16x32_bf16 v[8:11], v[234:237], v[198:201], v[8:11]
	v_mfma_f32_16x16x32_bf16 v[4:7], v[214:217], v[206:209], v[4:7]
	v_mfma_f32_16x16x32_bf16 v[0:3], v[234:237], v[206:209], v[0:3]
	v_mfma_f32_16x16x32_bf16 v[28:31], v[230:233], v[148:151], v[28:31]
	v_mfma_f32_16x16x32_bf16 v[24:27], v[238:241], v[148:151], v[24:27]
	v_mfma_f32_16x16x32_bf16 v[20:23], v[230:233], v[194:197], v[20:23]
	v_mfma_f32_16x16x32_bf16 v[16:19], v[238:241], v[194:197], v[16:19]
	v_mfma_f32_16x16x32_bf16 v[12:15], v[230:233], v[202:205], v[12:15]
	v_mfma_f32_16x16x32_bf16 v[8:11], v[238:241], v[202:205], v[8:11]
	v_mfma_f32_16x16x32_bf16 v[4:7], v[230:233], v[210:213], v[4:7]
	v_mfma_f32_16x16x32_bf16 v[0:3], v[238:241], v[210:213], v[0:3]
	s_setprio 0
	s_add_i32 s33, s33, 2
	s_add_u32 s4, s4, 0x100
	s_addc_u32 s5, s5, 0
	s_cmp_gt_u32 s33, 33
	s_mov_b64 s[20:21], s[22:23]
	s_barrier
	s_cbranch_scc0 .LBB0_77
	v_lshl_add_u32 v206, s3, 8, v225
	v_lshl_or_b32 v158, s2, 8, v227
	v_lshlrev_b32_e32 v232, 11, v206
	s_andn2_b64 vcc, exec, s[14:15]
	v_or_b32_e32 v231, 16, v158
	v_add_u32_e32 v194, v232, v158
	v_or_b32_e32 v230, 0x80, v158
	v_or_b32_e32 v229, 0x90, v158
	s_cbranch_vccnz .LBB0_80
	v_lshlrev_b64 v[132:133], 2, v[158:159]
	v_lshl_add_u64 v[140:141], s[16:17], 0, v[132:133]
	global_load_dwordx4 v[128:131], v[140:141], off
	v_lshl_add_u64 v[142:143], s[18:19], 0, v[132:133]
	v_readlane_b32 s2, v253, 8
	v_mov_b32_e32 v195, v159
	v_lshlrev_b32_e32 v136, 1, v206
	v_mov_b32_e32 v137, v159
	v_readlane_b32 s3, v253, 9
	v_lshlrev_b64 v[212:213], 2, v[194:195]
	v_add_u32_e32 v146, v232, v231
	v_lshl_add_u64 v[144:145], v[136:137], 2, s[2:3]
	v_lshl_add_u64 v[136:137], s[88:89], 0, v[212:213]
	v_mov_b32_e32 v147, v159
	v_lshl_add_u64 v[146:147], v[146:147], 2, s[88:89]
	v_or_b32_e32 v195, 16, v206
	v_mov_b32_e32 v201, v159
	v_mov_b32_e32 v209, v159
	v_lshl_add_u64 v[212:213], s[90:91], 0, v[212:213]
	s_waitcnt vmcnt(0)
	v_pk_mul_f32 v[152:153], v[130:131], s[78:79] op_sel_hi:[1,0]
	v_pk_mul_f32 v[154:155], v[128:129], s[78:79] op_sel_hi:[1,0]
	global_load_dwordx4 v[132:135], v[142:143], off
	global_load_dwordx4 v[128:131], v[140:141], off offset:64
	global_load_dwordx2 v[204:205], v[144:145], off
	global_load_dwordx4 v[196:199], v[146:147], off
	v_lshlrev_b32_e32 v146, 1, v195
	global_load_dwordx4 v[136:139], v[136:137], off
	v_lshlrev_b32_e32 v195, 11, v195
	v_mov_b32_e32 v147, v159
	v_add_u32_e32 v200, v195, v158
	v_lshl_add_u64 v[146:147], v[146:147], 2, s[2:3]
	v_lshl_add_u64 v[200:201], v[200:201], 2, s[88:89]
	global_load_dwordx2 v[214:215], v[146:147], off
	v_add_u32_e32 v208, v195, v231
	global_load_dwordx4 v[200:203], v[200:201], off
	v_lshl_add_u64 v[208:209], v[208:209], 2, s[88:89]
	global_load_dwordx4 v[208:211], v[208:209], off
	s_waitcnt vmcnt(0)
	v_pk_mul_f32 v[148:149], v[130:131], s[78:79] op_sel_hi:[1,0]
	v_pk_mul_f32 v[150:151], v[128:129], s[78:79] op_sel_hi:[1,0]
	global_load_dwordx4 v[128:131], v[142:143], off offset:64
	v_sub_f32_e32 v137, v137, v204
	v_sub_f32_e32 v136, v136, v204
	v_sub_f32_e32 v139, v139, v204
	v_sub_f32_e32 v138, v138, v204
	v_pk_mul_f32 v[138:139], v[204:205], v[138:139] op_sel:[1,0]
	v_pk_mul_f32 v[136:137], v[204:205], v[136:137] op_sel:[1,0]
	v_pk_fma_f32 v[138:139], v[152:153], v[138:139], v[126:127]
	v_pk_fma_f32 v[136:137], v[154:155], v[136:137], v[124:125]
	v_pk_fma_f32 v[138:139], v[134:135], s[78:79], v[138:139] op_sel_hi:[1,0,1]
	v_pk_fma_f32 v[136:137], v[132:133], s[78:79], v[136:137] op_sel_hi:[1,0,1]
	global_store_dwordx4 v[212:213], v[136:139], off
	s_nop 1
	v_sub_f32_e32 v137, v197, v204
	v_sub_f32_e32 v136, v196, v204
	v_sub_f32_e32 v139, v199, v204
	v_sub_f32_e32 v138, v198, v204
	v_pk_mul_f32 v[138:139], v[204:205], v[138:139] op_sel:[1,0]
	v_pk_mul_f32 v[136:137], v[204:205], v[136:137] op_sel:[1,0]
	v_pk_fma_f32 v[138:139], v[148:149], v[138:139], v[122:123]
	v_pk_fma_f32 v[136:137], v[150:151], v[136:137], v[120:121]
	v_or_b32_e32 v196, 16, v194
	v_mov_b32_e32 v197, v159
	v_lshl_add_u64 v[196:197], v[196:197], 2, s[90:91]
	s_waitcnt vmcnt(0)
;     template <bool LN, int BJ, int LO, int HI> DI void batch(const f32x4 (&acc)[2][2][4][2], unsigned row0, unsigned col0, const f32x4 (&gv)[2], const f32x4 (&bv)[2]) const {
;         f32x4 r[HI - LO]; float mean[(HI - LO) / 2], rstd[(HI - LO) / 2];
; #pragma unroll
;         for (int i = LO; i < HI; ++i) { const int ai = i >> 3, m = (i >> 1) & 3, n = i & 1; const unsigned row = row0 + ai * HALF + m * 16;
;             if (n == 0) { mean[(i - LO) >> 1] = 0.f; rstd[(i - LO) >> 1] = 1.f;
;                 if (LN) { const float2 st = *(const float2*)(stats + row * 2u); mean[(i - LO) >> 1] = st.x; rstd[(i - LO) >> 1] = st.y; } }
;             r[i - LO] = *(const f32x4*)(src + (row * (unsigned)DM + col0 + BJ * HALF + n * 16)); }
; #pragma unroll
;         for (int i = LO; i < HI; ++i) { const int ai = i >> 3, m = (i >> 1) & 3, n = i & 1; const unsigned row = row0 + ai * HALF + m * 16;
;             *(f32x4*)(Y + (row * (unsigned)DM + col0 + BJ * HALF + n * 16)) = acc[ai][BJ][m][n] + ((r[i - LO] - mean[(i - LO) >> 1]) * rstd[(i - LO) >> 1]) * gv[n] + bv[n]; }
;         __builtin_amdgcn_sched_barrier(0);
;     }
;     template <bool LN, int BJ> DI void load_gb(unsigned col0, f32x4 (&gv)[2], f32x4 (&bv)[2]) const {
; #pragma unroll
;         for (int n = 0; n < 2; ++n) {
;             if (LN) { gv[n] = *(const f32x4*)(gam + col0 + BJ * HALF + n * 16) * ALPHA; bv[n] = *(const f32x4*)(bet + col0 + BJ * HALF + n * 16) * ALPHA; }
;             else { gv[n] = (f32x4){ALPHA, ALPHA, ALPHA, ALPHA}; bv[n] = (f32x4){0.f, 0.f, 0.f, 0.f}; }
;         }
;     }
;     template <bool LN> DI void run(const f32x4 (&acc)[2][2][4][2], const Unit& u, int wr, int wc, int fr, int fq) const {
;         const unsigned row0 = u.pm * BM + wr * 64 + fr, col0 = u.pn * BM + wc * 32 + 4 * fq;
;         f32x4 gv[2], bv[2];
;         load_gb<LN, 0>(col0, gv, bv);
;         batch<LN, 0, 0, 4>(acc, row0, col0, gv, bv);
;         batch<LN, 0, 4, 8>(acc, row0, col0, gv, bv);
;         batch<LN, 0, 8, 12>(acc, row0, col0, gv, bv);
;         batch<LN, 0, 12, 16>(acc, row0, col0, gv, bv);
;         load_gb<LN, 1>(col0, gv, bv);
;         batch<LN, 1, 0, 8>(acc, row0, col0, gv, bv);
;         batch<LN, 1, 8, 16>(acc, row0, col0, gv, bv);
	v_pk_fma_f32 v[138:139], v[130:131], s[78:79], v[138:139] op_sel_hi:[1,0,1]
	v_pk_fma_f32 v[136:137], v[128:129], s[78:79], v[136:137] op_sel_hi:[1,0,1]
	global_store_dwordx4 v[196:197], v[136:139], off
	v_add_u32_e32 v196, 0x8000, v194
	v_mov_b32_e32 v197, v159
	v_sub_f32_e32 v137, v201, v214
	v_sub_f32_e32 v136, v200, v214
	v_sub_f32_e32 v139, v203, v214
	v_sub_f32_e32 v138, v202, v214
	v_pk_mul_f32 v[138:139], v[214:215], v[138:139] op_sel:[1,0]
	v_pk_mul_f32 v[136:137], v[214:215], v[136:137] op_sel:[1,0]
	v_pk_fma_f32 v[138:139], v[152:153], v[138:139], v[118:119]
	v_pk_fma_f32 v[136:137], v[154:155], v[136:137], v[116:117]
	v_pk_fma_f32 v[138:139], v[134:135], s[78:79], v[138:139] op_sel_hi:[1,0,1]
	v_pk_fma_f32 v[136:137], v[132:133], s[78:79], v[136:137] op_sel_hi:[1,0,1]
	v_lshl_add_u64 v[196:197], v[196:197], 2, s[90:91]
	global_store_dwordx4 v[196:197], v[136:139], off
	v_add_u32_e32 v196, 0x8010, v194
	v_mov_b32_e32 v197, v159
	v_sub_f32_e32 v137, v209, v214
	v_sub_f32_e32 v136, v208, v214
	v_sub_f32_e32 v139, v211, v214
	v_sub_f32_e32 v138, v210, v214
	v_pk_mul_f32 v[138:139], v[214:215], v[138:139] op_sel:[1,0]
	v_pk_mul_f32 v[136:137], v[214:215], v[136:137] op_sel:[1,0]
	v_pk_fma_f32 v[138:139], v[148:149], v[138:139], v[114:115]
	v_pk_fma_f32 v[136:137], v[150:151], v[136:137], v[112:113]
	v_pk_fma_f32 v[138:139], v[130:131], s[78:79], v[138:139] op_sel_hi:[1,0,1]
	v_pk_fma_f32 v[136:137], v[128:129], s[78:79], v[136:137] op_sel_hi:[1,0,1]
	v_lshl_add_u64 v[196:197], v[196:197], 2, s[90:91]
	global_store_dwordx4 v[196:197], v[136:139], off
	s_nop 1
	v_or_b32_e32 v138, 32, v206
	v_lshlrev_b32_e32 v136, 1, v138
	v_mov_b32_e32 v137, v159
	v_lshlrev_b32_e32 v236, 11, v138
	v_lshl_add_u64 v[200:201], v[136:137], 2, s[2:3]
	v_add_u32_e32 v136, v236, v158
	v_lshl_add_u64 v[136:137], v[136:137], 2, s[88:89]
	global_load_dwordx2 v[204:205], v[200:201], off
	v_add_u32_e32 v196, v236, v231
	global_load_dwordx4 v[136:139], v[136:137], off
	v_mov_b32_e32 v197, v159
	v_lshl_add_u64 v[196:197], v[196:197], 2, s[88:89]
	global_load_dwordx4 v[196:199], v[196:197], off
	v_or_b32_e32 v207, 48, v206
	v_lshlrev_b32_e32 v235, 11, v207
	v_lshlrev_b32_e32 v202, 1, v207
	v_mov_b32_e32 v203, v159
	v_add_u32_e32 v208, v235, v158
	v_mov_b32_e32 v209, v159
	v_lshl_add_u64 v[202:203], v[202:203], 2, s[2:3]
	v_lshl_add_u64 v[208:209], v[208:209], 2, s[88:89]
	global_load_dwordx2 v[216:217], v[202:203], off
	v_add_u32_e32 v212, v235, v231
	global_load_dwordx4 v[208:211], v[208:209], off
	v_mov_b32_e32 v213, v159
	v_lshl_add_u64 v[212:213], v[212:213], 2, s[88:89]
	global_load_dwordx4 v[212:215], v[212:213], off
	v_add_u32_e32 v218, 0x10000, v194
	v_mov_b32_e32 v219, v159
	v_lshl_add_u64 v[218:219], v[218:219], 2, s[90:91]
	s_waitcnt vmcnt(0)
	v_sub_f32_e32 v137, v137, v204
	v_sub_f32_e32 v136, v136, v204
	v_sub_f32_e32 v139, v139, v204
	v_sub_f32_e32 v138, v138, v204
	v_pk_mul_f32 v[138:139], v[204:205], v[138:139] op_sel:[1,0]
	v_pk_mul_f32 v[136:137], v[204:205], v[136:137] op_sel:[1,0]
	v_pk_fma_f32 v[138:139], v[152:153], v[138:139], v[110:111]
	v_pk_fma_f32 v[136:137], v[154:155], v[136:137], v[108:109]
	v_pk_fma_f32 v[138:139], v[134:135], s[78:79], v[138:139] op_sel_hi:[1,0,1]
	v_pk_fma_f32 v[136:137], v[132:133], s[78:79], v[136:137] op_sel_hi:[1,0,1]
	global_store_dwordx4 v[218:219], v[136:139], off
	s_nop 1
	v_sub_f32_e32 v137, v197, v204
	v_sub_f32_e32 v136, v196, v204
	v_sub_f32_e32 v139, v199, v204
	v_sub_f32_e32 v138, v198, v204
	v_pk_mul_f32 v[138:139], v[204:205], v[138:139] op_sel:[1,0]
	v_pk_mul_f32 v[136:137], v[204:205], v[136:137] op_sel:[1,0]
	v_pk_fma_f32 v[138:139], v[148:149], v[138:139], v[106:107]
	v_pk_fma_f32 v[136:137], v[150:151], v[136:137], v[104:105]
	v_add_u32_e32 v196, 0x10010, v194
	v_mov_b32_e32 v197, v159
	v_pk_fma_f32 v[138:139], v[130:131], s[78:79], v[138:139] op_sel_hi:[1,0,1]
	v_pk_fma_f32 v[136:137], v[128:129], s[78:79], v[136:137] op_sel_hi:[1,0,1]
	v_lshl_add_u64 v[196:197], v[196:197], 2, s[90:91]
	global_store_dwordx4 v[196:197], v[136:139], off
	v_add_u32_e32 v196, 0x18000, v194
	v_mov_b32_e32 v197, v159
	v_sub_f32_e32 v137, v209, v216
	v_sub_f32_e32 v136, v208, v216
	v_sub_f32_e32 v139, v211, v216
	v_sub_f32_e32 v138, v210, v216
	v_pk_mul_f32 v[138:139], v[216:217], v[138:139] op_sel:[1,0]
	v_pk_mul_f32 v[136:137], v[216:217], v[136:137] op_sel:[1,0]
	v_pk_fma_f32 v[138:139], v[152:153], v[138:139], v[102:103]
	v_pk_fma_f32 v[136:137], v[154:155], v[136:137], v[100:101]
	v_pk_fma_f32 v[138:139], v[134:135], s[78:79], v[138:139] op_sel_hi:[1,0,1]
	v_pk_fma_f32 v[136:137], v[132:133], s[78:79], v[136:137] op_sel_hi:[1,0,1]
	v_lshl_add_u64 v[196:197], v[196:197], 2, s[90:91]
	global_store_dwordx4 v[196:197], v[136:139], off
	v_add_u32_e32 v196, 0x18010, v194
	v_mov_b32_e32 v197, v159
	v_sub_f32_e32 v137, v213, v216
	v_sub_f32_e32 v136, v212, v216
	v_sub_f32_e32 v139, v215, v216
	v_sub_f32_e32 v138, v214, v216
	v_pk_mul_f32 v[138:139], v[216:217], v[138:139] op_sel:[1,0]
	v_pk_mul_f32 v[136:137], v[216:217], v[136:137] op_sel:[1,0]
	v_pk_fma_f32 v[138:139], v[148:149], v[138:139], v[98:99]
	v_pk_fma_f32 v[136:137], v[150:151], v[136:137], v[96:97]
	v_pk_fma_f32 v[138:139], v[130:131], s[78:79], v[138:139] op_sel_hi:[1,0,1]
	v_pk_fma_f32 v[136:137], v[128:129], s[78:79], v[136:137] op_sel_hi:[1,0,1]
	v_lshl_add_u64 v[196:197], v[196:197], 2, s[90:91]
	global_store_dwordx4 v[196:197], v[136:139], off
	s_nop 1
	v_add_u32_e32 v138, 0x80, v206
	v_lshlrev_b32_e32 v136, 1, v138
	v_mov_b32_e32 v137, v159
	v_lshlrev_b32_e32 v233, 11, v138
	v_lshl_add_u64 v[196:197], v[136:137], 2, s[2:3]
	v_add_u32_e32 v136, v233, v158
	v_lshl_add_u64 v[136:137], v[136:137], 2, s[88:89]
	global_load_dwordx2 v[204:205], v[196:197], off
	v_add_u32_e32 v198, v233, v231
	global_load_dwordx4 v[136:139], v[136:137], off
	v_mov_b32_e32 v199, v159
	v_add_u32_e32 v207, 0x90, v206
	v_lshl_add_u64 v[198:199], v[198:199], 2, s[88:89]
	v_lshlrev_b32_e32 v234, 11, v207
	global_load_dwordx4 v[208:211], v[198:199], off
	v_add_u32_e32 v212, v234, v158
	v_mov_b32_e32 v213, v159
	v_lshl_add_u64 v[212:213], v[212:213], 2, s[88:89]
	global_load_dwordx4 v[212:215], v[212:213], off
	v_lshlrev_b32_e32 v198, 1, v207
	v_mov_b32_e32 v199, v159
	v_lshl_add_u64 v[198:199], v[198:199], 2, s[2:3]
	global_load_dwordx2 v[220:221], v[198:199], off
	v_add_u32_e32 v216, v234, v231
	v_mov_b32_e32 v217, v159
	v_lshl_add_u64 v[216:217], v[216:217], 2, s[88:89]
	global_load_dwordx4 v[216:219], v[216:217], off
	v_add_u32_e32 v238, 0x40000, v194
	v_mov_b32_e32 v239, v159
	v_lshl_add_u64 v[238:239], v[238:239], 2, s[90:91]
	s_waitcnt vmcnt(0)
;     template <bool LN, int BJ, int LO, int HI> DI void batch(const f32x4 (&acc)[2][2][4][2], unsigned row0, unsigned col0, const f32x4 (&gv)[2], const f32x4 (&bv)[2]) const {
;         f32x4 r[HI - LO]; float mean[(HI - LO) / 2], rstd[(HI - LO) / 2];
; #pragma unroll
;         for (int i = LO; i < HI; ++i) { const int ai = i >> 3, m = (i >> 1) & 3, n = i & 1; const unsigned row = row0 + ai * HALF + m * 16;
;             if (n == 0) { mean[(i - LO) >> 1] = 0.f; rstd[(i - LO) >> 1] = 1.f;
;                 if (LN) { const float2 st = *(const float2*)(stats + row * 2u); mean[(i - LO) >> 1] = st.x; rstd[(i - LO) >> 1] = st.y; } }
;             r[i - LO] = *(const f32x4*)(src + (row * (unsigned)DM + col0 + BJ * HALF + n * 16)); }
; #pragma unroll
;         for (int i = LO; i < HI; ++i) { const int ai = i >> 3, m = (i >> 1) & 3, n = i & 1; const unsigned row = row0 + ai * HALF + m * 16;
;             *(f32x4*)(Y + (row * (unsigned)DM + col0 + BJ * HALF + n * 16)) = acc[ai][BJ][m][n] + ((r[i - LO] - mean[(i - LO) >> 1]) * rstd[(i - LO) >> 1]) * gv[n] + bv[n]; }
;         __builtin_amdgcn_sched_barrier(0);
;     }
;     template <bool LN, int BJ> DI void load_gb(unsigned col0, f32x4 (&gv)[2], f32x4 (&bv)[2]) const {
; #pragma unroll
;         for (int n = 0; n < 2; ++n) {
;             if (LN) { gv[n] = *(const f32x4*)(gam + col0 + BJ * HALF + n * 16) * ALPHA; bv[n] = *(const f32x4*)(bet + col0 + BJ * HALF + n * 16) * ALPHA; }
;             else { gv[n] = (f32x4){ALPHA, ALPHA, ALPHA, ALPHA}; bv[n] = (f32x4){0.f, 0.f, 0.f, 0.f}; }
;         }
;     }
;     template <bool LN> DI void run(const f32x4 (&acc)[2][2][4][2], const Unit& u, int wr, int wc, int fr, int fq) const {
;         const unsigned row0 = u.pm * BM + wr * 64 + fr, col0 = u.pn * BM + wc * 32 + 4 * fq;
;         f32x4 gv[2], bv[2];
;         load_gb<LN, 0>(col0, gv, bv);
;         batch<LN, 0, 0, 4>(acc, row0, col0, gv, bv);
;         batch<LN, 0, 4, 8>(acc, row0, col0, gv, bv);
;         batch<LN, 0, 8, 12>(acc, row0, col0, gv, bv);
;         batch<LN, 0, 12, 16>(acc, row0, col0, gv, bv);
;         load_gb<LN, 1>(col0, gv, bv);
;         batch<LN, 1, 0, 8>(acc, row0, col0, gv, bv);
;         batch<LN, 1, 8, 16>(acc, row0, col0, gv, bv);
	v_sub_f32_e32 v137, v137, v204
	v_sub_f32_e32 v136, v136, v204
	v_sub_f32_e32 v139, v139, v204
	v_sub_f32_e32 v138, v138, v204
	v_pk_mul_f32 v[138:139], v[204:205], v[138:139] op_sel:[1,0]
	v_pk_mul_f32 v[136:137], v[204:205], v[136:137] op_sel:[1,0]
	v_pk_fma_f32 v[138:139], v[152:153], v[138:139], v[94:95]
	v_pk_fma_f32 v[136:137], v[154:155], v[136:137], v[92:93]
	v_pk_fma_f32 v[138:139], v[134:135], s[78:79], v[138:139] op_sel_hi:[1,0,1]
	v_pk_fma_f32 v[136:137], v[132:133], s[78:79], v[136:137] op_sel_hi:[1,0,1]
	global_store_dwordx4 v[238:239], v[136:139], off
	s_nop 1
	v_sub_f32_e32 v137, v209, v204
	v_sub_f32_e32 v136, v208, v204
	v_sub_f32_e32 v139, v211, v204
	v_sub_f32_e32 v138, v210, v204
	v_pk_mul_f32 v[138:139], v[204:205], v[138:139] op_sel:[1,0]
	v_pk_mul_f32 v[136:137], v[204:205], v[136:137] op_sel:[1,0]
	v_pk_fma_f32 v[138:139], v[148:149], v[138:139], v[90:91]
	v_pk_fma_f32 v[136:137], v[150:151], v[136:137], v[88:89]
	v_add_u32_e32 v204, 0x40010, v194
	v_mov_b32_e32 v205, v159
	v_pk_fma_f32 v[138:139], v[130:131], s[78:79], v[138:139] op_sel_hi:[1,0,1]
	v_pk_fma_f32 v[136:137], v[128:129], s[78:79], v[136:137] op_sel_hi:[1,0,1]
	v_lshl_add_u64 v[204:205], v[204:205], 2, s[90:91]
	global_store_dwordx4 v[204:205], v[136:139], off
	v_add_u32_e32 v204, 0x48000, v194
	v_mov_b32_e32 v205, v159
	v_sub_f32_e32 v137, v213, v220
	v_sub_f32_e32 v136, v212, v220
	v_sub_f32_e32 v139, v215, v220
	v_sub_f32_e32 v138, v214, v220
	v_pk_mul_f32 v[138:139], v[220:221], v[138:139] op_sel:[1,0]
	v_pk_mul_f32 v[136:137], v[220:221], v[136:137] op_sel:[1,0]
	v_pk_fma_f32 v[138:139], v[152:153], v[138:139], v[86:87]
	v_pk_fma_f32 v[136:137], v[154:155], v[136:137], v[84:85]
	v_pk_fma_f32 v[138:139], v[134:135], s[78:79], v[138:139] op_sel_hi:[1,0,1]
	v_pk_fma_f32 v[136:137], v[132:133], s[78:79], v[136:137] op_sel_hi:[1,0,1]
	v_lshl_add_u64 v[204:205], v[204:205], 2, s[90:91]
	global_store_dwordx4 v[204:205], v[136:139], off
	v_add_u32_e32 v204, 0x48010, v194
	v_mov_b32_e32 v205, v159
	v_sub_f32_e32 v137, v217, v220
	v_sub_f32_e32 v136, v216, v220
	v_sub_f32_e32 v139, v219, v220
	v_sub_f32_e32 v138, v218, v220
	v_pk_mul_f32 v[138:139], v[220:221], v[138:139] op_sel:[1,0]
	v_pk_mul_f32 v[136:137], v[220:221], v[136:137] op_sel:[1,0]
	v_pk_fma_f32 v[138:139], v[148:149], v[138:139], v[82:83]
	v_pk_fma_f32 v[136:137], v[150:151], v[136:137], v[80:81]
	v_pk_fma_f32 v[138:139], v[130:131], s[78:79], v[138:139] op_sel_hi:[1,0,1]
	v_pk_fma_f32 v[136:137], v[128:129], s[78:79], v[136:137] op_sel_hi:[1,0,1]
	v_lshl_add_u64 v[204:205], v[204:205], 2, s[90:91]
	global_store_dwordx4 v[204:205], v[136:139], off
	s_nop 1
	v_add_u32_e32 v138, 0xa0, v206
	v_lshlrev_b32_e32 v136, 1, v138
	v_mov_b32_e32 v137, v159
	v_lshlrev_b32_e32 v237, 11, v138
	v_lshl_add_u64 v[204:205], v[136:137], 2, s[2:3]
	v_add_u32_e32 v136, v237, v158
	v_lshl_add_u64 v[136:137], v[136:137], 2, s[88:89]
	global_load_dwordx2 v[220:221], v[204:205], off
	v_add_u32_e32 v208, v237, v231
	global_load_dwordx4 v[136:139], v[136:137], off
	v_mov_b32_e32 v209, v159
	v_lshl_add_u64 v[208:209], v[208:209], 2, s[88:89]
	global_load_dwordx4 v[212:215], v[208:209], off
	v_add_u32_e32 v208, 0xb0, v206
	v_lshlrev_b32_e32 v206, 1, v208
	v_mov_b32_e32 v207, v159
	v_lshlrev_b32_e32 v238, 11, v208
	v_lshl_add_u64 v[210:211], v[206:207], 2, s[2:3]
	v_add_u32_e32 v206, v238, v158
	v_lshl_add_u64 v[206:207], v[206:207], 2, s[88:89]
	global_load_dwordx2 v[240:241], v[210:211], off
	v_add_u32_e32 v216, v238, v231
	global_load_dwordx4 v[206:209], v[206:207], off
	v_mov_b32_e32 v217, v159
	v_lshl_add_u64 v[216:217], v[216:217], 2, s[88:89]
	global_load_dwordx4 v[216:219], v[216:217], off
	v_add_u32_e32 v242, 0x50000, v194
	v_mov_b32_e32 v243, v159
	v_lshl_add_u64 v[242:243], v[242:243], 2, s[90:91]
	s_waitcnt vmcnt(0)
	v_sub_f32_e32 v137, v137, v220
	v_sub_f32_e32 v136, v136, v220
	v_sub_f32_e32 v139, v139, v220
	v_sub_f32_e32 v138, v138, v220
	v_pk_mul_f32 v[138:139], v[220:221], v[138:139] op_sel:[1,0]
	v_pk_mul_f32 v[136:137], v[220:221], v[136:137] op_sel:[1,0]
	v_pk_fma_f32 v[138:139], v[152:153], v[138:139], v[78:79]
	v_pk_fma_f32 v[136:137], v[154:155], v[136:137], v[76:77]
	v_pk_fma_f32 v[138:139], v[134:135], s[78:79], v[138:139] op_sel_hi:[1,0,1]
	v_pk_fma_f32 v[136:137], v[132:133], s[78:79], v[136:137] op_sel_hi:[1,0,1]
	global_store_dwordx4 v[242:243], v[136:139], off
	s_nop 1
	v_sub_f32_e32 v137, v213, v220
	v_sub_f32_e32 v136, v212, v220
	v_sub_f32_e32 v139, v215, v220
	v_sub_f32_e32 v138, v214, v220
	v_pk_mul_f32 v[138:139], v[220:221], v[138:139] op_sel:[1,0]
	v_pk_mul_f32 v[136:137], v[220:221], v[136:137] op_sel:[1,0]
	v_pk_fma_f32 v[138:139], v[148:149], v[138:139], v[74:75]
	v_pk_fma_f32 v[136:137], v[150:151], v[136:137], v[72:73]
	v_add_u32_e32 v212, 0x50010, v194
	v_mov_b32_e32 v213, v159
	v_pk_fma_f32 v[138:139], v[130:131], s[78:79], v[138:139] op_sel_hi:[1,0,1]
	v_pk_fma_f32 v[136:137], v[128:129], s[78:79], v[136:137] op_sel_hi:[1,0,1]
	v_lshl_add_u64 v[212:213], v[212:213], 2, s[90:91]
	global_store_dwordx4 v[212:213], v[136:139], off
	s_nop 1
	v_sub_f32_e32 v137, v207, v240
	v_sub_f32_e32 v136, v206, v240
	v_sub_f32_e32 v139, v209, v240
	v_sub_f32_e32 v138, v208, v240
	v_pk_mul_f32 v[136:137], v[240:241], v[136:137] op_sel:[1,0]
	v_pk_mul_f32 v[138:139], v[240:241], v[138:139] op_sel:[1,0]
	v_pk_fma_f32 v[136:137], v[154:155], v[136:137], v[68:69]
	v_pk_fma_f32 v[138:139], v[152:153], v[138:139], v[70:71]
	v_pk_fma_f32 v[132:133], v[132:133], s[78:79], v[136:137] op_sel_hi:[1,0,1]
	v_add_u32_e32 v136, 0x58000, v194
	v_mov_b32_e32 v137, v159
	v_pk_fma_f32 v[134:135], v[134:135], s[78:79], v[138:139] op_sel_hi:[1,0,1]
	v_lshl_add_u64 v[136:137], v[136:137], 2, s[90:91]
	global_store_dwordx4 v[136:137], v[132:135], off
	s_nop 1
	v_sub_f32_e32 v133, v217, v240
	v_sub_f32_e32 v132, v216, v240
	v_sub_f32_e32 v135, v219, v240
	v_sub_f32_e32 v134, v218, v240
	v_pk_mul_f32 v[132:133], v[240:241], v[132:133] op_sel:[1,0]
	v_pk_mul_f32 v[134:135], v[240:241], v[134:135] op_sel:[1,0]
	v_pk_fma_f32 v[132:133], v[150:151], v[132:133], v[64:65]
	v_pk_fma_f32 v[134:135], v[148:149], v[134:135], v[66:67]
	v_pk_fma_f32 v[128:129], v[128:129], s[78:79], v[132:133] op_sel_hi:[1,0,1]
	v_add_u32_e32 v132, 0x58010, v194
	v_mov_b32_e32 v133, v159
	v_pk_fma_f32 v[130:131], v[130:131], s[78:79], v[134:135] op_sel_hi:[1,0,1]
	v_lshl_add_u64 v[132:133], v[132:133], 2, s[90:91]
	global_store_dwordx4 v[132:133], v[128:131], off
	global_load_dwordx4 v[128:131], v[140:141], off offset:512
	v_add_u32_e32 v136, v232, v230
	v_mov_b32_e32 v137, v159
	v_lshl_add_u64 v[136:137], v[136:137], 2, s[88:89]
	s_waitcnt vmcnt(0)
;     template <bool LN, int BJ> DI void load_gb(unsigned col0, f32x4 (&gv)[2], f32x4 (&bv)[2]) const {
; #pragma unroll
;         for (int n = 0; n < 2; ++n) {
;             if (LN) { gv[n] = *(const f32x4*)(gam + col0 + BJ * HALF + n * 16) * ALPHA; bv[n] = *(const f32x4*)(bet + col0 + BJ * HALF + n * 16) * ALPHA; }
;             else { gv[n] = (f32x4){ALPHA, ALPHA, ALPHA, ALPHA}; bv[n] = (f32x4){0.f, 0.f, 0.f, 0.f}; }
;         }
;     }
;     template <bool LN> DI void run(const f32x4 (&acc)[2][2][4][2], const Unit& u, int wr, int wc, int fr, int fq) const {
;         const unsigned row0 = u.pm * BM + wr * 64 + fr, col0 = u.pn * BM + wc * 32 + 4 * fq;
;         f32x4 gv[2], bv[2];
;         load_gb<LN, 0>(col0, gv, bv);
;         batch<LN, 0, 0, 4>(acc, row0, col0, gv, bv);
;         batch<LN, 0, 4, 8>(acc, row0, col0, gv, bv);
;         batch<LN, 0, 8, 12>(acc, row0, col0, gv, bv);
;         batch<LN, 0, 12, 16>(acc, row0, col0, gv, bv);
;         load_gb<LN, 1>(col0, gv, bv);
;         batch<LN, 1, 0, 8>(acc, row0, col0, gv, bv);
;         batch<LN, 1, 8, 16>(acc, row0, col0, gv, bv);
	v_pk_mul_f32 v[212:213], v[130:131], s[78:79] op_sel_hi:[1,0]
	v_pk_mul_f32 v[214:215], v[128:129], s[78:79] op_sel_hi:[1,0]
	global_load_dwordx4 v[132:135], v[142:143], off offset:512
	global_load_dwordx4 v[128:131], v[140:141], off offset:576
	s_waitcnt vmcnt(0)
	v_pk_mul_f32 v[206:207], v[130:131], s[78:79] op_sel_hi:[1,0]
	v_pk_mul_f32 v[208:209], v[128:129], s[78:79] op_sel_hi:[1,0]
	global_load_dwordx4 v[128:131], v[142:143], off offset:576
	global_load_dwordx2 v[220:221], v[144:145], off
	global_load_dwordx4 v[240:243], v[136:137], off
	v_add_u32_e32 v136, v232, v229
	v_mov_b32_e32 v137, v159
	v_lshl_add_u64 v[136:137], v[136:137], 2, s[88:89]
	global_load_dwordx4 v[244:247], v[136:137], off
	global_load_dwordx2 v[218:219], v[146:147], off
	v_add_u32_e32 v136, v195, v230
	v_mov_b32_e32 v137, v159
	v_lshl_add_u64 v[136:137], v[136:137], 2, s[88:89]
	global_load_dwordx4 v[248:251], v[136:137], off
	v_add_u32_e32 v136, v195, v229
	v_mov_b32_e32 v137, v159
	v_lshl_add_u64 v[136:137], v[136:137], 2, s[88:89]
	global_load_dwordx4 v[152:155], v[136:137], off
	global_load_dwordx2 v[216:217], v[200:201], off
	v_add_u32_e32 v136, v236, v230
	v_mov_b32_e32 v137, v159
	v_lshl_add_u64 v[136:137], v[136:137], 2, s[88:89]
	global_load_dwordx4 v[148:151], v[136:137], off
	v_add_u32_e32 v136, v236, v229
	v_mov_b32_e32 v137, v159
	v_lshl_add_u64 v[136:137], v[136:137], 2, s[88:89]
	global_load_dwordx4 v[144:147], v[136:137], off
	global_load_dwordx2 v[200:201], v[202:203], off
	v_add_u32_e32 v136, v235, v230
	v_mov_b32_e32 v137, v159
	v_lshl_add_u64 v[136:137], v[136:137], 2, s[88:89]
	global_load_dwordx4 v[140:143], v[136:137], off
	v_add_u32_e32 v136, v235, v229
	v_mov_b32_e32 v137, v159
	v_lshl_add_u64 v[136:137], v[136:137], 2, s[88:89]
	global_load_dwordx4 v[136:139], v[136:137], off
	v_add_u32_e32 v202, 0x80, v194
	v_mov_b32_e32 v203, v159
	v_lshl_add_u64 v[202:203], v[202:203], 2, s[90:91]
	s_waitcnt vmcnt(0)
	v_sub_f32_e32 v241, v241, v220
	v_sub_f32_e32 v240, v240, v220
	v_sub_f32_e32 v243, v243, v220
	v_sub_f32_e32 v242, v242, v220
	v_pk_mul_f32 v[242:243], v[220:221], v[242:243] op_sel:[1,0]
	v_pk_mul_f32 v[240:241], v[220:221], v[240:241] op_sel:[1,0]
	v_pk_fma_f32 v[242:243], v[212:213], v[242:243], v[62:63]
	v_pk_fma_f32 v[240:241], v[214:215], v[240:241], v[60:61]
	v_pk_fma_f32 v[242:243], v[134:135], s[78:79], v[242:243] op_sel_hi:[1,0,1]
	v_pk_fma_f32 v[240:241], v[132:133], s[78:79], v[240:241] op_sel_hi:[1,0,1]
	global_store_dwordx4 v[202:203], v[240:243], off
	v_sub_f32_e32 v203, v245, v220
	v_sub_f32_e32 v202, v244, v220
	v_sub_f32_e32 v241, v247, v220
	v_sub_f32_e32 v240, v246, v220
	v_pk_mul_f32 v[202:203], v[220:221], v[202:203] op_sel:[1,0]
	v_pk_mul_f32 v[240:241], v[220:221], v[240:241] op_sel:[1,0]
	v_pk_fma_f32 v[202:203], v[208:209], v[202:203], v[56:57]
	v_pk_fma_f32 v[220:221], v[206:207], v[240:241], v[58:59]
	v_pk_fma_f32 v[240:241], v[128:129], s[78:79], v[202:203] op_sel_hi:[1,0,1]
	v_add_u32_e32 v202, 0x90, v194
	v_mov_b32_e32 v203, v159
	v_pk_fma_f32 v[242:243], v[130:131], s[78:79], v[220:221] op_sel_hi:[1,0,1]
	v_lshl_add_u64 v[202:203], v[202:203], 2, s[90:91]
	global_store_dwordx4 v[202:203], v[240:243], off
	v_sub_f32_e32 v203, v249, v218
	v_sub_f32_e32 v202, v248, v218
	v_sub_f32_e32 v221, v251, v218
	v_sub_f32_e32 v220, v250, v218
	v_pk_mul_f32 v[202:203], v[218:219], v[202:203] op_sel:[1,0]
	v_pk_mul_f32 v[220:221], v[218:219], v[220:221] op_sel:[1,0]
	v_pk_fma_f32 v[202:203], v[214:215], v[202:203], v[52:53]
	v_pk_fma_f32 v[220:221], v[212:213], v[220:221], v[54:55]
	v_pk_fma_f32 v[240:241], v[132:133], s[78:79], v[202:203] op_sel_hi:[1,0,1]
	v_add_u32_e32 v202, 0x8080, v194
	v_mov_b32_e32 v203, v159
	v_sub_f32_e32 v153, v153, v218
	v_sub_f32_e32 v152, v152, v218
	v_sub_f32_e32 v155, v155, v218
	v_sub_f32_e32 v154, v154, v218
	v_pk_fma_f32 v[242:243], v[134:135], s[78:79], v[220:221] op_sel_hi:[1,0,1]
	v_lshl_add_u64 v[202:203], v[202:203], 2, s[90:91]
	v_pk_mul_f32 v[154:155], v[218:219], v[154:155] op_sel:[1,0]
	v_pk_mul_f32 v[152:153], v[218:219], v[152:153] op_sel:[1,0]
	global_store_dwordx4 v[202:203], v[240:243], off
	v_pk_fma_f32 v[152:153], v[208:209], v[152:153], v[48:49]
	v_pk_fma_f32 v[154:155], v[206:207], v[154:155], v[50:51]
	v_add_u32_e32 v202, 0x8090, v194
	v_mov_b32_e32 v203, v159
	v_sub_f32_e32 v149, v149, v216
	v_sub_f32_e32 v148, v148, v216
	v_sub_f32_e32 v151, v151, v216
	v_sub_f32_e32 v150, v150, v216
	v_pk_fma_f32 v[154:155], v[130:131], s[78:79], v[154:155] op_sel_hi:[1,0,1]
	v_pk_fma_f32 v[152:153], v[128:129], s[78:79], v[152:153] op_sel_hi:[1,0,1]
	v_lshl_add_u64 v[202:203], v[202:203], 2, s[90:91]
	v_pk_mul_f32 v[150:151], v[216:217], v[150:151] op_sel:[1,0]
	v_pk_mul_f32 v[148:149], v[216:217], v[148:149] op_sel:[1,0]
	global_store_dwordx4 v[202:203], v[152:155], off
	v_pk_fma_f32 v[148:149], v[214:215], v[148:149], v[44:45]
	v_pk_fma_f32 v[150:151], v[212:213], v[150:151], v[46:47]
	v_add_u32_e32 v152, 0x10080, v194
	v_mov_b32_e32 v153, v159
	v_sub_f32_e32 v145, v145, v216
	v_sub_f32_e32 v144, v144, v216
	v_sub_f32_e32 v147, v147, v216
	v_sub_f32_e32 v146, v146, v216
	v_pk_fma_f32 v[150:151], v[134:135], s[78:79], v[150:151] op_sel_hi:[1,0,1]
	v_pk_fma_f32 v[148:149], v[132:133], s[78:79], v[148:149] op_sel_hi:[1,0,1]
	v_lshl_add_u64 v[152:153], v[152:153], 2, s[90:91]
	v_pk_mul_f32 v[146:147], v[216:217], v[146:147] op_sel:[1,0]
	v_pk_mul_f32 v[144:145], v[216:217], v[144:145] op_sel:[1,0]
	global_store_dwordx4 v[152:153], v[148:151], off
	v_pk_fma_f32 v[144:145], v[208:209], v[144:145], v[40:41]
	v_pk_fma_f32 v[146:147], v[206:207], v[146:147], v[42:43]
;     template <bool LN, int BJ, int LO, int HI> DI void batch(const f32x4 (&acc)[2][2][4][2], unsigned row0, unsigned col0, const f32x4 (&gv)[2], const f32x4 (&bv)[2]) const {
;         f32x4 r[HI - LO]; float mean[(HI - LO) / 2], rstd[(HI - LO) / 2];
; #pragma unroll
;         for (int i = LO; i < HI; ++i) { const int ai = i >> 3, m = (i >> 1) & 3, n = i & 1; const unsigned row = row0 + ai * HALF + m * 16;
;             if (n == 0) { mean[(i - LO) >> 1] = 0.f; rstd[(i - LO) >> 1] = 1.f;
;                 if (LN) { const float2 st = *(const float2*)(stats + row * 2u); mean[(i - LO) >> 1] = st.x; rstd[(i - LO) >> 1] = st.y; } }
;             r[i - LO] = *(const f32x4*)(src + (row * (unsigned)DM + col0 + BJ * HALF + n * 16)); }
; #pragma unroll
;         for (int i = LO; i < HI; ++i) { const int ai = i >> 3, m = (i >> 1) & 3, n = i & 1; const unsigned row = row0 + ai * HALF + m * 16;
;             *(f32x4*)(Y + (row * (unsigned)DM + col0 + BJ * HALF + n * 16)) = acc[ai][BJ][m][n] + ((r[i - LO] - mean[(i - LO) >> 1]) * rstd[(i - LO) >> 1]) * gv[n] + bv[n]; }
	v_add_u32_e32 v148, 0x10090, v194
	v_mov_b32_e32 v149, v159
	v_sub_f32_e32 v141, v141, v200
	v_sub_f32_e32 v140, v140, v200
	v_sub_f32_e32 v143, v143, v200
	v_sub_f32_e32 v142, v142, v200
	v_pk_fma_f32 v[146:147], v[130:131], s[78:79], v[146:147] op_sel_hi:[1,0,1]
	v_pk_fma_f32 v[144:145], v[128:129], s[78:79], v[144:145] op_sel_hi:[1,0,1]
	v_lshl_add_u64 v[148:149], v[148:149], 2, s[90:91]
	v_pk_mul_f32 v[142:143], v[200:201], v[142:143] op_sel:[1,0]
	v_pk_mul_f32 v[140:141], v[200:201], v[140:141] op_sel:[1,0]
	global_store_dwordx4 v[148:149], v[144:147], off
	v_pk_fma_f32 v[140:141], v[214:215], v[140:141], v[36:37]
	v_pk_fma_f32 v[142:143], v[212:213], v[142:143], v[38:39]
	v_add_u32_e32 v144, 0x18080, v194
	v_mov_b32_e32 v145, v159
	v_sub_f32_e32 v137, v137, v200
	v_sub_f32_e32 v136, v136, v200
	v_sub_f32_e32 v139, v139, v200
	v_sub_f32_e32 v138, v138, v200
	v_pk_fma_f32 v[142:143], v[134:135], s[78:79], v[142:143] op_sel_hi:[1,0,1]
	v_pk_fma_f32 v[140:141], v[132:133], s[78:79], v[140:141] op_sel_hi:[1,0,1]
	v_lshl_add_u64 v[144:145], v[144:145], 2, s[90:91]
	v_pk_mul_f32 v[138:139], v[200:201], v[138:139] op_sel:[1,0]
	v_pk_mul_f32 v[136:137], v[200:201], v[136:137] op_sel:[1,0]
	global_store_dwordx4 v[144:145], v[140:143], off
	v_pk_fma_f32 v[136:137], v[208:209], v[136:137], v[32:33]
	v_pk_fma_f32 v[138:139], v[206:207], v[138:139], v[34:35]
	v_add_u32_e32 v140, 0x18090, v194
	v_mov_b32_e32 v141, v159
	v_pk_fma_f32 v[138:139], v[130:131], s[78:79], v[138:139] op_sel_hi:[1,0,1]
	v_pk_fma_f32 v[136:137], v[128:129], s[78:79], v[136:137] op_sel_hi:[1,0,1]
	v_lshl_add_u64 v[140:141], v[140:141], 2, s[90:91]
	global_store_dwordx4 v[140:141], v[136:139], off
	s_nop 1
	v_add_u32_e32 v136, v233, v230
	v_mov_b32_e32 v137, v159
	v_lshl_add_u64 v[136:137], v[136:137], 2, s[88:89]
	global_load_dwordx2 v[220:221], v[196:197], off
	global_load_dwordx4 v[216:219], v[136:137], off
	v_add_u32_e32 v136, v233, v229
	v_mov_b32_e32 v137, v159
	v_lshl_add_u64 v[136:137], v[136:137], 2, s[88:89]
	global_load_dwordx4 v[240:243], v[136:137], off
	global_load_dwordx2 v[200:201], v[198:199], off
	v_add_u32_e32 v136, v234, v230
	v_mov_b32_e32 v137, v159
	v_lshl_add_u64 v[136:137], v[136:137], 2, s[88:89]
	global_load_dwordx4 v[244:247], v[136:137], off
	v_add_u32_e32 v136, v234, v229
	v_mov_b32_e32 v137, v159
	v_lshl_add_u64 v[136:137], v[136:137], 2, s[88:89]
	global_load_dwordx4 v[152:155], v[136:137], off
	global_load_dwordx2 v[198:199], v[204:205], off
	v_add_u32_e32 v136, v237, v230
	v_mov_b32_e32 v137, v159
	v_lshl_add_u64 v[136:137], v[136:137], 2, s[88:89]
	global_load_dwordx4 v[148:151], v[136:137], off
	v_add_u32_e32 v136, v237, v229
	v_mov_b32_e32 v137, v159
	v_lshl_add_u64 v[136:137], v[136:137], 2, s[88:89]
	global_load_dwordx4 v[144:147], v[136:137], off
	global_load_dwordx2 v[196:197], v[210:211], off
	v_add_u32_e32 v136, v238, v230
	v_mov_b32_e32 v137, v159
	v_lshl_add_u64 v[136:137], v[136:137], 2, s[88:89]
	global_load_dwordx4 v[140:143], v[136:137], off
	v_add_u32_e32 v136, v238, v229
	v_mov_b32_e32 v137, v159
	v_lshl_add_u64 v[136:137], v[136:137], 2, s[88:89]
	global_load_dwordx4 v[136:139], v[136:137], off
	v_add_u32_e32 v210, 0x40080, v194
	v_mov_b32_e32 v211, v159
	v_lshl_add_u64 v[210:211], v[210:211], 2, s[90:91]
	s_waitcnt vmcnt(0)
;     template <bool LN, int BJ, int LO, int HI> DI void batch(const f32x4 (&acc)[2][2][4][2], unsigned row0, unsigned col0, const f32x4 (&gv)[2], const f32x4 (&bv)[2]) const {
;         f32x4 r[HI - LO]; float mean[(HI - LO) / 2], rstd[(HI - LO) / 2];
; #pragma unroll
;         for (int i = LO; i < HI; ++i) { const int ai = i >> 3, m = (i >> 1) & 3, n = i & 1; const unsigned row = row0 + ai * HALF + m * 16;
;             if (n == 0) { mean[(i - LO) >> 1] = 0.f; rstd[(i - LO) >> 1] = 1.f;
;                 if (LN) { const float2 st = *(const float2*)(stats + row * 2u); mean[(i - LO) >> 1] = st.x; rstd[(i - LO) >> 1] = st.y; } }
;             r[i - LO] = *(const f32x4*)(src + (row * (unsigned)DM + col0 + BJ * HALF + n * 16)); }
; #pragma unroll
;         for (int i = LO; i < HI; ++i) { const int ai = i >> 3, m = (i >> 1) & 3, n = i & 1; const unsigned row = row0 + ai * HALF + m * 16;
;             *(f32x4*)(Y + (row * (unsigned)DM + col0 + BJ * HALF + n * 16)) = acc[ai][BJ][m][n] + ((r[i - LO] - mean[(i - LO) >> 1]) * rstd[(i - LO) >> 1]) * gv[n] + bv[n]; }
	v_sub_f32_e32 v203, v217, v220
	v_sub_f32_e32 v202, v216, v220
	v_sub_f32_e32 v205, v219, v220
	v_sub_f32_e32 v204, v218, v220
	v_pk_mul_f32 v[204:205], v[220:221], v[204:205] op_sel:[1,0]
	v_pk_mul_f32 v[202:203], v[220:221], v[202:203] op_sel:[1,0]
	v_pk_fma_f32 v[204:205], v[212:213], v[204:205], v[30:31]
	v_pk_fma_f32 v[202:203], v[214:215], v[202:203], v[28:29]
	v_pk_fma_f32 v[204:205], v[134:135], s[78:79], v[204:205] op_sel_hi:[1,0,1]
	v_pk_fma_f32 v[202:203], v[132:133], s[78:79], v[202:203] op_sel_hi:[1,0,1]
	global_store_dwordx4 v[210:211], v[202:205], off
	v_add_u32_e32 v210, 0x40090, v194
	v_mov_b32_e32 v211, v159
	v_sub_f32_e32 v203, v241, v220
	v_sub_f32_e32 v202, v240, v220
	v_sub_f32_e32 v205, v243, v220
	v_sub_f32_e32 v204, v242, v220
	v_pk_mul_f32 v[204:205], v[220:221], v[204:205] op_sel:[1,0]
	v_pk_mul_f32 v[202:203], v[220:221], v[202:203] op_sel:[1,0]
	v_pk_fma_f32 v[204:205], v[206:207], v[204:205], v[26:27]
	v_pk_fma_f32 v[202:203], v[208:209], v[202:203], v[24:25]
	v_pk_fma_f32 v[204:205], v[130:131], s[78:79], v[204:205] op_sel_hi:[1,0,1]
	v_pk_fma_f32 v[202:203], v[128:129], s[78:79], v[202:203] op_sel_hi:[1,0,1]
	v_lshl_add_u64 v[210:211], v[210:211], 2, s[90:91]
	global_store_dwordx4 v[210:211], v[202:205], off
	v_sub_f32_e32 v149, v149, v198
	v_sub_f32_e32 v148, v148, v198
	v_sub_f32_e32 v203, v245, v200
	v_sub_f32_e32 v202, v244, v200
	v_sub_f32_e32 v141, v141, v196
	v_sub_f32_e32 v140, v140, v196
	v_sub_f32_e32 v205, v247, v200
	v_sub_f32_e32 v204, v246, v200
	v_pk_mul_f32 v[202:203], v[200:201], v[202:203] op_sel:[1,0]
	v_sub_f32_e32 v151, v151, v198
	v_sub_f32_e32 v150, v150, v198
	v_pk_mul_f32 v[148:149], v[198:199], v[148:149] op_sel:[1,0]
	v_sub_f32_e32 v143, v143, v196
	v_sub_f32_e32 v142, v142, v196
	v_pk_mul_f32 v[140:141], v[196:197], v[140:141] op_sel:[1,0]
	v_pk_mul_f32 v[204:205], v[200:201], v[204:205] op_sel:[1,0]
	v_pk_fma_f32 v[202:203], v[214:215], v[202:203], v[20:21]
	v_sub_f32_e32 v153, v153, v200
	v_sub_f32_e32 v152, v152, v200
	v_sub_f32_e32 v155, v155, v200
	v_sub_f32_e32 v154, v154, v200
	v_pk_mul_f32 v[150:151], v[198:199], v[150:151] op_sel:[1,0]
	v_pk_fma_f32 v[148:149], v[214:215], v[148:149], v[12:13]
	v_pk_mul_f32 v[142:143], v[196:197], v[142:143] op_sel:[1,0]
	v_pk_fma_f32 v[140:141], v[214:215], v[140:141], v[4:5]
	v_pk_fma_f32 v[204:205], v[212:213], v[204:205], v[22:23]
	v_pk_fma_f32 v[202:203], v[132:133], s[78:79], v[202:203] op_sel_hi:[1,0,1]
	v_pk_mul_f32 v[154:155], v[200:201], v[154:155] op_sel:[1,0]
	v_pk_mul_f32 v[152:153], v[200:201], v[152:153] op_sel:[1,0]
	v_pk_fma_f32 v[150:151], v[212:213], v[150:151], v[14:15]
	v_pk_fma_f32 v[148:149], v[132:133], s[78:79], v[148:149] op_sel_hi:[1,0,1]
	v_pk_fma_f32 v[142:143], v[212:213], v[142:143], v[6:7]
	v_pk_fma_f32 v[132:133], v[132:133], s[78:79], v[140:141] op_sel_hi:[1,0,1]
	v_add_u32_e32 v140, 0x58080, v194
	v_mov_b32_e32 v141, v159
	v_pk_fma_f32 v[204:205], v[134:135], s[78:79], v[204:205] op_sel_hi:[1,0,1]
	v_pk_fma_f32 v[152:153], v[208:209], v[152:153], v[16:17]
	v_pk_fma_f32 v[154:155], v[206:207], v[154:155], v[18:19]
	v_add_u32_e32 v200, 0x48090, v194
	v_mov_b32_e32 v201, v159
	v_pk_fma_f32 v[150:151], v[134:135], s[78:79], v[150:151] op_sel_hi:[1,0,1]
	v_pk_fma_f32 v[134:135], v[134:135], s[78:79], v[142:143] op_sel_hi:[1,0,1]
	v_lshl_add_u64 v[140:141], v[140:141], 2, s[90:91]
	v_pk_fma_f32 v[154:155], v[130:131], s[78:79], v[154:155] op_sel_hi:[1,0,1]
	v_pk_fma_f32 v[152:153], v[128:129], s[78:79], v[152:153] op_sel_hi:[1,0,1]
	v_lshl_add_u64 v[200:201], v[200:201], 2, s[90:91]
	v_sub_f32_e32 v145, v145, v198
	v_sub_f32_e32 v144, v144, v198
	global_store_dwordx4 v[140:141], v[132:135], off
	global_store_dwordx4 v[200:201], v[152:155], off
	v_sub_f32_e32 v147, v147, v198
	v_sub_f32_e32 v133, v137, v196
	v_sub_f32_e32 v132, v136, v196
	v_add_u32_e32 v152, 0x50080, v194
	v_mov_b32_e32 v153, v159
	v_sub_f32_e32 v146, v146, v198
	v_pk_mul_f32 v[144:145], v[198:199], v[144:145] op_sel:[1,0]
	v_sub_f32_e32 v135, v139, v196
	v_sub_f32_e32 v134, v138, v196
	v_pk_mul_f32 v[132:133], v[196:197], v[132:133] op_sel:[1,0]
	v_lshl_add_u64 v[152:153], v[152:153], 2, s[90:91]
	v_pk_mul_f32 v[146:147], v[198:199], v[146:147] op_sel:[1,0]
	v_pk_fma_f32 v[144:145], v[208:209], v[144:145], v[8:9]
	v_pk_mul_f32 v[134:135], v[196:197], v[134:135] op_sel:[1,0]
	v_pk_fma_f32 v[132:133], v[208:209], v[132:133], v[0:1]
	v_add_u32_e32 v210, 0x48080, v194
	v_mov_b32_e32 v211, v159
	global_store_dwordx4 v[152:153], v[148:151], off
	v_pk_fma_f32 v[146:147], v[206:207], v[146:147], v[10:11]
	v_pk_fma_f32 v[144:145], v[128:129], s[78:79], v[144:145] op_sel_hi:[1,0,1]
	v_add_u32_e32 v148, 0x50090, v194
	v_mov_b32_e32 v149, v159
	v_pk_fma_f32 v[134:135], v[206:207], v[134:135], v[2:3]
	v_pk_fma_f32 v[128:129], v[128:129], s[78:79], v[132:133] op_sel_hi:[1,0,1]
	v_add_u32_e32 v132, 0x58090, v194
	v_mov_b32_e32 v133, v159
	v_lshl_add_u64 v[210:211], v[210:211], 2, s[90:91]
	v_pk_fma_f32 v[146:147], v[130:131], s[78:79], v[146:147] op_sel_hi:[1,0,1]
	v_lshl_add_u64 v[148:149], v[148:149], 2, s[90:91]
	v_pk_fma_f32 v[130:131], v[130:131], s[78:79], v[134:135] op_sel_hi:[1,0,1]
	v_lshl_add_u64 v[132:133], v[132:133], 2, s[90:91]
	global_store_dwordx4 v[210:211], v[202:205], off
	global_store_dwordx4 v[148:149], v[144:147], off
	global_store_dwordx4 v[132:133], v[128:131], off
	s_mov_b64 s[20:21], 0
	s_branch .LBB0_81

; #define PG8_STAGE(bufoff, gbase) do { _Pragma("unroll") for (int _i = 0; _i < 2; ++_i) \
;         __builtin_amdgcn_global_load_lds((const unsigned*)((const char*)(gbase) + voff[_i]), (LAS unsigned*)(lds + (bufoff) + ldsw + _i * 8192), 16, 0, 0); } while (0)
; #define PG8_LDA(dst, b, h) do { _Pragma("unroll") for (int m = 0; m < 4; ++m) _Pragma("unroll") for (int k = 0; k < 2; ++k) dst[m][k] = *(const LAS bf16x8*)(lds + PG8_SA(b, h) + aoff + m * 2048 + k * 1024); } while (0)
; #define PG8_LDB(dst, b, h) do { _Pragma("unroll") for (int n = 0; n < 2; ++n) _Pragma("unroll") for (int k = 0; k < 2; ++k) dst[n][k] = *(const LAS bf16x8*)(lds + PG8_SB(b, h) + boff + n * 2048 + k * 1024); } while (0)
; #define PG8_MMA(ai, bj, At, Bt) do { __builtin_amdgcn_s_setprio(1); _Pragma("unroll") for (int m = 0; m < 4; ++m) _Pragma("unroll") for (int n = 0; n < 2; ++n) _Pragma("unroll") for (int k = 0; k < 2; ++k) \
;         acc[ai][bj][m][n] = __builtin_amdgcn_mfma_f32_16x16x32_bf16(Bt[n][k], At[m][k], acc[ai][bj][m][n], 0, 0, 0); __builtin_amdgcn_s_setprio(0); } while (0)
; #define PG8_WAIT_L(n) asm volatile("s_waitcnt lgkmcnt(" #n ")" ::: "memory")
; #define PG8_BAR __builtin_amdgcn_s_barrier()
; #define PG8_SCHED __builtin_amdgcn_sched_barrier(0)
; template <class Epi>
; DI void gemm_phase(LAS unsigned char* lds, const Gemm g, const StaticOrder& S, const Epi& E) {
;     ...
;         for (int t = 0; t < nt; t += 2) {
;             const bool last = (t == nt - 2);
;             const char* a1 = cA + (size_t)(t + 1) * kstep;
;             const char* a2 = last ? nA : cA + (size_t)(t + 2) * kstep; const char* b2 = last ? nB : cB + (size_t)(t + 2) * kstep;
;             const char* a3 = a2 + kstep; const char* b3 = b2 + kstep;
;             PG8_LDB(B0, 0, 0); PG8_SCHED; PG8_LDA(At, 0, 0); PG8_STAGE(PG8_SA(1, 1), a1 + hstep);
;             PG8_WAIT_L(8); PG8_BAR; PG8_WAIT_L(0); PG8_MMA(0, 0, At, B0); PG8_BAR; PG8_SCHED;
;             PG8_LDB(B1, 0, 1); PG8_STAGE(PG8_SB(0, 0), b2);
;             PG8_BAR; PG8_WAIT_L(0); PG8_MMA(0, 1, At, B1); PG8_BAR;
;             PG8_LDA(At, 0, 1); PG8_STAGE(PG8_SA(0, 0), a2);
;             PG8_BAR; PG8_WAIT_L(0); PG8_MMA(1, 0, At, B0); PG8_BAR; PG8_SCHED;
.LBB0_134:
	s_add_u32 s18, s16, 0x100
	s_addc_u32 s19, s17, 0
	s_add_i32 s39, 0, 0x10000
	v_add_u32_e32 v148, s39, v199
	ds_read_b128 v[96:99], v148
	ds_read_b128 v[100:103], v148 offset:1024
	ds_read_b128 v[136:139], v148 offset:2048
	ds_read_b128 v[148:151], v148 offset:3072
	s_cmpk_eq_i32 s33, 0x54
	s_cselect_b32 s23, s9, s19
	s_cselect_b32 s22, s8, s18
	s_cselect_b32 s21, s11, s5
	s_cselect_b32 s20, s10, s4
	v_lshl_add_u64 v[218:219], s[16:17], 0, v[144:145]
	s_add_i32 m0, s28, 0xc000
	ds_read_b128 v[152:155], v201
	ds_read_b128 v[186:189], v201 offset:1024
	ds_read_b128 v[190:193], v201 offset:2048
	ds_read_b128 v[194:197], v201 offset:3072
	ds_read_b128 v[202:205], v201 offset:4096
	ds_read_b128 v[206:209], v201 offset:5120
	ds_read_b128 v[210:213], v201 offset:6144
	ds_read_b128 v[214:217], v201 offset:7168
	global_load_lds_dwordx4 v[218:219], off
	v_lshl_add_u64 v[218:219], s[16:17], 0, v[146:147]
	s_add_i32 m0, s28, 0xe000
	s_nop 0
	global_load_lds_dwordx4 v[218:219], off
	s_waitcnt lgkmcnt(8)
	s_setprio 1
	s_barrier
	s_waitcnt lgkmcnt(0)
	v_mfma_f32_16x16x32_bf16 v[132:135], v[96:99], v[152:155], v[132:135]
	v_mfma_f32_16x16x32_bf16 v[128:131], v[136:139], v[152:155], v[128:131]
	v_mfma_f32_16x16x32_bf16 v[124:127], v[96:99], v[190:193], v[124:127]
	v_mfma_f32_16x16x32_bf16 v[120:123], v[136:139], v[190:193], v[120:123]
	v_mfma_f32_16x16x32_bf16 v[116:119], v[96:99], v[202:205], v[116:119]
	v_mfma_f32_16x16x32_bf16 v[112:115], v[136:139], v[202:205], v[112:115]
	v_mfma_f32_16x16x32_bf16 v[108:111], v[96:99], v[210:213], v[108:111]
	v_mfma_f32_16x16x32_bf16 v[104:107], v[136:139], v[210:213], v[104:107]
	v_mfma_f32_16x16x32_bf16 v[132:135], v[100:103], v[186:189], v[132:135]
	v_mfma_f32_16x16x32_bf16 v[128:131], v[148:151], v[186:189], v[128:131]
	v_mfma_f32_16x16x32_bf16 v[124:127], v[100:103], v[194:197], v[124:127]
	v_mfma_f32_16x16x32_bf16 v[120:123], v[148:151], v[194:197], v[120:123]
	v_mfma_f32_16x16x32_bf16 v[116:119], v[100:103], v[206:209], v[116:119]
	v_mfma_f32_16x16x32_bf16 v[112:115], v[148:151], v[206:209], v[112:115]
	v_mfma_f32_16x16x32_bf16 v[108:111], v[100:103], v[214:217], v[108:111]
	v_mfma_f32_16x16x32_bf16 v[104:107], v[148:151], v[214:217], v[104:107]
	s_setprio 0
	s_barrier
	s_add_i32 s40, 0, 0x14000
	s_add_i32 s16, s39, s27
	v_add_u32_e32 v158, s40, v199
	v_lshl_add_u64 v[218:219], s[20:21], 0, v[142:143]
	s_mov_b32 m0, s16
	ds_read_b128 v[226:229], v158
	ds_read_b128 v[230:233], v158 offset:1024
	ds_read_b128 v[234:237], v158 offset:2048
	ds_read_b128 v[238:241], v158 offset:3072
	global_load_lds_dwordx4 v[218:219], off
	v_lshl_add_u64 v[220:221], s[20:21], 0, v[140:141]
	s_add_i32 m0, s16, 0x2000
	s_nop 0
	global_load_lds_dwordx4 v[220:221], off
	s_waitcnt lgkmcnt(0)
	s_setprio 1
	s_barrier
	v_mfma_f32_16x16x32_bf16 v[60:63], v[226:229], v[152:155], v[60:63]
	v_mfma_f32_16x16x32_bf16 v[56:59], v[234:237], v[152:155], v[56:59]
	v_mfma_f32_16x16x32_bf16 v[52:55], v[226:229], v[190:193], v[52:55]
	v_mfma_f32_16x16x32_bf16 v[48:51], v[234:237], v[190:193], v[48:51]
	v_mfma_f32_16x16x32_bf16 v[44:47], v[226:229], v[202:205], v[44:47]
	v_mfma_f32_16x16x32_bf16 v[40:43], v[234:237], v[202:205], v[40:43]
	v_mfma_f32_16x16x32_bf16 v[36:39], v[226:229], v[210:213], v[36:39]
	v_mfma_f32_16x16x32_bf16 v[32:35], v[234:237], v[210:213], v[32:35]
	v_mfma_f32_16x16x32_bf16 v[60:63], v[230:233], v[186:189], v[60:63]
	v_mfma_f32_16x16x32_bf16 v[56:59], v[238:241], v[186:189], v[56:59]
	v_mfma_f32_16x16x32_bf16 v[52:55], v[230:233], v[194:197], v[52:55]
	v_mfma_f32_16x16x32_bf16 v[48:51], v[238:241], v[194:197], v[48:51]
	v_mfma_f32_16x16x32_bf16 v[44:47], v[230:233], v[206:209], v[44:47]
	v_mfma_f32_16x16x32_bf16 v[40:43], v[238:241], v[206:209], v[40:43]
	v_mfma_f32_16x16x32_bf16 v[36:39], v[230:233], v[214:217], v[36:39]
	v_mfma_f32_16x16x32_bf16 v[32:35], v[238:241], v[214:217], v[32:35]
	s_setprio 0
	s_mov_b32 m0, s28
	v_lshl_add_u64 v[242:243], s[22:23], 0, v[142:143]
	s_barrier
	ds_read_b128 v[152:155], v201 offset:16384
	ds_read_b128 v[186:189], v201 offset:17408
	ds_read_b128 v[190:193], v201 offset:18432
	ds_read_b128 v[194:197], v201 offset:19456
	ds_read_b128 v[202:205], v201 offset:20480
	ds_read_b128 v[206:209], v201 offset:21504
	ds_read_b128 v[210:213], v201 offset:22528
	ds_read_b128 v[214:217], v201 offset:23552
	global_load_lds_dwordx4 v[242:243], off
	v_lshl_add_u64 v[244:245], s[22:23], 0, v[140:141]
	s_mov_b32 m0, s29
	s_nop 0
	global_load_lds_dwordx4 v[244:245], off
	s_waitcnt lgkmcnt(0)
	s_setprio 1
	s_barrier
	v_mfma_f32_16x16x32_bf16 v[92:95], v[96:99], v[152:155], v[92:95]
	v_mfma_f32_16x16x32_bf16 v[88:91], v[136:139], v[152:155], v[88:91]
	v_mfma_f32_16x16x32_bf16 v[84:87], v[96:99], v[190:193], v[84:87]
	v_mfma_f32_16x16x32_bf16 v[80:83], v[136:139], v[190:193], v[80:83]
	v_mfma_f32_16x16x32_bf16 v[76:79], v[96:99], v[202:205], v[76:79]
	v_mfma_f32_16x16x32_bf16 v[72:75], v[136:139], v[202:205], v[72:75]
	v_mfma_f32_16x16x32_bf16 v[68:71], v[96:99], v[210:213], v[68:71]
	v_mfma_f32_16x16x32_bf16 v[64:67], v[136:139], v[210:213], v[64:67]
	v_mfma_f32_16x16x32_bf16 v[92:95], v[100:103], v[186:189], v[92:95]
	v_mfma_f32_16x16x32_bf16 v[88:91], v[148:151], v[186:189], v[88:91]
	v_mfma_f32_16x16x32_bf16 v[84:87], v[100:103], v[194:197], v[84:87]
	v_mfma_f32_16x16x32_bf16 v[80:83], v[148:151], v[194:197], v[80:83]
	v_mfma_f32_16x16x32_bf16 v[76:79], v[100:103], v[206:209], v[76:79]
	v_mfma_f32_16x16x32_bf16 v[72:75], v[148:151], v[206:209], v[72:75]
	v_mfma_f32_16x16x32_bf16 v[68:71], v[100:103], v[214:217], v[68:71]
	v_mfma_f32_16x16x32_bf16 v[64:67], v[148:151], v[214:217], v[64:67]
	s_setprio 0
	s_barrier
; #define PG8_STAGE(bufoff, gbase) do { _Pragma("unroll") for (int _i = 0; _i < 2; ++_i) \
;         __builtin_amdgcn_global_load_lds((const unsigned*)((const char*)(gbase) + voff[_i]), (LAS unsigned*)(lds + (bufoff) + ldsw + _i * 8192), 16, 0, 0); } while (0)
; #define PG8_LDA(dst, b, h) do { _Pragma("unroll") for (int m = 0; m < 4; ++m) _Pragma("unroll") for (int k = 0; k < 2; ++k) dst[m][k] = *(const LAS bf16x8*)(lds + PG8_SA(b, h) + aoff + m * 2048 + k * 1024); } while (0)
; #define PG8_LDB(dst, b, h) do { _Pragma("unroll") for (int n = 0; n < 2; ++n) _Pragma("unroll") for (int k = 0; k < 2; ++k) dst[n][k] = *(const LAS bf16x8*)(lds + PG8_SB(b, h) + boff + n * 2048 + k * 1024); } while (0)
; #define PG8_MMA(ai, bj, At, Bt) do { __builtin_amdgcn_s_setprio(1); _Pragma("unroll") for (int m = 0; m < 4; ++m) _Pragma("unroll") for (int n = 0; n < 2; ++n) _Pragma("unroll") for (int k = 0; k < 2; ++k) \
;         acc[ai][bj][m][n] = __builtin_amdgcn_mfma_f32_16x16x32_bf16(Bt[n][k], At[m][k], acc[ai][bj][m][n], 0, 0, 0); __builtin_amdgcn_s_setprio(0); } while (0)
; #define PG8_WAIT_V(n) asm volatile("s_waitcnt vmcnt(" #n ")" ::: "memory")
; #define PG8_WAIT_L(n) asm volatile("s_waitcnt lgkmcnt(" #n ")" ::: "memory")
; #define PG8_BAR __builtin_amdgcn_s_barrier()
; #define PG8_SCHED __builtin_amdgcn_sched_barrier(0)
; template <class Epi>
; DI void gemm_phase(LAS unsigned char* lds, const Gemm g, const StaticOrder& S, const Epi& E) {
;     ...
;             PG8_STAGE(PG8_SB(0, 1), b2 + hstep);
;             PG8_WAIT_V(6); PG8_BAR; PG8_MMA(1, 1, At, B1); PG8_BAR;
;             PG8_LDB(B0, 1, 0); PG8_SCHED; PG8_LDA(At, 1, 0); PG8_STAGE(PG8_SA(0, 1), a2 + hstep);
;             PG8_WAIT_L(8); PG8_BAR; PG8_WAIT_L(0); PG8_MMA(0, 0, At, B0); PG8_BAR; PG8_SCHED;
;             PG8_LDB(B1, 1, 1); PG8_STAGE(PG8_SB(1, 0), b3);
;             PG8_BAR; PG8_WAIT_L(0); PG8_MMA(0, 1, At, B1); PG8_BAR;
;             PG8_LDA(At, 1, 1); PG8_STAGE(PG8_SA(1, 0), a3);
;             PG8_BAR; PG8_WAIT_L(0); PG8_MMA(1, 0, At, B0); PG8_BAR; PG8_SCHED;
	s_add_u32 s16, s20, 0x160000
	s_addc_u32 s17, s21, 0
	s_add_i32 s39, s40, s27
	v_lshl_add_u64 v[96:97], s[16:17], 0, v[142:143]
	s_mov_b32 m0, s39
	s_nop 0
	global_load_lds_dwordx4 v[96:97], off
	v_lshl_add_u64 v[96:97], s[16:17], 0, v[140:141]
	s_add_i32 m0, s39, 0x2000
	s_nop 0
	global_load_lds_dwordx4 v[96:97], off
	s_waitcnt vmcnt(6)
	s_setprio 1
	s_barrier
	v_mfma_f32_16x16x32_bf16 v[28:31], v[226:229], v[152:155], v[28:31]
	v_mfma_f32_16x16x32_bf16 v[24:27], v[234:237], v[152:155], v[24:27]
	v_mfma_f32_16x16x32_bf16 v[20:23], v[226:229], v[190:193], v[20:23]
	v_mfma_f32_16x16x32_bf16 v[16:19], v[234:237], v[190:193], v[16:19]
	v_mfma_f32_16x16x32_bf16 v[12:15], v[226:229], v[202:205], v[12:15]
	v_mfma_f32_16x16x32_bf16 v[8:11], v[234:237], v[202:205], v[8:11]
	v_mfma_f32_16x16x32_bf16 v[4:7], v[226:229], v[210:213], v[4:7]
	v_mfma_f32_16x16x32_bf16 v[0:3], v[234:237], v[210:213], v[0:3]
	v_mfma_f32_16x16x32_bf16 v[28:31], v[230:233], v[186:189], v[28:31]
	v_mfma_f32_16x16x32_bf16 v[24:27], v[238:241], v[186:189], v[24:27]
	v_mfma_f32_16x16x32_bf16 v[20:23], v[230:233], v[194:197], v[20:23]
	v_mfma_f32_16x16x32_bf16 v[16:19], v[238:241], v[194:197], v[16:19]
	v_mfma_f32_16x16x32_bf16 v[12:15], v[230:233], v[206:209], v[12:15]
	v_mfma_f32_16x16x32_bf16 v[8:11], v[238:241], v[206:209], v[8:11]
	v_mfma_f32_16x16x32_bf16 v[4:7], v[230:233], v[214:217], v[4:7]
	v_mfma_f32_16x16x32_bf16 v[0:3], v[238:241], v[214:217], v[0:3]
	s_setprio 0
	s_add_i32 s39, 0, 0x18000
	v_add_u32_e32 v148, s39, v199
	s_barrier
	ds_read_b128 v[96:99], v148
	ds_read_b128 v[100:103], v148 offset:1024
	ds_read_b128 v[136:139], v148 offset:2048
	ds_read_b128 v[148:151], v148 offset:3072
	s_add_u32 s16, s22, 0x160000
	s_addc_u32 s17, s23, 0
	s_mov_b32 m0, s30
	v_lshl_add_u64 v[226:227], s[16:17], 0, v[142:143]
	ds_read_b128 v[152:155], v201 offset:32768
	ds_read_b128 v[186:189], v201 offset:33792
	ds_read_b128 v[190:193], v201 offset:34816
	ds_read_b128 v[194:197], v201 offset:35840
	ds_read_b128 v[202:205], v201 offset:36864
	ds_read_b128 v[206:209], v201 offset:37888
	ds_read_b128 v[210:213], v201 offset:38912
	ds_read_b128 v[214:217], v201 offset:39936
	global_load_lds_dwordx4 v[226:227], off
	v_lshl_add_u64 v[226:227], s[16:17], 0, v[140:141]
	s_mov_b32 m0, s31
	s_nop 0
	global_load_lds_dwordx4 v[226:227], off
	s_waitcnt lgkmcnt(8)
	s_setprio 1
	s_barrier
	s_waitcnt lgkmcnt(0)
	v_mfma_f32_16x16x32_bf16 v[132:135], v[96:99], v[152:155], v[132:135]
	v_mfma_f32_16x16x32_bf16 v[128:131], v[136:139], v[152:155], v[128:131]
	v_mfma_f32_16x16x32_bf16 v[124:127], v[96:99], v[190:193], v[124:127]
	v_mfma_f32_16x16x32_bf16 v[120:123], v[136:139], v[190:193], v[120:123]
	v_mfma_f32_16x16x32_bf16 v[116:119], v[96:99], v[202:205], v[116:119]
	v_mfma_f32_16x16x32_bf16 v[112:115], v[136:139], v[202:205], v[112:115]
	v_mfma_f32_16x16x32_bf16 v[108:111], v[96:99], v[210:213], v[108:111]
	v_mfma_f32_16x16x32_bf16 v[104:107], v[136:139], v[210:213], v[104:107]
	v_mfma_f32_16x16x32_bf16 v[132:135], v[100:103], v[186:189], v[132:135]
	v_mfma_f32_16x16x32_bf16 v[128:131], v[148:151], v[186:189], v[128:131]
	v_mfma_f32_16x16x32_bf16 v[124:127], v[100:103], v[194:197], v[124:127]
	v_mfma_f32_16x16x32_bf16 v[120:123], v[148:151], v[194:197], v[120:123]
	v_mfma_f32_16x16x32_bf16 v[116:119], v[100:103], v[206:209], v[116:119]
	v_mfma_f32_16x16x32_bf16 v[112:115], v[148:151], v[206:209], v[112:115]
	v_mfma_f32_16x16x32_bf16 v[108:111], v[100:103], v[214:217], v[108:111]
	v_mfma_f32_16x16x32_bf16 v[104:107], v[148:151], v[214:217], v[104:107]
	s_setprio 0
	s_barrier
	s_add_i32 s22, 0, 0x1c000
	s_add_i32 s16, s39, s27
	v_add_u32_e32 v158, s22, v199
	v_lshl_add_u64 v[218:219], v[218:219], 0, s[94:95]
	s_mov_b32 m0, s16
	ds_read_b128 v[226:229], v158
	ds_read_b128 v[230:233], v158 offset:1024
	ds_read_b128 v[234:237], v158 offset:2048
	ds_read_b128 v[238:241], v158 offset:3072
	global_load_lds_dwordx4 v[218:219], off
	v_lshl_add_u64 v[218:219], v[220:221], 0, s[94:95]
	s_add_i32 m0, s16, 0x2000
	s_nop 0
	global_load_lds_dwordx4 v[218:219], off
	s_waitcnt lgkmcnt(0)
	s_setprio 1
	s_barrier
	v_mfma_f32_16x16x32_bf16 v[60:63], v[226:229], v[152:155], v[60:63]
	v_mfma_f32_16x16x32_bf16 v[56:59], v[234:237], v[152:155], v[56:59]
	v_mfma_f32_16x16x32_bf16 v[52:55], v[226:229], v[190:193], v[52:55]
	v_mfma_f32_16x16x32_bf16 v[48:51], v[234:237], v[190:193], v[48:51]
	v_mfma_f32_16x16x32_bf16 v[44:47], v[226:229], v[202:205], v[44:47]
	v_mfma_f32_16x16x32_bf16 v[40:43], v[234:237], v[202:205], v[40:43]
	v_mfma_f32_16x16x32_bf16 v[36:39], v[226:229], v[210:213], v[36:39]
	v_mfma_f32_16x16x32_bf16 v[32:35], v[234:237], v[210:213], v[32:35]
	v_mfma_f32_16x16x32_bf16 v[60:63], v[230:233], v[186:189], v[60:63]
	v_mfma_f32_16x16x32_bf16 v[56:59], v[238:241], v[186:189], v[56:59]
	v_mfma_f32_16x16x32_bf16 v[52:55], v[230:233], v[194:197], v[52:55]
	v_mfma_f32_16x16x32_bf16 v[48:51], v[238:241], v[194:197], v[48:51]
	v_mfma_f32_16x16x32_bf16 v[44:47], v[230:233], v[206:209], v[44:47]
	v_mfma_f32_16x16x32_bf16 v[40:43], v[238:241], v[206:209], v[40:43]
	v_mfma_f32_16x16x32_bf16 v[36:39], v[230:233], v[214:217], v[36:39]
	v_mfma_f32_16x16x32_bf16 v[32:35], v[238:241], v[214:217], v[32:35]
	s_setprio 0
	s_mov_b32 m0, s34
	v_lshl_add_u64 v[218:219], v[242:243], 0, s[94:95]
	s_barrier
	ds_read_b128 v[152:155], v201 offset:49152
	ds_read_b128 v[186:189], v201 offset:50176
	ds_read_b128 v[190:193], v201 offset:51200
	ds_read_b128 v[194:197], v201 offset:52224
	ds_read_b128 v[202:205], v201 offset:53248
	ds_read_b128 v[206:209], v201 offset:54272
	ds_read_b128 v[210:213], v201 offset:55296
	ds_read_b128 v[214:217], v201 offset:56320
	global_load_lds_dwordx4 v[218:219], off
	v_lshl_add_u64 v[218:219], v[244:245], 0, s[94:95]
	s_mov_b32 m0, s35
	s_nop 0
	global_load_lds_dwordx4 v[218:219], off
	s_waitcnt lgkmcnt(0)
	s_setprio 1
	s_barrier
; #define PG8_WAIT_V(n) asm volatile("s_waitcnt vmcnt(" #n ")" ::: "memory")
; #define PG8_WAIT_L(n) asm volatile("s_waitcnt lgkmcnt(" #n ")" ::: "memory")
; template <class Epi>
; DI void gemm_phase(LAS unsigned char* lds, const Gemm g, const StaticOrder& S, const Epi& E) {
;     ...
;             PG8_BAR; PG8_WAIT_L(0); PG8_MMA(1, 0, At, B0); PG8_BAR; PG8_SCHED;
;             PG8_STAGE(PG8_SB(1, 1), b3 + hstep);
;             PG8_WAIT_V(6); PG8_BAR; PG8_MMA(1, 1, At, B1); PG8_BAR;
;     template <bool LN, int BJ, int LO, int HI> DI void batch(const f32x4 (&acc)[2][2][4][2], unsigned row0, unsigned col0, const f32x4 (&gv)[2], const f32x4 (&bv)[2]) const {
;         f32x4 r[HI - LO]; float mean[(HI - LO) / 2], rstd[(HI - LO) / 2];
; #pragma unroll
;         for (int i = LO; i < HI; ++i) { const int ai = i >> 3, m = (i >> 1) & 3, n = i & 1; const unsigned row = row0 + ai * HALF + m * 16;
;             if (n == 0) { mean[(i - LO) >> 1] = 0.f; rstd[(i - LO) >> 1] = 1.f;
;                 if (LN) { const float2 st = *(const float2*)(stats + row * 2u); mean[(i - LO) >> 1] = st.x; rstd[(i - LO) >> 1] = st.y; } }
;             r[i - LO] = *(const f32x4*)(src + (row * (unsigned)DM + col0 + BJ * HALF + n * 16)); }
; #pragma unroll
;         for (int i = LO; i < HI; ++i) { const int ai = i >> 3, m = (i >> 1) & 3, n = i & 1; const unsigned row = row0 + ai * HALF + m * 16;
;             *(f32x4*)(Y + (row * (unsigned)DM + col0 + BJ * HALF + n * 16)) = acc[ai][BJ][m][n] + ((r[i - LO] - mean[(i - LO) >> 1]) * rstd[(i - LO) >> 1]) * gv[n] + bv[n]; }
;         __builtin_amdgcn_sched_barrier(0);
;     }
;     template <bool LN, int BJ> DI void load_gb(unsigned col0, f32x4 (&gv)[2], f32x4 (&bv)[2]) const {
; #pragma unroll
;         for (int n = 0; n < 2; ++n) {
;             if (LN) { gv[n] = *(const f32x4*)(gam + col0 + BJ * HALF + n * 16) * ALPHA; bv[n] = *(const f32x4*)(bet + col0 + BJ * HALF + n * 16) * ALPHA; }
;             else { gv[n] = (f32x4){ALPHA, ALPHA, ALPHA, ALPHA}; bv[n] = (f32x4){0.f, 0.f, 0.f, 0.f}; }
;         }
;     }
;     template <bool LN> DI void run(const f32x4 (&acc)[2][2][4][2], const Unit& u, int wr, int wc, int fr, int fq) const {
;         const unsigned row0 = u.pm * BM + wr * 64 + fr, col0 = u.pn * BM + wc * 32 + 4 * fq;
;         f32x4 gv[2], bv[2];
;         load_gb<LN, 0>(col0, gv, bv);
;         batch<LN, 0, 0, 4>(acc, row0, col0, gv, bv);
	v_mfma_f32_16x16x32_bf16 v[92:95], v[96:99], v[152:155], v[92:95]
	v_mfma_f32_16x16x32_bf16 v[88:91], v[136:139], v[152:155], v[88:91]
	v_mfma_f32_16x16x32_bf16 v[84:87], v[96:99], v[190:193], v[84:87]
	v_mfma_f32_16x16x32_bf16 v[80:83], v[136:139], v[190:193], v[80:83]
	v_mfma_f32_16x16x32_bf16 v[76:79], v[96:99], v[202:205], v[76:79]
	v_mfma_f32_16x16x32_bf16 v[72:75], v[136:139], v[202:205], v[72:75]
	v_mfma_f32_16x16x32_bf16 v[68:71], v[96:99], v[210:213], v[68:71]
	v_mfma_f32_16x16x32_bf16 v[64:67], v[136:139], v[210:213], v[64:67]
	v_mfma_f32_16x16x32_bf16 v[92:95], v[100:103], v[186:189], v[92:95]
	v_mfma_f32_16x16x32_bf16 v[88:91], v[148:151], v[186:189], v[88:91]
	v_mfma_f32_16x16x32_bf16 v[84:87], v[100:103], v[194:197], v[84:87]
	v_mfma_f32_16x16x32_bf16 v[80:83], v[148:151], v[194:197], v[80:83]
	v_mfma_f32_16x16x32_bf16 v[76:79], v[100:103], v[206:209], v[76:79]
	v_mfma_f32_16x16x32_bf16 v[72:75], v[148:151], v[206:209], v[72:75]
	v_mfma_f32_16x16x32_bf16 v[68:71], v[100:103], v[214:217], v[68:71]
	v_mfma_f32_16x16x32_bf16 v[64:67], v[148:151], v[214:217], v[64:67]
	s_setprio 0
	s_barrier
	s_add_u32 s16, s20, 0x160080
	s_addc_u32 s17, s21, 0
	s_add_i32 s20, s22, s27
	v_lshl_add_u64 v[96:97], s[16:17], 0, v[142:143]
	s_mov_b32 m0, s20
	s_nop 0
	global_load_lds_dwordx4 v[96:97], off
	v_lshl_add_u64 v[96:97], s[16:17], 0, v[140:141]
	s_add_i32 m0, s20, 0x2000
	s_nop 0
	global_load_lds_dwordx4 v[96:97], off
	s_waitcnt vmcnt(6)
	s_setprio 1
	s_barrier
	v_mfma_f32_16x16x32_bf16 v[28:31], v[226:229], v[152:155], v[28:31]
	v_mfma_f32_16x16x32_bf16 v[24:27], v[234:237], v[152:155], v[24:27]
	v_mfma_f32_16x16x32_bf16 v[20:23], v[226:229], v[190:193], v[20:23]
	v_mfma_f32_16x16x32_bf16 v[16:19], v[234:237], v[190:193], v[16:19]
	v_mfma_f32_16x16x32_bf16 v[12:15], v[226:229], v[202:205], v[12:15]
	v_mfma_f32_16x16x32_bf16 v[8:11], v[234:237], v[202:205], v[8:11]
	v_mfma_f32_16x16x32_bf16 v[4:7], v[226:229], v[210:213], v[4:7]
	v_mfma_f32_16x16x32_bf16 v[0:3], v[234:237], v[210:213], v[0:3]
	v_mfma_f32_16x16x32_bf16 v[28:31], v[230:233], v[186:189], v[28:31]
	v_mfma_f32_16x16x32_bf16 v[24:27], v[238:241], v[186:189], v[24:27]
	v_mfma_f32_16x16x32_bf16 v[20:23], v[230:233], v[194:197], v[20:23]
	v_mfma_f32_16x16x32_bf16 v[16:19], v[238:241], v[194:197], v[16:19]
	v_mfma_f32_16x16x32_bf16 v[12:15], v[230:233], v[206:209], v[12:15]
	v_mfma_f32_16x16x32_bf16 v[8:11], v[238:241], v[206:209], v[8:11]
	v_mfma_f32_16x16x32_bf16 v[4:7], v[230:233], v[214:217], v[4:7]
	v_mfma_f32_16x16x32_bf16 v[0:3], v[238:241], v[214:217], v[0:3]
	s_setprio 0
	s_add_i32 s33, s33, 2
	s_add_u32 s4, s4, 0x100
	s_addc_u32 s5, s5, 0
	s_cmpk_gt_u32 s33, 0x55
	s_mov_b64 s[16:17], s[18:19]
	s_barrier
	s_cbranch_scc0 .LBB0_134
	v_lshl_or_b32 v158, s2, 8, v200
	v_lshlrev_b64 v[100:101], 2, v[158:159]
	v_lshl_add_u64 v[150:151], s[12:13], 0, v[100:101]
	global_load_dwordx4 v[96:99], v[150:151], off
	v_lshl_add_u64 v[152:153], s[14:15], 0, v[100:101]
	v_lshl_add_u32 v203, s3, 8, v198
	v_lshlrev_b32_e32 v202, 11, v203
	v_add_u32_e32 v148, v202, v158
	v_mov_b32_e32 v149, v159
	v_lshlrev_b32_e32 v136, 1, v203
	v_mov_b32_e32 v137, v159
	v_lshlrev_b64 v[220:221], 2, v[148:149]
	v_lshl_add_u64 v[154:155], v[136:137], 2, s[96:97]
	v_lshl_add_u64 v[136:137], s[90:91], 0, v[220:221]
	v_or_b32_e32 v204, 16, v158
	v_or_b32_e32 v138, 16, v203
	v_lshlrev_b32_e32 v149, 11, v138
	s_waitcnt vmcnt(0)
	v_pk_mul_f32 v[192:193], v[98:99], s[78:79] op_sel_hi:[1,0]
	v_pk_mul_f32 v[194:195], v[96:97], s[78:79] op_sel_hi:[1,0]
	global_load_dwordx4 v[100:103], v[152:153], off
	global_load_dwordx4 v[96:99], v[150:151], off offset:64
	global_load_dwordx2 v[218:219], v[154:155], off
	global_load_dwordx4 v[206:209], v[136:137], off
	v_add_u32_e32 v136, v202, v204
	v_mov_b32_e32 v137, v159
	v_lshl_add_u64 v[136:137], v[136:137], 2, s[90:91]
	global_load_dwordx4 v[210:213], v[136:137], off
	v_lshlrev_b32_e32 v136, 1, v138
	v_mov_b32_e32 v137, v159
	v_lshl_add_u64 v[186:187], v[136:137], 2, s[96:97]
	v_add_u32_e32 v136, v149, v158
	v_lshl_add_u64 v[136:137], v[136:137], 2, s[90:91]
	global_load_dwordx2 v[196:197], v[186:187], off
	global_load_dwordx4 v[214:217], v[136:137], off
	v_add_u32_e32 v136, v149, v204
	v_mov_b32_e32 v137, v159
	v_lshl_add_u64 v[136:137], v[136:137], 2, s[90:91]
	global_load_dwordx4 v[136:139], v[136:137], off
	s_waitcnt vmcnt(0)
	v_pk_mul_f32 v[188:189], v[98:99], s[78:79] op_sel_hi:[1,0]
	v_pk_mul_f32 v[190:191], v[96:97], s[78:79] op_sel_hi:[1,0]
	global_load_dwordx4 v[96:99], v[152:153], off offset:64
	v_sub_f32_e32 v207, v207, v218
	v_sub_f32_e32 v206, v206, v218
	v_sub_f32_e32 v209, v209, v218
	v_sub_f32_e32 v208, v208, v218
	v_pk_mul_f32 v[208:209], v[218:219], v[208:209] op_sel:[1,0]
	v_pk_mul_f32 v[206:207], v[218:219], v[206:207] op_sel:[1,0]
	v_pk_fma_f32 v[134:135], v[192:193], v[208:209], v[134:135]
	v_pk_fma_f32 v[132:133], v[194:195], v[206:207], v[132:133]
	v_pk_fma_f32 v[134:135], v[102:103], s[78:79], v[134:135] op_sel_hi:[1,0,1]
	v_pk_fma_f32 v[132:133], v[100:101], s[78:79], v[132:133] op_sel_hi:[1,0,1]
	v_lshl_add_u64 v[206:207], s[88:89], 0, v[220:221]
	global_store_dwordx4 v[206:207], v[132:135], off
	s_nop 1
	v_sub_f32_e32 v133, v211, v218
	v_sub_f32_e32 v132, v210, v218
	v_sub_f32_e32 v135, v213, v218
	v_sub_f32_e32 v134, v212, v218
	v_pk_mul_f32 v[134:135], v[218:219], v[134:135] op_sel:[1,0]
	v_pk_mul_f32 v[132:133], v[218:219], v[132:133] op_sel:[1,0]
	v_pk_fma_f32 v[130:131], v[188:189], v[134:135], v[130:131]
	v_pk_fma_f32 v[128:129], v[190:191], v[132:133], v[128:129]
	v_or_b32_e32 v132, 16, v148
	v_mov_b32_e32 v133, v159
	v_lshl_add_u64 v[132:133], v[132:133], 2, s[88:89]
	s_waitcnt vmcnt(0)
;     template <bool LN, int BJ, int LO, int HI> DI void batch(const f32x4 (&acc)[2][2][4][2], unsigned row0, unsigned col0, const f32x4 (&gv)[2], const f32x4 (&bv)[2]) const {
;         f32x4 r[HI - LO]; float mean[(HI - LO) / 2], rstd[(HI - LO) / 2];
; #pragma unroll
;         for (int i = LO; i < HI; ++i) { const int ai = i >> 3, m = (i >> 1) & 3, n = i & 1; const unsigned row = row0 + ai * HALF + m * 16;
;             if (n == 0) { mean[(i - LO) >> 1] = 0.f; rstd[(i - LO) >> 1] = 1.f;
;                 if (LN) { const float2 st = *(const float2*)(stats + row * 2u); mean[(i - LO) >> 1] = st.x; rstd[(i - LO) >> 1] = st.y; } }
;             r[i - LO] = *(const f32x4*)(src + (row * (unsigned)DM + col0 + BJ * HALF + n * 16)); }
; #pragma unroll
;         for (int i = LO; i < HI; ++i) { const int ai = i >> 3, m = (i >> 1) & 3, n = i & 1; const unsigned row = row0 + ai * HALF + m * 16;
;             *(f32x4*)(Y + (row * (unsigned)DM + col0 + BJ * HALF + n * 16)) = acc[ai][BJ][m][n] + ((r[i - LO] - mean[(i - LO) >> 1]) * rstd[(i - LO) >> 1]) * gv[n] + bv[n]; }
	v_pk_fma_f32 v[130:131], v[98:99], s[78:79], v[130:131] op_sel_hi:[1,0,1]
	v_pk_fma_f32 v[128:129], v[96:97], s[78:79], v[128:129] op_sel_hi:[1,0,1]
	global_store_dwordx4 v[132:133], v[128:131], off
	s_nop 1
	v_sub_f32_e32 v129, v215, v196
	v_sub_f32_e32 v128, v214, v196
	v_sub_f32_e32 v131, v217, v196
	v_sub_f32_e32 v130, v216, v196
	v_pk_mul_f32 v[130:131], v[196:197], v[130:131] op_sel:[1,0]
	v_pk_mul_f32 v[128:129], v[196:197], v[128:129] op_sel:[1,0]
	v_pk_fma_f32 v[126:127], v[192:193], v[130:131], v[126:127]
	v_pk_fma_f32 v[124:125], v[194:195], v[128:129], v[124:125]
	v_add_u32_e32 v128, 0x8000, v148
	v_mov_b32_e32 v129, v159
	v_pk_fma_f32 v[126:127], v[102:103], s[78:79], v[126:127] op_sel_hi:[1,0,1]
	v_pk_fma_f32 v[124:125], v[100:101], s[78:79], v[124:125] op_sel_hi:[1,0,1]
	v_lshl_add_u64 v[128:129], v[128:129], 2, s[88:89]
	global_store_dwordx4 v[128:129], v[124:127], off
	s_nop 1
	v_sub_f32_e32 v125, v137, v196
	v_sub_f32_e32 v124, v136, v196
	v_sub_f32_e32 v127, v139, v196
	v_sub_f32_e32 v126, v138, v196
	v_pk_mul_f32 v[126:127], v[196:197], v[126:127] op_sel:[1,0]
	v_pk_mul_f32 v[124:125], v[196:197], v[124:125] op_sel:[1,0]
	v_pk_fma_f32 v[122:123], v[188:189], v[126:127], v[122:123]
	v_pk_fma_f32 v[120:121], v[190:191], v[124:125], v[120:121]
	v_add_u32_e32 v124, 0x8010, v148
	v_mov_b32_e32 v125, v159
	v_pk_fma_f32 v[122:123], v[98:99], s[78:79], v[122:123] op_sel_hi:[1,0,1]
	v_pk_fma_f32 v[120:121], v[96:97], s[78:79], v[120:121] op_sel_hi:[1,0,1]
	v_lshl_add_u64 v[124:125], v[124:125], 2, s[88:89]
	global_store_dwordx4 v[124:125], v[120:123], off
	s_nop 1
	v_or_b32_e32 v122, 32, v203
	v_lshlrev_b32_e32 v124, 11, v122
	v_lshlrev_b32_e32 v120, 1, v122
	v_mov_b32_e32 v121, v159
	v_add_u32_e32 v122, v124, v158
	v_mov_b32_e32 v123, v159
	v_lshl_add_u64 v[120:121], v[120:121], 2, s[96:97]
	v_lshl_add_u64 v[122:123], v[122:123], 2, s[90:91]
	global_load_dwordx2 v[138:139], v[120:121], off
	global_load_dwordx4 v[126:129], v[122:123], off
	v_add_u32_e32 v122, v124, v204
	v_mov_b32_e32 v123, v159
	v_lshl_add_u64 v[122:123], v[122:123], 2, s[90:91]
	global_load_dwordx4 v[130:133], v[122:123], off
	v_or_b32_e32 v125, 48, v203
	v_lshlrev_b32_e32 v122, 1, v125
	v_lshlrev_b32_e32 v125, 11, v125
	v_mov_b32_e32 v123, v159
	v_add_u32_e32 v134, v125, v158
	v_mov_b32_e32 v135, v159
	v_lshl_add_u64 v[122:123], v[122:123], 2, s[96:97]
	v_lshl_add_u64 v[134:135], v[134:135], 2, s[90:91]
	global_load_dwordx2 v[196:197], v[122:123], off
	v_add_u32_e32 v206, v125, v204
	global_load_dwordx4 v[134:137], v[134:135], off
	v_mov_b32_e32 v207, v159
	v_lshl_add_u64 v[206:207], v[206:207], 2, s[90:91]
	global_load_dwordx4 v[206:209], v[206:207], off
	s_waitcnt vmcnt(0)
	v_sub_f32_e32 v127, v127, v138
	v_sub_f32_e32 v126, v126, v138
	v_sub_f32_e32 v129, v129, v138
	v_sub_f32_e32 v128, v128, v138
	v_pk_mul_f32 v[128:129], v[138:139], v[128:129] op_sel:[1,0]
	v_pk_mul_f32 v[126:127], v[138:139], v[126:127] op_sel:[1,0]
	v_pk_fma_f32 v[118:119], v[192:193], v[128:129], v[118:119]
	v_pk_fma_f32 v[116:117], v[194:195], v[126:127], v[116:117]
	v_add_u32_e32 v126, 0x10000, v148
	v_mov_b32_e32 v127, v159
	v_pk_fma_f32 v[118:119], v[102:103], s[78:79], v[118:119] op_sel_hi:[1,0,1]
	v_pk_fma_f32 v[116:117], v[100:101], s[78:79], v[116:117] op_sel_hi:[1,0,1]
	v_lshl_add_u64 v[126:127], v[126:127], 2, s[88:89]
	global_store_dwordx4 v[126:127], v[116:119], off
	s_nop 1
	v_sub_f32_e32 v117, v131, v138
	v_sub_f32_e32 v116, v130, v138
	v_sub_f32_e32 v119, v133, v138
	v_sub_f32_e32 v118, v132, v138
	v_pk_mul_f32 v[118:119], v[138:139], v[118:119] op_sel:[1,0]
	v_pk_mul_f32 v[116:117], v[138:139], v[116:117] op_sel:[1,0]
	v_pk_fma_f32 v[114:115], v[188:189], v[118:119], v[114:115]
	v_pk_fma_f32 v[112:113], v[190:191], v[116:117], v[112:113]
	v_add_u32_e32 v116, 0x10010, v148
	v_mov_b32_e32 v117, v159
	v_pk_fma_f32 v[114:115], v[98:99], s[78:79], v[114:115] op_sel_hi:[1,0,1]
	v_pk_fma_f32 v[112:113], v[96:97], s[78:79], v[112:113] op_sel_hi:[1,0,1]
	v_lshl_add_u64 v[116:117], v[116:117], 2, s[88:89]
	global_store_dwordx4 v[116:117], v[112:115], off
	s_nop 1
	v_sub_f32_e32 v113, v135, v196
	v_sub_f32_e32 v112, v134, v196
	v_sub_f32_e32 v115, v137, v196
	v_sub_f32_e32 v114, v136, v196
	v_pk_mul_f32 v[114:115], v[196:197], v[114:115] op_sel:[1,0]
	v_pk_mul_f32 v[112:113], v[196:197], v[112:113] op_sel:[1,0]
	v_pk_fma_f32 v[110:111], v[192:193], v[114:115], v[110:111]
	v_pk_fma_f32 v[108:109], v[194:195], v[112:113], v[108:109]
	v_add_u32_e32 v112, 0x18000, v148
	v_mov_b32_e32 v113, v159
	v_pk_fma_f32 v[110:111], v[102:103], s[78:79], v[110:111] op_sel_hi:[1,0,1]
	v_pk_fma_f32 v[108:109], v[100:101], s[78:79], v[108:109] op_sel_hi:[1,0,1]
	v_lshl_add_u64 v[112:113], v[112:113], 2, s[88:89]
	global_store_dwordx4 v[112:113], v[108:111], off
	s_nop 1
	v_sub_f32_e32 v109, v207, v196
	v_sub_f32_e32 v108, v206, v196
	v_sub_f32_e32 v111, v209, v196
	v_sub_f32_e32 v110, v208, v196
	v_pk_mul_f32 v[110:111], v[196:197], v[110:111] op_sel:[1,0]
	v_pk_mul_f32 v[108:109], v[196:197], v[108:109] op_sel:[1,0]
	v_pk_fma_f32 v[106:107], v[188:189], v[110:111], v[106:107]
	v_pk_fma_f32 v[104:105], v[190:191], v[108:109], v[104:105]
	v_add_u32_e32 v108, 0x18010, v148
	v_mov_b32_e32 v109, v159
	v_pk_fma_f32 v[106:107], v[98:99], s[78:79], v[106:107] op_sel_hi:[1,0,1]
	v_pk_fma_f32 v[104:105], v[96:97], s[78:79], v[104:105] op_sel_hi:[1,0,1]
	v_lshl_add_u64 v[108:109], v[108:109], 2, s[88:89]
	global_store_dwordx4 v[108:109], v[104:107], off
	s_nop 1
	v_add_u32_e32 v106, 0x80, v203
	v_lshlrev_b32_e32 v114, 11, v106
	v_lshlrev_b32_e32 v104, 1, v106
	v_mov_b32_e32 v105, v159
	v_add_u32_e32 v106, v114, v158
	v_mov_b32_e32 v107, v159
	v_lshl_add_u64 v[104:105], v[104:105], 2, s[96:97]
	v_lshl_add_u64 v[106:107], v[106:107], 2, s[90:91]
	global_load_dwordx2 v[112:113], v[104:105], off
	global_load_dwordx4 v[108:111], v[106:107], off
	v_add_u32_e32 v106, v114, v204
	v_mov_b32_e32 v107, v159
	v_lshl_add_u64 v[106:107], v[106:107], 2, s[90:91]
	global_load_dwordx4 v[116:119], v[106:107], off
	v_add_u32_e32 v115, 0x90, v203
	v_lshlrev_b32_e32 v106, 1, v115
	v_lshlrev_b32_e32 v115, 11, v115
	v_mov_b32_e32 v107, v159
	v_add_u32_e32 v126, v115, v158
	v_mov_b32_e32 v127, v159
	v_lshl_add_u64 v[106:107], v[106:107], 2, s[96:97]
	v_lshl_add_u64 v[126:127], v[126:127], 2, s[90:91]
	global_load_dwordx2 v[134:135], v[106:107], off
	v_add_u32_e32 v130, v115, v204
	global_load_dwordx4 v[126:129], v[126:127], off
	v_mov_b32_e32 v131, v159
	v_lshl_add_u64 v[130:131], v[130:131], 2, s[90:91]
	global_load_dwordx4 v[130:133], v[130:131], off
	s_waitcnt vmcnt(0)
;     template <bool LN, int BJ, int LO, int HI> DI void batch(const f32x4 (&acc)[2][2][4][2], unsigned row0, unsigned col0, const f32x4 (&gv)[2], const f32x4 (&bv)[2]) const {
;         f32x4 r[HI - LO]; float mean[(HI - LO) / 2], rstd[(HI - LO) / 2];
; #pragma unroll
;         for (int i = LO; i < HI; ++i) { const int ai = i >> 3, m = (i >> 1) & 3, n = i & 1; const unsigned row = row0 + ai * HALF + m * 16;
;             if (n == 0) { mean[(i - LO) >> 1] = 0.f; rstd[(i - LO) >> 1] = 1.f;
;                 if (LN) { const float2 st = *(const float2*)(stats + row * 2u); mean[(i - LO) >> 1] = st.x; rstd[(i - LO) >> 1] = st.y; } }
;             r[i - LO] = *(const f32x4*)(src + (row * (unsigned)DM + col0 + BJ * HALF + n * 16)); }
; #pragma unroll
;         for (int i = LO; i < HI; ++i) { const int ai = i >> 3, m = (i >> 1) & 3, n = i & 1; const unsigned row = row0 + ai * HALF + m * 16;
;             *(f32x4*)(Y + (row * (unsigned)DM + col0 + BJ * HALF + n * 16)) = acc[ai][BJ][m][n] + ((r[i - LO] - mean[(i - LO) >> 1]) * rstd[(i - LO) >> 1]) * gv[n] + bv[n]; }
	v_sub_f32_e32 v109, v109, v112
	v_sub_f32_e32 v108, v108, v112
	v_sub_f32_e32 v111, v111, v112
	v_sub_f32_e32 v110, v110, v112
	v_pk_mul_f32 v[110:111], v[112:113], v[110:111] op_sel:[1,0]
	v_pk_mul_f32 v[108:109], v[112:113], v[108:109] op_sel:[1,0]
	v_pk_fma_f32 v[94:95], v[192:193], v[110:111], v[94:95]
	v_pk_fma_f32 v[92:93], v[194:195], v[108:109], v[92:93]
	v_add_u32_e32 v108, 0x40000, v148
	v_mov_b32_e32 v109, v159
	v_pk_fma_f32 v[94:95], v[102:103], s[78:79], v[94:95] op_sel_hi:[1,0,1]
	v_pk_fma_f32 v[92:93], v[100:101], s[78:79], v[92:93] op_sel_hi:[1,0,1]
	v_lshl_add_u64 v[108:109], v[108:109], 2, s[88:89]
	global_store_dwordx4 v[108:109], v[92:95], off
	s_nop 1
	v_sub_f32_e32 v93, v117, v112
	v_sub_f32_e32 v92, v116, v112
	v_sub_f32_e32 v95, v119, v112
	v_sub_f32_e32 v94, v118, v112
	v_pk_mul_f32 v[94:95], v[112:113], v[94:95] op_sel:[1,0]
	v_pk_mul_f32 v[92:93], v[112:113], v[92:93] op_sel:[1,0]
	v_pk_fma_f32 v[90:91], v[188:189], v[94:95], v[90:91]
	v_pk_fma_f32 v[88:89], v[190:191], v[92:93], v[88:89]
	v_add_u32_e32 v92, 0x40010, v148
	v_mov_b32_e32 v93, v159
	v_pk_fma_f32 v[90:91], v[98:99], s[78:79], v[90:91] op_sel_hi:[1,0,1]
	v_pk_fma_f32 v[88:89], v[96:97], s[78:79], v[88:89] op_sel_hi:[1,0,1]
	v_lshl_add_u64 v[92:93], v[92:93], 2, s[88:89]
	global_store_dwordx4 v[92:93], v[88:91], off
	s_nop 1
	v_sub_f32_e32 v89, v127, v134
	v_sub_f32_e32 v88, v126, v134
	v_sub_f32_e32 v91, v129, v134
	v_sub_f32_e32 v90, v128, v134
	v_pk_mul_f32 v[90:91], v[134:135], v[90:91] op_sel:[1,0]
	v_pk_mul_f32 v[88:89], v[134:135], v[88:89] op_sel:[1,0]
	v_pk_fma_f32 v[86:87], v[192:193], v[90:91], v[86:87]
	v_pk_fma_f32 v[84:85], v[194:195], v[88:89], v[84:85]
	v_add_u32_e32 v88, 0x48000, v148
	v_mov_b32_e32 v89, v159
	v_pk_fma_f32 v[86:87], v[102:103], s[78:79], v[86:87] op_sel_hi:[1,0,1]
	v_pk_fma_f32 v[84:85], v[100:101], s[78:79], v[84:85] op_sel_hi:[1,0,1]
	v_lshl_add_u64 v[88:89], v[88:89], 2, s[88:89]
	global_store_dwordx4 v[88:89], v[84:87], off
	s_nop 1
	v_sub_f32_e32 v85, v131, v134
	v_sub_f32_e32 v84, v130, v134
	v_sub_f32_e32 v87, v133, v134
	v_sub_f32_e32 v86, v132, v134
	v_pk_mul_f32 v[86:87], v[134:135], v[86:87] op_sel:[1,0]
	v_pk_mul_f32 v[84:85], v[134:135], v[84:85] op_sel:[1,0]
	v_pk_fma_f32 v[82:83], v[188:189], v[86:87], v[82:83]
	v_pk_fma_f32 v[80:81], v[190:191], v[84:85], v[80:81]
	v_add_u32_e32 v84, 0x48010, v148
	v_mov_b32_e32 v85, v159
	v_pk_fma_f32 v[82:83], v[98:99], s[78:79], v[82:83] op_sel_hi:[1,0,1]
	v_pk_fma_f32 v[80:81], v[96:97], s[78:79], v[80:81] op_sel_hi:[1,0,1]
	v_lshl_add_u64 v[84:85], v[84:85], 2, s[88:89]
	global_store_dwordx4 v[84:85], v[80:83], off
	s_nop 1
	v_add_u32_e32 v82, 0xa0, v203
	v_lshlrev_b32_e32 v80, 1, v82
	v_mov_b32_e32 v81, v159
	v_lshlrev_b32_e32 v116, 11, v82
	v_lshl_add_u64 v[108:109], v[80:81], 2, s[96:97]
	v_add_u32_e32 v80, v116, v158
	v_lshl_add_u64 v[80:81], v[80:81], 2, s[90:91]
	global_load_dwordx2 v[112:113], v[108:109], off
	v_add_u32_e32 v84, v116, v204
	global_load_dwordx4 v[80:83], v[80:81], off
	v_mov_b32_e32 v85, v159
	v_lshl_add_u64 v[84:85], v[84:85], 2, s[90:91]
	global_load_dwordx4 v[84:87], v[84:85], off
	v_add_u32_e32 v90, 0xb0, v203
	v_lshlrev_b32_e32 v88, 1, v90
	v_mov_b32_e32 v89, v159
	v_lshlrev_b32_e32 v117, 11, v90
	v_lshl_add_u64 v[110:111], v[88:89], 2, s[96:97]
	v_add_u32_e32 v88, v117, v158
	v_lshl_add_u64 v[88:89], v[88:89], 2, s[90:91]
	global_load_dwordx2 v[118:119], v[110:111], off
	v_add_u32_e32 v92, v117, v204
	global_load_dwordx4 v[88:91], v[88:89], off
	v_mov_b32_e32 v93, v159
	v_lshl_add_u64 v[92:93], v[92:93], 2, s[90:91]
	global_load_dwordx4 v[92:95], v[92:93], off
	s_waitcnt vmcnt(0)
	v_sub_f32_e32 v81, v81, v112
	v_sub_f32_e32 v80, v80, v112
	v_sub_f32_e32 v83, v83, v112
	v_sub_f32_e32 v82, v82, v112
	v_pk_mul_f32 v[82:83], v[112:113], v[82:83] op_sel:[1,0]
	v_pk_mul_f32 v[80:81], v[112:113], v[80:81] op_sel:[1,0]
	v_pk_fma_f32 v[78:79], v[192:193], v[82:83], v[78:79]
	v_pk_fma_f32 v[76:77], v[194:195], v[80:81], v[76:77]
	v_add_u32_e32 v80, 0x50000, v148
	v_mov_b32_e32 v81, v159
	v_pk_fma_f32 v[78:79], v[102:103], s[78:79], v[78:79] op_sel_hi:[1,0,1]
	v_pk_fma_f32 v[76:77], v[100:101], s[78:79], v[76:77] op_sel_hi:[1,0,1]
	v_lshl_add_u64 v[80:81], v[80:81], 2, s[88:89]
	global_store_dwordx4 v[80:81], v[76:79], off
	s_nop 1
	v_sub_f32_e32 v77, v85, v112
	v_sub_f32_e32 v76, v84, v112
	v_sub_f32_e32 v79, v87, v112
	v_sub_f32_e32 v78, v86, v112
	v_pk_mul_f32 v[78:79], v[112:113], v[78:79] op_sel:[1,0]
	v_pk_mul_f32 v[76:77], v[112:113], v[76:77] op_sel:[1,0]
	v_pk_fma_f32 v[74:75], v[188:189], v[78:79], v[74:75]
	v_pk_fma_f32 v[72:73], v[190:191], v[76:77], v[72:73]
	v_add_u32_e32 v76, 0x50010, v148
	v_mov_b32_e32 v77, v159
	v_pk_fma_f32 v[74:75], v[98:99], s[78:79], v[74:75] op_sel_hi:[1,0,1]
	v_pk_fma_f32 v[72:73], v[96:97], s[78:79], v[72:73] op_sel_hi:[1,0,1]
	v_lshl_add_u64 v[76:77], v[76:77], 2, s[88:89]
	global_store_dwordx4 v[76:77], v[72:75], off
	s_nop 1
	v_sub_f32_e32 v73, v89, v118
	v_sub_f32_e32 v72, v88, v118
	v_sub_f32_e32 v75, v91, v118
	v_sub_f32_e32 v74, v90, v118
	v_pk_mul_f32 v[74:75], v[118:119], v[74:75] op_sel:[1,0]
	v_pk_mul_f32 v[72:73], v[118:119], v[72:73] op_sel:[1,0]
	v_pk_fma_f32 v[70:71], v[192:193], v[74:75], v[70:71]
	v_pk_fma_f32 v[68:69], v[194:195], v[72:73], v[68:69]
	v_add_u32_e32 v72, 0x58000, v148
	v_mov_b32_e32 v73, v159
	v_pk_fma_f32 v[70:71], v[102:103], s[78:79], v[70:71] op_sel_hi:[1,0,1]
	v_pk_fma_f32 v[68:69], v[100:101], s[78:79], v[68:69] op_sel_hi:[1,0,1]
	v_lshl_add_u64 v[72:73], v[72:73], 2, s[88:89]
	global_store_dwordx4 v[72:73], v[68:71], off
	s_nop 1
	v_sub_f32_e32 v69, v93, v118
	v_sub_f32_e32 v68, v92, v118
	v_sub_f32_e32 v71, v95, v118
	v_sub_f32_e32 v70, v94, v118
	v_pk_mul_f32 v[70:71], v[118:119], v[70:71] op_sel:[1,0]
	v_pk_mul_f32 v[68:69], v[118:119], v[68:69] op_sel:[1,0]
	v_pk_fma_f32 v[66:67], v[188:189], v[70:71], v[66:67]
	v_pk_fma_f32 v[64:65], v[190:191], v[68:69], v[64:65]
	v_add_u32_e32 v68, 0x58010, v148
	v_mov_b32_e32 v69, v159
	v_pk_fma_f32 v[66:67], v[98:99], s[78:79], v[66:67] op_sel_hi:[1,0,1]
	v_pk_fma_f32 v[64:65], v[96:97], s[78:79], v[64:65] op_sel_hi:[1,0,1]
	v_lshl_add_u64 v[68:69], v[68:69], 2, s[88:89]
	global_store_dwordx4 v[68:69], v[64:67], off
	global_load_dwordx4 v[64:67], v[150:151], off offset:512
	v_or_b32_e32 v119, 0x80, v158
	v_add_u32_e32 v72, v202, v119
	v_mov_b32_e32 v73, v159
	v_lshl_add_u64 v[72:73], v[72:73], 2, s[90:91]
	v_or_b32_e32 v118, 0x90, v158
	v_add_u32_e32 v158, v202, v118
	s_waitcnt vmcnt(0)
;     template <bool LN, int BJ, int LO, int HI> DI void batch(const f32x4 (&acc)[2][2][4][2], unsigned row0, unsigned col0, const f32x4 (&gv)[2], const f32x4 (&bv)[2]) const {
;         f32x4 r[HI - LO]; float mean[(HI - LO) / 2], rstd[(HI - LO) / 2];
; #pragma unroll
;         for (int i = LO; i < HI; ++i) { const int ai = i >> 3, m = (i >> 1) & 3, n = i & 1; const unsigned row = row0 + ai * HALF + m * 16;
;             if (n == 0) { mean[(i - LO) >> 1] = 0.f; rstd[(i - LO) >> 1] = 1.f;
;                 if (LN) { const float2 st = *(const float2*)(stats + row * 2u); mean[(i - LO) >> 1] = st.x; rstd[(i - LO) >> 1] = st.y; } }
;             r[i - LO] = *(const f32x4*)(src + (row * (unsigned)DM + col0 + BJ * HALF + n * 16)); }
; #pragma unroll
;         for (int i = LO; i < HI; ++i) { const int ai = i >> 3, m = (i >> 1) & 3, n = i & 1; const unsigned row = row0 + ai * HALF + m * 16;
;             *(f32x4*)(Y + (row * (unsigned)DM + col0 + BJ * HALF + n * 16)) = acc[ai][BJ][m][n] + ((r[i - LO] - mean[(i - LO) >> 1]) * rstd[(i - LO) >> 1]) * gv[n] + bv[n]; }
;         __builtin_amdgcn_sched_barrier(0);
;     }
;     template <bool LN, int BJ> DI void load_gb(unsigned col0, f32x4 (&gv)[2], f32x4 (&bv)[2]) const {
; #pragma unroll
;         for (int n = 0; n < 2; ++n) {
;             if (LN) { gv[n] = *(const f32x4*)(gam + col0 + BJ * HALF + n * 16) * ALPHA; bv[n] = *(const f32x4*)(bet + col0 + BJ * HALF + n * 16) * ALPHA; }
;             else { gv[n] = (f32x4){ALPHA, ALPHA, ALPHA, ALPHA}; bv[n] = (f32x4){0.f, 0.f, 0.f, 0.f}; }
;         }
;     }
	v_pk_mul_f32 v[96:97], v[66:67], s[78:79] op_sel_hi:[1,0]
	v_pk_mul_f32 v[98:99], v[64:65], s[78:79] op_sel_hi:[1,0]
	global_load_dwordx4 v[68:71], v[152:153], off offset:512
	global_load_dwordx4 v[64:67], v[150:151], off offset:576
	global_load_dwordx2 v[138:139], v[154:155], off
	global_load_dwordx4 v[126:129], v[72:73], off
	v_lshl_add_u64 v[72:73], v[158:159], 2, s[90:91]
	v_add_u32_e32 v158, v149, v119
	s_waitcnt vmcnt(0)
	v_pk_mul_f32 v[92:93], v[66:67], s[78:79] op_sel_hi:[1,0]
	v_pk_mul_f32 v[94:95], v[64:65], s[78:79] op_sel_hi:[1,0]
	global_load_dwordx4 v[64:67], v[152:153], off offset:576
	global_load_dwordx4 v[130:133], v[72:73], off
	global_load_dwordx2 v[112:113], v[186:187], off
	v_lshl_add_u64 v[72:73], v[158:159], 2, s[90:91]
	global_load_dwordx4 v[134:137], v[72:73], off
	v_add_u32_e32 v158, v149, v118
	v_lshl_add_u64 v[72:73], v[158:159], 2, s[90:91]
	global_load_dwordx4 v[88:91], v[72:73], off
	global_load_dwordx2 v[102:103], v[120:121], off
	v_add_u32_e32 v158, v124, v119
	v_lshl_add_u64 v[72:73], v[158:159], 2, s[90:91]
	global_load_dwordx4 v[84:87], v[72:73], off
	v_add_u32_e32 v158, v124, v118
	v_lshl_add_u64 v[72:73], v[158:159], 2, s[90:91]
	global_load_dwordx4 v[80:83], v[72:73], off
	global_load_dwordx2 v[100:101], v[122:123], off
	v_add_u32_e32 v158, v125, v119
	v_lshl_add_u64 v[72:73], v[158:159], 2, s[90:91]
	global_load_dwordx4 v[76:79], v[72:73], off
	v_add_u32_e32 v158, v125, v118
	v_lshl_add_u64 v[72:73], v[158:159], 2, s[90:91]
	global_load_dwordx4 v[72:75], v[72:73], off
	v_sub_f32_e32 v121, v127, v138
	v_sub_f32_e32 v120, v126, v138
	v_sub_f32_e32 v123, v129, v138
	v_sub_f32_e32 v122, v128, v138
	v_pk_mul_f32 v[122:123], v[138:139], v[122:123] op_sel:[1,0]
	v_pk_mul_f32 v[120:121], v[138:139], v[120:121] op_sel:[1,0]
	v_or_b32_e32 v158, 0x80, v148
	v_pk_fma_f32 v[60:61], v[98:99], v[120:121], v[60:61]
	v_pk_fma_f32 v[62:63], v[96:97], v[122:123], v[62:63]
	v_pk_fma_f32 v[60:61], v[68:69], s[78:79], v[60:61] op_sel_hi:[1,0,1]
	v_pk_fma_f32 v[62:63], v[70:71], s[78:79], v[62:63] op_sel_hi:[1,0,1]
	v_lshl_add_u64 v[120:121], v[158:159], 2, s[88:89]
	global_store_dwordx4 v[120:121], v[60:63], off
	v_or_b32_e32 v158, 0x90, v148
	s_waitcnt vmcnt(0)
	v_sub_f32_e32 v61, v131, v138
	v_sub_f32_e32 v60, v130, v138
	v_sub_f32_e32 v63, v133, v138
	v_sub_f32_e32 v62, v132, v138
	v_pk_mul_f32 v[62:63], v[138:139], v[62:63] op_sel:[1,0]
	v_pk_mul_f32 v[60:61], v[138:139], v[60:61] op_sel:[1,0]
	v_pk_fma_f32 v[58:59], v[92:93], v[62:63], v[58:59]
	v_pk_fma_f32 v[56:57], v[94:95], v[60:61], v[56:57]
	v_pk_fma_f32 v[58:59], v[66:67], s[78:79], v[58:59] op_sel_hi:[1,0,1]
	v_pk_fma_f32 v[56:57], v[64:65], s[78:79], v[56:57] op_sel_hi:[1,0,1]
	v_lshl_add_u64 v[60:61], v[158:159], 2, s[88:89]
	global_store_dwordx4 v[60:61], v[56:59], off
	v_add_u32_e32 v158, 0x8080, v148
	s_nop 0
	v_sub_f32_e32 v57, v135, v112
	v_sub_f32_e32 v56, v134, v112
	v_sub_f32_e32 v59, v137, v112
	v_sub_f32_e32 v58, v136, v112
	v_pk_mul_f32 v[58:59], v[112:113], v[58:59] op_sel:[1,0]
	v_pk_mul_f32 v[56:57], v[112:113], v[56:57] op_sel:[1,0]
	v_pk_fma_f32 v[54:55], v[96:97], v[58:59], v[54:55]
	v_pk_fma_f32 v[52:53], v[98:99], v[56:57], v[52:53]
	v_pk_fma_f32 v[54:55], v[70:71], s[78:79], v[54:55] op_sel_hi:[1,0,1]
	v_pk_fma_f32 v[52:53], v[68:69], s[78:79], v[52:53] op_sel_hi:[1,0,1]
	v_lshl_add_u64 v[56:57], v[158:159], 2, s[88:89]
	global_store_dwordx4 v[56:57], v[52:55], off
	v_add_u32_e32 v158, 0x8090, v148
	s_nop 0
	v_sub_f32_e32 v53, v89, v112
	v_sub_f32_e32 v52, v88, v112
	v_sub_f32_e32 v55, v91, v112
	v_sub_f32_e32 v54, v90, v112
	v_pk_mul_f32 v[54:55], v[112:113], v[54:55] op_sel:[1,0]
	v_pk_mul_f32 v[52:53], v[112:113], v[52:53] op_sel:[1,0]
	v_pk_fma_f32 v[50:51], v[92:93], v[54:55], v[50:51]
	v_pk_fma_f32 v[48:49], v[94:95], v[52:53], v[48:49]
	v_pk_fma_f32 v[50:51], v[66:67], s[78:79], v[50:51] op_sel_hi:[1,0,1]
	v_pk_fma_f32 v[48:49], v[64:65], s[78:79], v[48:49] op_sel_hi:[1,0,1]
	v_lshl_add_u64 v[52:53], v[158:159], 2, s[88:89]
	global_store_dwordx4 v[52:53], v[48:51], off
	v_add_u32_e32 v158, 0x10080, v148
	s_nop 0
	v_sub_f32_e32 v49, v85, v102
	v_sub_f32_e32 v48, v84, v102
	v_sub_f32_e32 v51, v87, v102
	v_sub_f32_e32 v50, v86, v102
	v_pk_mul_f32 v[50:51], v[102:103], v[50:51] op_sel:[1,0]
	v_pk_mul_f32 v[48:49], v[102:103], v[48:49] op_sel:[1,0]
	v_pk_fma_f32 v[46:47], v[96:97], v[50:51], v[46:47]
	v_pk_fma_f32 v[44:45], v[98:99], v[48:49], v[44:45]
	v_pk_fma_f32 v[46:47], v[70:71], s[78:79], v[46:47] op_sel_hi:[1,0,1]
	v_pk_fma_f32 v[44:45], v[68:69], s[78:79], v[44:45] op_sel_hi:[1,0,1]
	v_lshl_add_u64 v[48:49], v[158:159], 2, s[88:89]
	global_store_dwordx4 v[48:49], v[44:47], off
	v_add_u32_e32 v158, 0x10090, v148
	s_nop 0
	v_sub_f32_e32 v45, v81, v102
	v_sub_f32_e32 v44, v80, v102
	v_sub_f32_e32 v47, v83, v102
	v_sub_f32_e32 v46, v82, v102
	v_pk_mul_f32 v[46:47], v[102:103], v[46:47] op_sel:[1,0]
	v_pk_mul_f32 v[44:45], v[102:103], v[44:45] op_sel:[1,0]
	v_pk_fma_f32 v[42:43], v[92:93], v[46:47], v[42:43]
	v_pk_fma_f32 v[40:41], v[94:95], v[44:45], v[40:41]
	v_pk_fma_f32 v[42:43], v[66:67], s[78:79], v[42:43] op_sel_hi:[1,0,1]
	v_pk_fma_f32 v[40:41], v[64:65], s[78:79], v[40:41] op_sel_hi:[1,0,1]
	v_lshl_add_u64 v[44:45], v[158:159], 2, s[88:89]
	global_store_dwordx4 v[44:45], v[40:43], off
	v_add_u32_e32 v158, 0x18080, v148
	s_nop 0
	v_sub_f32_e32 v41, v77, v100
	v_sub_f32_e32 v40, v76, v100
	v_sub_f32_e32 v43, v79, v100
	v_sub_f32_e32 v42, v78, v100
	v_pk_mul_f32 v[42:43], v[100:101], v[42:43] op_sel:[1,0]
	v_pk_mul_f32 v[40:41], v[100:101], v[40:41] op_sel:[1,0]
	v_pk_fma_f32 v[38:39], v[96:97], v[42:43], v[38:39]
;     template <bool LN, int BJ, int LO, int HI> DI void batch(const f32x4 (&acc)[2][2][4][2], unsigned row0, unsigned col0, const f32x4 (&gv)[2], const f32x4 (&bv)[2]) const {
;         f32x4 r[HI - LO]; float mean[(HI - LO) / 2], rstd[(HI - LO) / 2];
; #pragma unroll
;         for (int i = LO; i < HI; ++i) { const int ai = i >> 3, m = (i >> 1) & 3, n = i & 1; const unsigned row = row0 + ai * HALF + m * 16;
;             if (n == 0) { mean[(i - LO) >> 1] = 0.f; rstd[(i - LO) >> 1] = 1.f;
;                 if (LN) { const float2 st = *(const float2*)(stats + row * 2u); mean[(i - LO) >> 1] = st.x; rstd[(i - LO) >> 1] = st.y; } }
;             r[i - LO] = *(const f32x4*)(src + (row * (unsigned)DM + col0 + BJ * HALF + n * 16)); }
; #pragma unroll
;         for (int i = LO; i < HI; ++i) { const int ai = i >> 3, m = (i >> 1) & 3, n = i & 1; const unsigned row = row0 + ai * HALF + m * 16;
;             *(f32x4*)(Y + (row * (unsigned)DM + col0 + BJ * HALF + n * 16)) = acc[ai][BJ][m][n] + ((r[i - LO] - mean[(i - LO) >> 1]) * rstd[(i - LO) >> 1]) * gv[n] + bv[n]; }
	v_pk_fma_f32 v[36:37], v[98:99], v[40:41], v[36:37]
	v_pk_fma_f32 v[38:39], v[70:71], s[78:79], v[38:39] op_sel_hi:[1,0,1]
	v_pk_fma_f32 v[36:37], v[68:69], s[78:79], v[36:37] op_sel_hi:[1,0,1]
	v_lshl_add_u64 v[40:41], v[158:159], 2, s[88:89]
	global_store_dwordx4 v[40:41], v[36:39], off
	v_add_u32_e32 v158, 0x18090, v148
	s_nop 0
	v_sub_f32_e32 v37, v73, v100
	v_sub_f32_e32 v36, v72, v100
	v_sub_f32_e32 v39, v75, v100
	v_sub_f32_e32 v38, v74, v100
	v_pk_mul_f32 v[38:39], v[100:101], v[38:39] op_sel:[1,0]
	v_pk_mul_f32 v[36:37], v[100:101], v[36:37] op_sel:[1,0]
	v_pk_fma_f32 v[34:35], v[92:93], v[38:39], v[34:35]
	v_pk_fma_f32 v[32:33], v[94:95], v[36:37], v[32:33]
	v_pk_fma_f32 v[34:35], v[66:67], s[78:79], v[34:35] op_sel_hi:[1,0,1]
	v_pk_fma_f32 v[32:33], v[64:65], s[78:79], v[32:33] op_sel_hi:[1,0,1]
	v_lshl_add_u64 v[36:37], v[158:159], 2, s[88:89]
	global_store_dwordx4 v[36:37], v[32:35], off
	v_add_u32_e32 v158, v114, v119
	s_nop 0
	v_lshl_add_u64 v[32:33], v[158:159], 2, s[90:91]
	global_load_dwordx2 v[62:63], v[104:105], off
	global_load_dwordx4 v[54:57], v[32:33], off
	v_add_u32_e32 v158, v114, v118
	v_lshl_add_u64 v[32:33], v[158:159], 2, s[90:91]
	global_load_dwordx4 v[58:61], v[32:33], off
	global_load_dwordx2 v[52:53], v[106:107], off
	v_add_u32_e32 v158, v115, v119
	v_lshl_add_u64 v[32:33], v[158:159], 2, s[90:91]
	global_load_dwordx4 v[72:75], v[32:33], off
	v_add_u32_e32 v158, v115, v118
	v_lshl_add_u64 v[32:33], v[158:159], 2, s[90:91]
	global_load_dwordx4 v[76:79], v[32:33], off
	global_load_dwordx2 v[50:51], v[108:109], off
	v_add_u32_e32 v158, v116, v119
	v_lshl_add_u64 v[32:33], v[158:159], 2, s[90:91]
	global_load_dwordx4 v[44:47], v[32:33], off
	v_add_u32_e32 v158, v116, v118
	v_lshl_add_u64 v[32:33], v[158:159], 2, s[90:91]
	global_load_dwordx4 v[40:43], v[32:33], off
	global_load_dwordx2 v[48:49], v[110:111], off
	v_add_u32_e32 v158, v117, v119
	v_lshl_add_u64 v[32:33], v[158:159], 2, s[90:91]
	global_load_dwordx4 v[36:39], v[32:33], off
	v_add_u32_e32 v158, v117, v118
	v_lshl_add_u64 v[32:33], v[158:159], 2, s[90:91]
	global_load_dwordx4 v[32:35], v[32:33], off
	v_add_u32_e32 v158, 0x40080, v148
	s_waitcnt vmcnt(0)
; #define PG8_WAIT_V(n) asm volatile("s_waitcnt vmcnt(" #n ")" ::: "memory")
; #define PG8_BAR __builtin_amdgcn_s_barrier()
; template <class Epi>
; DI void gemm_phase(LAS unsigned char* lds, const Gemm g, const StaticOrder& S, const Epi& E) {
;     ...
;     PG8_WAIT_V(0);
;     if (wr == 0) PG8_BAR;
;     template <bool LN, int BJ, int LO, int HI> DI void batch(const f32x4 (&acc)[2][2][4][2], unsigned row0, unsigned col0, const f32x4 (&gv)[2], const f32x4 (&bv)[2]) const {
;         f32x4 r[HI - LO]; float mean[(HI - LO) / 2], rstd[(HI - LO) / 2];
; #pragma unroll
;         for (int i = LO; i < HI; ++i) { const int ai = i >> 3, m = (i >> 1) & 3, n = i & 1; const unsigned row = row0 + ai * HALF + m * 16;
;             if (n == 0) { mean[(i - LO) >> 1] = 0.f; rstd[(i - LO) >> 1] = 1.f;
;                 if (LN) { const float2 st = *(const float2*)(stats + row * 2u); mean[(i - LO) >> 1] = st.x; rstd[(i - LO) >> 1] = st.y; } }
;             r[i - LO] = *(const f32x4*)(src + (row * (unsigned)DM + col0 + BJ * HALF + n * 16)); }
; #pragma unroll
;         for (int i = LO; i < HI; ++i) { const int ai = i >> 3, m = (i >> 1) & 3, n = i & 1; const unsigned row = row0 + ai * HALF + m * 16;
;             *(f32x4*)(Y + (row * (unsigned)DM + col0 + BJ * HALF + n * 16)) = acc[ai][BJ][m][n] + ((r[i - LO] - mean[(i - LO) >> 1]) * rstd[(i - LO) >> 1]) * gv[n] + bv[n]; }
	v_sub_f32_e32 v55, v55, v62
	v_sub_f32_e32 v54, v54, v62
	v_sub_f32_e32 v57, v57, v62
	v_sub_f32_e32 v56, v56, v62
	v_pk_mul_f32 v[56:57], v[62:63], v[56:57] op_sel:[1,0]
	v_pk_mul_f32 v[54:55], v[62:63], v[54:55] op_sel:[1,0]
	v_pk_fma_f32 v[30:31], v[96:97], v[56:57], v[30:31]
	v_pk_fma_f32 v[28:29], v[98:99], v[54:55], v[28:29]
	v_pk_fma_f32 v[30:31], v[70:71], s[78:79], v[30:31] op_sel_hi:[1,0,1]
	v_pk_fma_f32 v[28:29], v[68:69], s[78:79], v[28:29] op_sel_hi:[1,0,1]
	v_lshl_add_u64 v[54:55], v[158:159], 2, s[88:89]
	global_store_dwordx4 v[54:55], v[28:31], off
	v_add_u32_e32 v158, 0x40090, v148
	s_nop 0
	v_sub_f32_e32 v29, v59, v62
	v_sub_f32_e32 v28, v58, v62
	v_sub_f32_e32 v31, v61, v62
	v_sub_f32_e32 v30, v60, v62
	v_pk_mul_f32 v[30:31], v[62:63], v[30:31] op_sel:[1,0]
	v_pk_mul_f32 v[28:29], v[62:63], v[28:29] op_sel:[1,0]
	v_pk_fma_f32 v[26:27], v[92:93], v[30:31], v[26:27]
	v_pk_fma_f32 v[24:25], v[94:95], v[28:29], v[24:25]
	v_pk_fma_f32 v[26:27], v[66:67], s[78:79], v[26:27] op_sel_hi:[1,0,1]
	v_pk_fma_f32 v[24:25], v[64:65], s[78:79], v[24:25] op_sel_hi:[1,0,1]
	v_lshl_add_u64 v[28:29], v[158:159], 2, s[88:89]
	global_store_dwordx4 v[28:29], v[24:27], off
	v_add_u32_e32 v158, 0x48080, v148
	s_nop 0
	v_sub_f32_e32 v25, v73, v52
	v_sub_f32_e32 v24, v72, v52
	v_sub_f32_e32 v27, v75, v52
	v_sub_f32_e32 v26, v74, v52
	v_pk_mul_f32 v[26:27], v[52:53], v[26:27] op_sel:[1,0]
	v_pk_mul_f32 v[24:25], v[52:53], v[24:25] op_sel:[1,0]
	v_pk_fma_f32 v[22:23], v[96:97], v[26:27], v[22:23]
	v_pk_fma_f32 v[20:21], v[98:99], v[24:25], v[20:21]
	v_pk_fma_f32 v[22:23], v[70:71], s[78:79], v[22:23] op_sel_hi:[1,0,1]
	v_pk_fma_f32 v[20:21], v[68:69], s[78:79], v[20:21] op_sel_hi:[1,0,1]
	v_lshl_add_u64 v[24:25], v[158:159], 2, s[88:89]
	global_store_dwordx4 v[24:25], v[20:23], off
	v_add_u32_e32 v158, 0x48090, v148
	s_nop 0
	v_sub_f32_e32 v21, v77, v52
	v_sub_f32_e32 v20, v76, v52
	v_sub_f32_e32 v23, v79, v52
	v_sub_f32_e32 v22, v78, v52
	v_pk_mul_f32 v[22:23], v[52:53], v[22:23] op_sel:[1,0]
	v_pk_mul_f32 v[20:21], v[52:53], v[20:21] op_sel:[1,0]
	v_pk_fma_f32 v[18:19], v[92:93], v[22:23], v[18:19]
	v_pk_fma_f32 v[16:17], v[94:95], v[20:21], v[16:17]
	v_pk_fma_f32 v[18:19], v[66:67], s[78:79], v[18:19] op_sel_hi:[1,0,1]
	v_pk_fma_f32 v[16:17], v[64:65], s[78:79], v[16:17] op_sel_hi:[1,0,1]
	v_lshl_add_u64 v[20:21], v[158:159], 2, s[88:89]
	global_store_dwordx4 v[20:21], v[16:19], off
	v_add_u32_e32 v158, 0x50080, v148
	s_nop 0
	v_sub_f32_e32 v17, v45, v50
	v_sub_f32_e32 v16, v44, v50
	v_sub_f32_e32 v19, v47, v50
	v_sub_f32_e32 v18, v46, v50
	v_pk_mul_f32 v[18:19], v[50:51], v[18:19] op_sel:[1,0]
	v_pk_mul_f32 v[16:17], v[50:51], v[16:17] op_sel:[1,0]
	v_pk_fma_f32 v[14:15], v[96:97], v[18:19], v[14:15]
	v_pk_fma_f32 v[12:13], v[98:99], v[16:17], v[12:13]
	v_pk_fma_f32 v[14:15], v[70:71], s[78:79], v[14:15] op_sel_hi:[1,0,1]
	v_pk_fma_f32 v[12:13], v[68:69], s[78:79], v[12:13] op_sel_hi:[1,0,1]
	v_lshl_add_u64 v[16:17], v[158:159], 2, s[88:89]
	global_store_dwordx4 v[16:17], v[12:15], off
	v_add_u32_e32 v158, 0x50090, v148
	s_nop 0
	v_sub_f32_e32 v13, v41, v50
	v_sub_f32_e32 v12, v40, v50
	v_sub_f32_e32 v15, v43, v50
	v_sub_f32_e32 v14, v42, v50
	v_pk_mul_f32 v[14:15], v[50:51], v[14:15] op_sel:[1,0]
	v_pk_mul_f32 v[12:13], v[50:51], v[12:13] op_sel:[1,0]
	v_pk_fma_f32 v[10:11], v[92:93], v[14:15], v[10:11]
	v_pk_fma_f32 v[8:9], v[94:95], v[12:13], v[8:9]
	v_pk_fma_f32 v[10:11], v[66:67], s[78:79], v[10:11] op_sel_hi:[1,0,1]
	v_pk_fma_f32 v[8:9], v[64:65], s[78:79], v[8:9] op_sel_hi:[1,0,1]
	v_lshl_add_u64 v[12:13], v[158:159], 2, s[88:89]
	global_store_dwordx4 v[12:13], v[8:11], off
	v_add_u32_e32 v158, 0x58080, v148
	s_nop 0
	v_sub_f32_e32 v9, v37, v48
	v_sub_f32_e32 v8, v36, v48
	v_sub_f32_e32 v11, v39, v48
	v_sub_f32_e32 v10, v38, v48
	v_pk_mul_f32 v[10:11], v[48:49], v[10:11] op_sel:[1,0]
	v_pk_mul_f32 v[8:9], v[48:49], v[8:9] op_sel:[1,0]
	v_pk_fma_f32 v[6:7], v[96:97], v[10:11], v[6:7]
	v_pk_fma_f32 v[4:5], v[98:99], v[8:9], v[4:5]
	v_pk_fma_f32 v[6:7], v[70:71], s[78:79], v[6:7] op_sel_hi:[1,0,1]
	v_pk_fma_f32 v[4:5], v[68:69], s[78:79], v[4:5] op_sel_hi:[1,0,1]
	v_lshl_add_u64 v[8:9], v[158:159], 2, s[88:89]
	global_store_dwordx4 v[8:9], v[4:7], off
	v_add_u32_e32 v158, 0x58090, v148
	s_nop 0
	v_sub_f32_e32 v5, v33, v48
	v_sub_f32_e32 v4, v32, v48
	v_sub_f32_e32 v7, v35, v48
	v_sub_f32_e32 v6, v34, v48
	v_pk_mul_f32 v[6:7], v[48:49], v[6:7] op_sel:[1,0]
	v_pk_mul_f32 v[4:5], v[48:49], v[4:5] op_sel:[1,0]
	v_pk_fma_f32 v[2:3], v[92:93], v[6:7], v[2:3]
	v_pk_fma_f32 v[0:1], v[94:95], v[4:5], v[0:1]
	v_pk_fma_f32 v[2:3], v[66:67], s[78:79], v[2:3] op_sel_hi:[1,0,1]
	v_pk_fma_f32 v[0:1], v[64:65], s[78:79], v[0:1] op_sel_hi:[1,0,1]
	v_lshl_add_u64 v[4:5], v[158:159], 2, s[88:89]
	global_store_dwordx4 v[4:5], v[0:3], off
	s_and_b64 vcc, exec, s[6:7]
	s_mov_b32 s2, s37
	s_mov_b32 s3, s38
	s_mov_b64 s[18:19], s[10:11]
	s_mov_b64 s[16:17], s[8:9]
	v_readlane_b32 s33, v255, 39
	s_cbranch_vccz .LBB0_123
	s_waitcnt vmcnt(0)
	s_cmpk_gt_u32 s24, 0xff
	s_cbranch_scc1 .LBB0_138
	s_barrier

; #define PG8_STAGE(bufoff, gbase) do { _Pragma("unroll") for (int _i = 0; _i < 2; ++_i) \
;         __builtin_amdgcn_global_load_lds((const unsigned*)((const char*)(gbase) + voff[_i]), (LAS unsigned*)(lds + (bufoff) + ldsw + _i * 8192), 16, 0, 0); } while (0)
; #define PG8_LDA(dst, b, h) do { _Pragma("unroll") for (int m = 0; m < 4; ++m) _Pragma("unroll") for (int k = 0; k < 2; ++k) dst[m][k] = *(const LAS bf16x8*)(lds + PG8_SA(b, h) + aoff + m * 2048 + k * 1024); } while (0)
; #define PG8_LDB(dst, b, h) do { _Pragma("unroll") for (int n = 0; n < 2; ++n) _Pragma("unroll") for (int k = 0; k < 2; ++k) dst[n][k] = *(const LAS bf16x8*)(lds + PG8_SB(b, h) + boff + n * 2048 + k * 1024); } while (0)
; #define PG8_MMA(ai, bj, At, Bt) do { __builtin_amdgcn_s_setprio(1); _Pragma("unroll") for (int m = 0; m < 4; ++m) _Pragma("unroll") for (int n = 0; n < 2; ++n) _Pragma("unroll") for (int k = 0; k < 2; ++k) \
;         acc[ai][bj][m][n] = __builtin_amdgcn_mfma_f32_16x16x32_bf16(Bt[n][k], At[m][k], acc[ai][bj][m][n], 0, 0, 0); __builtin_amdgcn_s_setprio(0); } while (0)
; #define PG8_WAIT_L(n) asm volatile("s_waitcnt lgkmcnt(" #n ")" ::: "memory")
; #define PG8_BAR __builtin_amdgcn_s_barrier()
; #define PG8_SCHED __builtin_amdgcn_sched_barrier(0)
; template <class Epi>
; DI void gemm_phase(LAS unsigned char* lds, const Gemm g, const StaticOrder& S, const Epi& E) {
;     ...
;         for (int t = 0; t < nt; t += 2) {
;             const bool last = (t == nt - 2);
;             const char* a1 = cA + (size_t)(t + 1) * kstep;
;             const char* a2 = last ? nA : cA + (size_t)(t + 2) * kstep; const char* b2 = last ? nB : cB + (size_t)(t + 2) * kstep;
;             const char* a3 = a2 + kstep; const char* b3 = b2 + kstep;
;             PG8_LDB(B0, 0, 0); PG8_SCHED; PG8_LDA(At, 0, 0); PG8_STAGE(PG8_SA(1, 1), a1 + hstep);
;             PG8_WAIT_L(8); PG8_BAR; PG8_WAIT_L(0); PG8_MMA(0, 0, At, B0); PG8_BAR; PG8_SCHED;
;             PG8_LDB(B1, 0, 1); PG8_STAGE(PG8_SB(0, 0), b2);
;             PG8_BAR; PG8_WAIT_L(0); PG8_MMA(0, 1, At, B1); PG8_BAR;
;             PG8_LDA(At, 0, 1); PG8_STAGE(PG8_SA(0, 0), a2);
;             PG8_BAR; PG8_WAIT_L(0); PG8_MMA(1, 0, At, B0); PG8_BAR; PG8_SCHED;
.LBB0_202:
	s_add_u32 s18, s8, 0xfff80080
	s_addc_u32 s19, s9, -1
	s_add_i32 s37, 0, 0x10000
	v_add_u32_e32 v140, s37, v187
	s_waitcnt lgkmcnt(0)
	ds_read_b128 v[128:131], v140
	ds_read_b128 v[132:135], v140 offset:1024
	ds_read_b128 v[136:139], v140 offset:2048
	ds_read_b128 v[190:193], v140 offset:3072
	s_cmp_eq_u32 s36, 28
	s_cselect_b32 s21, s4, s19
	s_cselect_b32 s20, s5, s18
	s_cselect_b32 s19, s11, s35
	s_cselect_b32 s18, s13, s33
	v_lshl_add_u64 v[140:141], s[8:9], 0, v[150:151]
	s_add_i32 m0, s26, 0xc000
	ds_read_b128 v[194:197], v189
	ds_read_b128 v[198:201], v189 offset:1024
	ds_read_b128 v[202:205], v189 offset:2048
	ds_read_b128 v[206:209], v189 offset:3072
	ds_read_b128 v[210:213], v189 offset:4096
	ds_read_b128 v[214:217], v189 offset:5120
	ds_read_b128 v[226:229], v189 offset:6144
	ds_read_b128 v[230:233], v189 offset:7168
	global_load_lds_dwordx4 v[140:141], off
	v_lshl_add_u64 v[140:141], s[8:9], 0, v[152:153]
	s_add_i32 m0, s26, 0xe000
	s_nop 0
	global_load_lds_dwordx4 v[140:141], off
	s_waitcnt lgkmcnt(8)
	s_setprio 1
	s_barrier
	s_waitcnt lgkmcnt(0)
	v_mfma_f32_16x16x32_bf16 v[124:127], v[128:131], v[194:197], v[124:127]
	v_mfma_f32_16x16x32_bf16 v[120:123], v[136:139], v[194:197], v[120:123]
	v_mfma_f32_16x16x32_bf16 v[108:111], v[128:131], v[202:205], v[108:111]
	v_mfma_f32_16x16x32_bf16 v[104:107], v[136:139], v[202:205], v[104:107]
	v_mfma_f32_16x16x32_bf16 v[92:95], v[128:131], v[210:213], v[92:95]
	v_mfma_f32_16x16x32_bf16 v[88:91], v[136:139], v[210:213], v[88:91]
	v_mfma_f32_16x16x32_bf16 v[76:79], v[128:131], v[226:229], v[76:79]
	v_mfma_f32_16x16x32_bf16 v[72:75], v[136:139], v[226:229], v[72:75]
	v_mfma_f32_16x16x32_bf16 v[124:127], v[132:135], v[198:201], v[124:127]
	v_mfma_f32_16x16x32_bf16 v[120:123], v[190:193], v[198:201], v[120:123]
	v_mfma_f32_16x16x32_bf16 v[108:111], v[132:135], v[206:209], v[108:111]
	v_mfma_f32_16x16x32_bf16 v[104:107], v[190:193], v[206:209], v[104:107]
	v_mfma_f32_16x16x32_bf16 v[92:95], v[132:135], v[214:217], v[92:95]
	v_mfma_f32_16x16x32_bf16 v[88:91], v[190:193], v[214:217], v[88:91]
	v_mfma_f32_16x16x32_bf16 v[76:79], v[132:135], v[230:233], v[76:79]
	v_mfma_f32_16x16x32_bf16 v[72:75], v[190:193], v[230:233], v[72:75]
	s_setprio 0
	s_barrier
	s_add_i32 s40, 0, 0x14000
	v_add_u32_e32 v140, s40, v187
	s_add_i32 s37, s37, s25
	ds_read_b128 v[234:237], v140
	ds_read_b128 v[238:241], v140 offset:1024
	ds_read_b128 v[242:245], v140 offset:2048
	ds_read_b128 v[246:249], v140 offset:3072
	v_lshl_add_u64 v[140:141], s[18:19], 0, v[144:145]
	s_mov_b32 m0, s37
	v_lshl_add_u64 v[154:155], s[18:19], 0, v[142:143]
	global_load_lds_dwordx4 v[140:141], off
	s_add_i32 m0, s37, 0x2000
	s_nop 0
	global_load_lds_dwordx4 v[154:155], off
	s_waitcnt lgkmcnt(0)
	s_setprio 1
	s_barrier
	v_mfma_f32_16x16x32_bf16 v[116:119], v[234:237], v[194:197], v[116:119]
	v_mfma_f32_16x16x32_bf16 v[112:115], v[242:245], v[194:197], v[112:115]
	v_mfma_f32_16x16x32_bf16 v[100:103], v[234:237], v[202:205], v[100:103]
	v_mfma_f32_16x16x32_bf16 v[96:99], v[242:245], v[202:205], v[96:99]
	v_mfma_f32_16x16x32_bf16 v[84:87], v[234:237], v[210:213], v[84:87]
	v_mfma_f32_16x16x32_bf16 v[80:83], v[242:245], v[210:213], v[80:83]
	v_mfma_f32_16x16x32_bf16 v[68:71], v[234:237], v[226:229], v[68:71]
	v_mfma_f32_16x16x32_bf16 v[64:67], v[242:245], v[226:229], v[64:67]
	v_mfma_f32_16x16x32_bf16 v[116:119], v[238:241], v[198:201], v[116:119]
	v_mfma_f32_16x16x32_bf16 v[112:115], v[246:249], v[198:201], v[112:115]
	v_mfma_f32_16x16x32_bf16 v[100:103], v[238:241], v[206:209], v[100:103]
	v_mfma_f32_16x16x32_bf16 v[96:99], v[246:249], v[206:209], v[96:99]
	v_mfma_f32_16x16x32_bf16 v[84:87], v[238:241], v[214:217], v[84:87]
	v_mfma_f32_16x16x32_bf16 v[80:83], v[246:249], v[214:217], v[80:83]
	v_mfma_f32_16x16x32_bf16 v[68:71], v[238:241], v[230:233], v[68:71]
	v_mfma_f32_16x16x32_bf16 v[64:67], v[246:249], v[230:233], v[64:67]
	s_setprio 0
	s_mov_b32 m0, s26
	v_lshl_add_u64 v[218:219], s[20:21], 0, v[144:145]
	s_barrier
	ds_read_b128 v[194:197], v189 offset:16384
	ds_read_b128 v[198:201], v189 offset:17408
	ds_read_b128 v[202:205], v189 offset:18432
	ds_read_b128 v[206:209], v189 offset:19456
	ds_read_b128 v[210:213], v189 offset:20480
	ds_read_b128 v[214:217], v189 offset:21504
	ds_read_b128 v[226:229], v189 offset:22528
	ds_read_b128 v[230:233], v189 offset:23552
	global_load_lds_dwordx4 v[218:219], off
	v_lshl_add_u64 v[250:251], s[20:21], 0, v[142:143]
	s_mov_b32 m0, s27
	s_nop 0
	global_load_lds_dwordx4 v[250:251], off
	s_waitcnt lgkmcnt(0)
	s_setprio 1
	s_barrier
	v_mfma_f32_16x16x32_bf16 v[60:63], v[128:131], v[194:197], v[60:63]
	v_mfma_f32_16x16x32_bf16 v[56:59], v[136:139], v[194:197], v[56:59]
	v_mfma_f32_16x16x32_bf16 v[44:47], v[128:131], v[202:205], v[44:47]
	v_mfma_f32_16x16x32_bf16 v[40:43], v[136:139], v[202:205], v[40:43]
	v_mfma_f32_16x16x32_bf16 v[28:31], v[128:131], v[210:213], v[28:31]
	v_mfma_f32_16x16x32_bf16 v[24:27], v[136:139], v[210:213], v[24:27]
	v_mfma_f32_16x16x32_bf16 v[12:15], v[128:131], v[226:229], v[12:15]
	v_mfma_f32_16x16x32_bf16 v[8:11], v[136:139], v[226:229], v[8:11]
	v_mfma_f32_16x16x32_bf16 v[60:63], v[132:135], v[198:201], v[60:63]
	v_mfma_f32_16x16x32_bf16 v[56:59], v[190:193], v[198:201], v[56:59]
	v_mfma_f32_16x16x32_bf16 v[44:47], v[132:135], v[206:209], v[44:47]
	v_mfma_f32_16x16x32_bf16 v[40:43], v[190:193], v[206:209], v[40:43]
	v_mfma_f32_16x16x32_bf16 v[28:31], v[132:135], v[214:217], v[28:31]
	v_mfma_f32_16x16x32_bf16 v[24:27], v[190:193], v[214:217], v[24:27]
	v_mfma_f32_16x16x32_bf16 v[12:15], v[132:135], v[230:233], v[12:15]
	v_mfma_f32_16x16x32_bf16 v[8:11], v[190:193], v[230:233], v[8:11]
	s_setprio 0
	s_barrier
; #define PG8_STAGE(bufoff, gbase) do { _Pragma("unroll") for (int _i = 0; _i < 2; ++_i) \
;         __builtin_amdgcn_global_load_lds((const unsigned*)((const char*)(gbase) + voff[_i]), (LAS unsigned*)(lds + (bufoff) + ldsw + _i * 8192), 16, 0, 0); } while (0)
; #define PG8_LDA(dst, b, h) do { _Pragma("unroll") for (int m = 0; m < 4; ++m) _Pragma("unroll") for (int k = 0; k < 2; ++k) dst[m][k] = *(const LAS bf16x8*)(lds + PG8_SA(b, h) + aoff + m * 2048 + k * 1024); } while (0)
; #define PG8_LDB(dst, b, h) do { _Pragma("unroll") for (int n = 0; n < 2; ++n) _Pragma("unroll") for (int k = 0; k < 2; ++k) dst[n][k] = *(const LAS bf16x8*)(lds + PG8_SB(b, h) + boff + n * 2048 + k * 1024); } while (0)
; #define PG8_MMA(ai, bj, At, Bt) do { __builtin_amdgcn_s_setprio(1); _Pragma("unroll") for (int m = 0; m < 4; ++m) _Pragma("unroll") for (int n = 0; n < 2; ++n) _Pragma("unroll") for (int k = 0; k < 2; ++k) \
;         acc[ai][bj][m][n] = __builtin_amdgcn_mfma_f32_16x16x32_bf16(Bt[n][k], At[m][k], acc[ai][bj][m][n], 0, 0, 0); __builtin_amdgcn_s_setprio(0); } while (0)
; #define PG8_WAIT_V(n) asm volatile("s_waitcnt vmcnt(" #n ")" ::: "memory")
; #define PG8_WAIT_L(n) asm volatile("s_waitcnt lgkmcnt(" #n ")" ::: "memory")
; #define PG8_BAR __builtin_amdgcn_s_barrier()
; #define PG8_SCHED __builtin_amdgcn_sched_barrier(0)
; template <class Epi>
; DI void gemm_phase(LAS unsigned char* lds, const Gemm g, const StaticOrder& S, const Epi& E) {
;     ...
;             PG8_BAR; PG8_WAIT_L(0); PG8_MMA(1, 0, At, B0); PG8_BAR; PG8_SCHED;
;             PG8_STAGE(PG8_SB(0, 1), b2 + hstep);
;             PG8_WAIT_V(6); PG8_BAR; PG8_MMA(1, 1, At, B1); PG8_BAR;
;             PG8_LDB(B0, 1, 0); PG8_SCHED; PG8_LDA(At, 1, 0); PG8_STAGE(PG8_SA(0, 1), a2 + hstep);
;             PG8_WAIT_L(8); PG8_BAR; PG8_WAIT_L(0); PG8_MMA(0, 0, At, B0); PG8_BAR; PG8_SCHED;
;             PG8_LDB(B1, 1, 1); PG8_STAGE(PG8_SB(1, 0), b3);
;             PG8_BAR; PG8_WAIT_L(0); PG8_MMA(0, 1, At, B1); PG8_BAR;
;             PG8_LDA(At, 1, 1); PG8_STAGE(PG8_SA(1, 0), a3);
;             PG8_BAR; PG8_WAIT_L(0); PG8_MMA(1, 0, At, B0); PG8_BAR; PG8_SCHED;
	s_add_u32 s38, s18, 0x80000
	s_addc_u32 s39, s19, 0
	s_add_i32 s37, s40, s25
	v_lshl_add_u64 v[128:129], s[38:39], 0, v[144:145]
	s_mov_b32 m0, s37
	s_nop 0
	global_load_lds_dwordx4 v[128:129], off
	v_lshl_add_u64 v[128:129], s[38:39], 0, v[142:143]
	s_add_i32 m0, s37, 0x2000
	s_nop 0
	global_load_lds_dwordx4 v[128:129], off
	s_waitcnt vmcnt(6)
	s_setprio 1
	s_barrier
	v_mfma_f32_16x16x32_bf16 v[52:55], v[234:237], v[194:197], v[52:55]
	v_mfma_f32_16x16x32_bf16 v[48:51], v[242:245], v[194:197], v[48:51]
	v_mfma_f32_16x16x32_bf16 v[36:39], v[234:237], v[202:205], v[36:39]
	v_mfma_f32_16x16x32_bf16 v[32:35], v[242:245], v[202:205], v[32:35]
	v_mfma_f32_16x16x32_bf16 v[20:23], v[234:237], v[210:213], v[20:23]
	v_mfma_f32_16x16x32_bf16 v[16:19], v[242:245], v[210:213], v[16:19]
	v_mfma_f32_16x16x32_bf16 v[4:7], v[234:237], v[226:229], v[4:7]
	v_mfma_f32_16x16x32_bf16 v[0:3], v[242:245], v[226:229], v[0:3]
	v_mfma_f32_16x16x32_bf16 v[52:55], v[238:241], v[198:201], v[52:55]
	v_mfma_f32_16x16x32_bf16 v[48:51], v[246:249], v[198:201], v[48:51]
	v_mfma_f32_16x16x32_bf16 v[36:39], v[238:241], v[206:209], v[36:39]
	v_mfma_f32_16x16x32_bf16 v[32:35], v[246:249], v[206:209], v[32:35]
	v_mfma_f32_16x16x32_bf16 v[20:23], v[238:241], v[214:217], v[20:23]
	v_mfma_f32_16x16x32_bf16 v[16:19], v[246:249], v[214:217], v[16:19]
	v_mfma_f32_16x16x32_bf16 v[4:7], v[238:241], v[230:233], v[4:7]
	v_mfma_f32_16x16x32_bf16 v[0:3], v[246:249], v[230:233], v[0:3]
	s_setprio 0
	s_add_i32 s37, 0, 0x18000
	v_add_u32_e32 v158, s37, v187
	s_barrier
	ds_read_b128 v[128:131], v158
	ds_read_b128 v[132:135], v158 offset:1024
	ds_read_b128 v[136:139], v158 offset:2048
	ds_read_b128 v[190:193], v158 offset:3072
	s_add_u32 s20, s20, 0x80000
	s_addc_u32 s21, s21, 0
	s_mov_b32 m0, s28
	v_lshl_add_u64 v[234:235], s[20:21], 0, v[144:145]
	ds_read_b128 v[194:197], v189 offset:32768
	ds_read_b128 v[198:201], v189 offset:33792
	ds_read_b128 v[202:205], v189 offset:34816
	ds_read_b128 v[206:209], v189 offset:35840
	ds_read_b128 v[210:213], v189 offset:36864
	ds_read_b128 v[214:217], v189 offset:37888
	ds_read_b128 v[226:229], v189 offset:38912
	ds_read_b128 v[230:233], v189 offset:39936
	global_load_lds_dwordx4 v[234:235], off
	v_lshl_add_u64 v[234:235], s[20:21], 0, v[142:143]
	s_mov_b32 m0, s29
	s_nop 0
	global_load_lds_dwordx4 v[234:235], off
	s_waitcnt lgkmcnt(8)
	s_setprio 1
	s_barrier
	s_waitcnt lgkmcnt(0)
	v_mfma_f32_16x16x32_bf16 v[124:127], v[128:131], v[194:197], v[124:127]
	v_mfma_f32_16x16x32_bf16 v[120:123], v[136:139], v[194:197], v[120:123]
	v_mfma_f32_16x16x32_bf16 v[108:111], v[128:131], v[202:205], v[108:111]
	v_mfma_f32_16x16x32_bf16 v[104:107], v[136:139], v[202:205], v[104:107]
	v_mfma_f32_16x16x32_bf16 v[92:95], v[128:131], v[210:213], v[92:95]
	v_mfma_f32_16x16x32_bf16 v[88:91], v[136:139], v[210:213], v[88:91]
	v_mfma_f32_16x16x32_bf16 v[76:79], v[128:131], v[226:229], v[76:79]
	v_mfma_f32_16x16x32_bf16 v[72:75], v[136:139], v[226:229], v[72:75]
	v_mfma_f32_16x16x32_bf16 v[124:127], v[132:135], v[198:201], v[124:127]
	v_mfma_f32_16x16x32_bf16 v[120:123], v[190:193], v[198:201], v[120:123]
	v_mfma_f32_16x16x32_bf16 v[108:111], v[132:135], v[206:209], v[108:111]
	v_mfma_f32_16x16x32_bf16 v[104:107], v[190:193], v[206:209], v[104:107]
	v_mfma_f32_16x16x32_bf16 v[92:95], v[132:135], v[214:217], v[92:95]
	v_mfma_f32_16x16x32_bf16 v[88:91], v[190:193], v[214:217], v[88:91]
	v_mfma_f32_16x16x32_bf16 v[76:79], v[132:135], v[230:233], v[76:79]
	v_mfma_f32_16x16x32_bf16 v[72:75], v[190:193], v[230:233], v[72:75]
	s_setprio 0
	s_barrier
	s_add_i32 s20, 0, 0x1c000
	s_add_i32 s21, s37, s25
	v_add_u32_e32 v158, s20, v187
	v_lshl_add_u64 v[140:141], v[140:141], 0, s[94:95]
	s_mov_b32 m0, s21
	ds_read_b128 v[234:237], v158
	ds_read_b128 v[238:241], v158 offset:1024
	ds_read_b128 v[242:245], v158 offset:2048
	ds_read_b128 v[246:249], v158 offset:3072
	global_load_lds_dwordx4 v[140:141], off
	v_lshl_add_u64 v[140:141], v[154:155], 0, s[94:95]
	s_add_i32 m0, s21, 0x2000
	s_nop 0
	global_load_lds_dwordx4 v[140:141], off
	s_waitcnt lgkmcnt(0)
	s_setprio 1
	s_barrier
; #define PG8_STAGE(bufoff, gbase) do { _Pragma("unroll") for (int _i = 0; _i < 2; ++_i) \
;         __builtin_amdgcn_global_load_lds((const unsigned*)((const char*)(gbase) + voff[_i]), (LAS unsigned*)(lds + (bufoff) + ldsw + _i * 8192), 16, 0, 0); } while (0)
; #define PG8_MMA(ai, bj, At, Bt) do { __builtin_amdgcn_s_setprio(1); _Pragma("unroll") for (int m = 0; m < 4; ++m) _Pragma("unroll") for (int n = 0; n < 2; ++n) _Pragma("unroll") for (int k = 0; k < 2; ++k) \
;         acc[ai][bj][m][n] = __builtin_amdgcn_mfma_f32_16x16x32_bf16(Bt[n][k], At[m][k], acc[ai][bj][m][n], 0, 0, 0); __builtin_amdgcn_s_setprio(0); } while (0)
; #define PG8_WAIT_V(n) asm volatile("s_waitcnt vmcnt(" #n ")" ::: "memory")
; #define PG8_WAIT_L(n) asm volatile("s_waitcnt lgkmcnt(" #n ")" ::: "memory")
; #define PG8_BAR __builtin_amdgcn_s_barrier()
; #define PG8_SCHED __builtin_amdgcn_sched_barrier(0)
; template <class Epi>
; DI void gemm_phase(LAS unsigned char* lds, const Gemm g, const StaticOrder& S, const Epi& E) {
;     ...
;             PG8_BAR; PG8_WAIT_L(0); PG8_MMA(1, 0, At, B0); PG8_BAR; PG8_SCHED;
;             PG8_STAGE(PG8_SB(1, 1), b3 + hstep);
;             PG8_WAIT_V(6); PG8_BAR; PG8_MMA(1, 1, At, B1); PG8_BAR;
;     DI void operator()(const f32x4 (&acc)[2][2][4][2], const Unit& u, int wr, int wc, int fr, int fq) const {
;         const int row0 = u.pm * BM + wr * 64 + fr, col0 = u.pn * BM + wc * 16 + 4 * fq;
;         const bool rot = u.pn < 18;
; #pragma unroll
;         for (int ai = 0; ai < 2; ++ai)
; #pragma unroll
;             for (int m = 0; m < 4; ++m) { const int row = row0 + ai * HALF + m * 16; u16* rowp = O + (size_t)row * NQKV_DIL + col0;
;                 f32x4 c4 = (f32x4){1.f, 1.f, 1.f, 1.f}, s4 = (f32x4){0.f, 0.f, 0.f, 0.f};
;                 if (rot) { const int pos = row & (SEQ - 1); c4 = *(const f32x4*)(cs + pos * 64 + wc * 16 + 4 * fq); s4 = *(const f32x4*)(sn + pos * 64 + wc * 16 + 4 * fq); }
	v_mfma_f32_16x16x32_bf16 v[116:119], v[234:237], v[194:197], v[116:119]
	v_mfma_f32_16x16x32_bf16 v[112:115], v[242:245], v[194:197], v[112:115]
	v_mfma_f32_16x16x32_bf16 v[100:103], v[234:237], v[202:205], v[100:103]
	v_mfma_f32_16x16x32_bf16 v[96:99], v[242:245], v[202:205], v[96:99]
	v_mfma_f32_16x16x32_bf16 v[84:87], v[234:237], v[210:213], v[84:87]
	v_mfma_f32_16x16x32_bf16 v[80:83], v[242:245], v[210:213], v[80:83]
	v_mfma_f32_16x16x32_bf16 v[68:71], v[234:237], v[226:229], v[68:71]
	v_mfma_f32_16x16x32_bf16 v[64:67], v[242:245], v[226:229], v[64:67]
	v_mfma_f32_16x16x32_bf16 v[116:119], v[238:241], v[198:201], v[116:119]
	v_mfma_f32_16x16x32_bf16 v[112:115], v[246:249], v[198:201], v[112:115]
	v_mfma_f32_16x16x32_bf16 v[100:103], v[238:241], v[206:209], v[100:103]
	v_mfma_f32_16x16x32_bf16 v[96:99], v[246:249], v[206:209], v[96:99]
	v_mfma_f32_16x16x32_bf16 v[84:87], v[238:241], v[214:217], v[84:87]
	v_mfma_f32_16x16x32_bf16 v[80:83], v[246:249], v[214:217], v[80:83]
	v_mfma_f32_16x16x32_bf16 v[68:71], v[238:241], v[230:233], v[68:71]
	v_mfma_f32_16x16x32_bf16 v[64:67], v[246:249], v[230:233], v[64:67]
	s_setprio 0
	s_mov_b32 m0, s30
	v_lshl_add_u64 v[140:141], v[218:219], 0, s[94:95]
	s_barrier
	ds_read_b128 v[194:197], v189 offset:49152
	ds_read_b128 v[198:201], v189 offset:50176
	ds_read_b128 v[202:205], v189 offset:51200
	ds_read_b128 v[206:209], v189 offset:52224
	ds_read_b128 v[210:213], v189 offset:53248
	ds_read_b128 v[214:217], v189 offset:54272
	ds_read_b128 v[226:229], v189 offset:55296
	ds_read_b128 v[230:233], v189 offset:56320
	global_load_lds_dwordx4 v[140:141], off
	v_lshl_add_u64 v[140:141], v[250:251], 0, s[94:95]
	s_mov_b32 m0, s31
	s_nop 0
	global_load_lds_dwordx4 v[140:141], off
	s_waitcnt lgkmcnt(0)
	s_setprio 1
	s_barrier
	v_mfma_f32_16x16x32_bf16 v[60:63], v[128:131], v[194:197], v[60:63]
	v_mfma_f32_16x16x32_bf16 v[56:59], v[136:139], v[194:197], v[56:59]
	v_mfma_f32_16x16x32_bf16 v[44:47], v[128:131], v[202:205], v[44:47]
	v_mfma_f32_16x16x32_bf16 v[40:43], v[136:139], v[202:205], v[40:43]
	v_mfma_f32_16x16x32_bf16 v[28:31], v[128:131], v[210:213], v[28:31]
	v_mfma_f32_16x16x32_bf16 v[24:27], v[136:139], v[210:213], v[24:27]
	v_mfma_f32_16x16x32_bf16 v[12:15], v[128:131], v[226:229], v[12:15]
	v_mfma_f32_16x16x32_bf16 v[8:11], v[136:139], v[226:229], v[8:11]
	v_mfma_f32_16x16x32_bf16 v[60:63], v[132:135], v[198:201], v[60:63]
	v_mfma_f32_16x16x32_bf16 v[56:59], v[190:193], v[198:201], v[56:59]
	v_mfma_f32_16x16x32_bf16 v[44:47], v[132:135], v[206:209], v[44:47]
	v_mfma_f32_16x16x32_bf16 v[40:43], v[190:193], v[206:209], v[40:43]
	v_mfma_f32_16x16x32_bf16 v[28:31], v[132:135], v[214:217], v[28:31]
	v_mfma_f32_16x16x32_bf16 v[24:27], v[190:193], v[214:217], v[24:27]
	v_mfma_f32_16x16x32_bf16 v[12:15], v[132:135], v[230:233], v[12:15]
	v_mfma_f32_16x16x32_bf16 v[8:11], v[190:193], v[230:233], v[8:11]
	s_setprio 0
	s_barrier
	s_add_u32 s18, s18, 0x80080
	s_addc_u32 s19, s19, 0
	s_add_i32 s20, s20, s25
	v_lshl_add_u64 v[128:129], s[18:19], 0, v[144:145]
	s_mov_b32 m0, s20
	s_nop 0
	global_load_lds_dwordx4 v[128:129], off
	v_lshl_add_u64 v[128:129], s[18:19], 0, v[142:143]
	s_add_i32 m0, s20, 0x2000
	s_nop 0
	global_load_lds_dwordx4 v[128:129], off
	s_waitcnt vmcnt(6)
	s_setprio 1
	s_barrier
	v_mfma_f32_16x16x32_bf16 v[52:55], v[234:237], v[194:197], v[52:55]
	v_mfma_f32_16x16x32_bf16 v[48:51], v[242:245], v[194:197], v[48:51]
	v_mfma_f32_16x16x32_bf16 v[36:39], v[234:237], v[202:205], v[36:39]
	v_mfma_f32_16x16x32_bf16 v[32:35], v[242:245], v[202:205], v[32:35]
	v_mfma_f32_16x16x32_bf16 v[20:23], v[234:237], v[210:213], v[20:23]
	v_mfma_f32_16x16x32_bf16 v[16:19], v[242:245], v[210:213], v[16:19]
	v_mfma_f32_16x16x32_bf16 v[4:7], v[234:237], v[226:229], v[4:7]
	v_mfma_f32_16x16x32_bf16 v[0:3], v[242:245], v[226:229], v[0:3]
	v_mfma_f32_16x16x32_bf16 v[52:55], v[238:241], v[198:201], v[52:55]
	v_mfma_f32_16x16x32_bf16 v[48:51], v[246:249], v[198:201], v[48:51]
	v_mfma_f32_16x16x32_bf16 v[36:39], v[238:241], v[206:209], v[36:39]
	v_mfma_f32_16x16x32_bf16 v[32:35], v[246:249], v[206:209], v[32:35]
	v_mfma_f32_16x16x32_bf16 v[20:23], v[238:241], v[214:217], v[20:23]
	v_mfma_f32_16x16x32_bf16 v[16:19], v[246:249], v[214:217], v[16:19]
	v_mfma_f32_16x16x32_bf16 v[4:7], v[238:241], v[230:233], v[4:7]
	v_mfma_f32_16x16x32_bf16 v[0:3], v[246:249], v[230:233], v[0:3]
	s_setprio 0
	s_add_i32 s36, s36, 2
	s_add_u32 s8, s8, 0x100
	s_addc_u32 s9, s9, 0
	s_add_u32 s33, s33, 0x100
	s_addc_u32 s35, s35, 0
	s_cmp_gt_u32 s36, 29
	s_barrier
	s_cbranch_scc0 .LBB0_202
	s_cmp_lt_i32 s2, 18
	v_lshl_add_u32 v190, s3, 8, v186
	v_mov_b32_e32 v128, 1.0
	v_mov_b32_e32 v132, 0
	s_cselect_b64 s[18:19], -1, 0
	s_cmp_gt_i32 s2, 17
	v_mov_b32_e32 v134, 0
	v_mov_b32_e32 v135, 0
	v_mov_b32_e32 v136, 0
	v_mov_b32_e32 v137, 0
	v_mov_b32_e32 v138, 1.0
	v_mov_b32_e32 v139, 1.0
	v_mov_b32_e32 v140, 1.0
	v_mov_b32_e32 v141, 1.0
	s_cbranch_scc1 .LBB0_205
	v_lshlrev_b32_e32 v129, 8, v190
	v_and_b32_e32 v158, 0xfcf00, v129
	v_lshl_add_u64 v[130:131], v[146:147], 0, v[158:159]
	v_lshl_add_u64 v[134:135], v[148:149], 0, v[158:159]
	global_load_dwordx4 v[138:141], v[130:131], off
	s_nop 0
	global_load_dwordx4 v[134:137], v[134:135], off

; #define PG8_STAGE(bufoff, gbase) do { _Pragma("unroll") for (int _i = 0; _i < 2; ++_i) \
;         __builtin_amdgcn_global_load_lds((const unsigned*)((const char*)(gbase) + voff[_i]), (LAS unsigned*)(lds + (bufoff) + ldsw + _i * 8192), 16, 0, 0); } while (0)
; #define PG8_LDA(dst, b, h) do { _Pragma("unroll") for (int m = 0; m < 4; ++m) _Pragma("unroll") for (int k = 0; k < 2; ++k) dst[m][k] = *(const LAS bf16x8*)(lds + PG8_SA(b, h) + aoff + m * 2048 + k * 1024); } while (0)
; #define PG8_LDB(dst, b, h) do { _Pragma("unroll") for (int n = 0; n < 2; ++n) _Pragma("unroll") for (int k = 0; k < 2; ++k) dst[n][k] = *(const LAS bf16x8*)(lds + PG8_SB(b, h) + boff + n * 2048 + k * 1024); } while (0)
; #define PG8_MMA(ai, bj, At, Bt) do { __builtin_amdgcn_s_setprio(1); _Pragma("unroll") for (int m = 0; m < 4; ++m) _Pragma("unroll") for (int n = 0; n < 2; ++n) _Pragma("unroll") for (int k = 0; k < 2; ++k) \
;         acc[ai][bj][m][n] = __builtin_amdgcn_mfma_f32_16x16x32_bf16(Bt[n][k], At[m][k], acc[ai][bj][m][n], 0, 0, 0); __builtin_amdgcn_s_setprio(0); } while (0)
; #define PG8_WAIT_L(n) asm volatile("s_waitcnt lgkmcnt(" #n ")" ::: "memory")
; #define PG8_BAR __builtin_amdgcn_s_barrier()
; #define PG8_SCHED __builtin_amdgcn_sched_barrier(0)
; template <class Epi>
; DI void gemm_phase(LAS unsigned char* lds, const Gemm g, const StaticOrder& S, const Epi& E) {
;     ...
;         for (int t = 0; t < nt; t += 2) {
;             const bool last = (t == nt - 2);
;             const char* a1 = cA + (size_t)(t + 1) * kstep;
;             const char* a2 = last ? nA : cA + (size_t)(t + 2) * kstep; const char* b2 = last ? nB : cB + (size_t)(t + 2) * kstep;
;             const char* a3 = a2 + kstep; const char* b3 = b2 + kstep;
;             PG8_LDB(B0, 0, 0); PG8_SCHED; PG8_LDA(At, 0, 0); PG8_STAGE(PG8_SA(1, 1), a1 + hstep);
;             PG8_WAIT_L(8); PG8_BAR; PG8_WAIT_L(0); PG8_MMA(0, 0, At, B0); PG8_BAR; PG8_SCHED;
;             PG8_LDB(B1, 0, 1); PG8_STAGE(PG8_SB(0, 0), b2);
;             PG8_BAR; PG8_WAIT_L(0); PG8_MMA(0, 1, At, B1); PG8_BAR;
;             PG8_LDA(At, 0, 1); PG8_STAGE(PG8_SA(0, 0), a2);
;             PG8_BAR; PG8_WAIT_L(0); PG8_MMA(1, 0, At, B0); PG8_BAR; PG8_SCHED;
.LBB0_231:
	s_add_u32 s18, s16, 0xfff80080
	s_addc_u32 s19, s17, -1
	s_add_i32 s37, 0, 0x10000
	v_add_u32_e32 v150, s37, v135
	ds_read_b128 v[138:141], v150
	ds_read_b128 v[142:145], v150 offset:1024
	ds_read_b128 v[146:149], v150 offset:2048
	ds_read_b128 v[150:153], v150 offset:3072
	s_cmp_eq_u32 s36, 28
	s_cselect_b32 s21, s4, s19
	s_cselect_b32 s20, s5, s18
	s_cselect_b32 s19, s9, s35
	s_cselect_b32 s18, s11, s34
	v_lshl_add_u64 v[154:155], s[16:17], 0, v[130:131]
	s_add_i32 m0, s24, 0xc000
	ds_read_b128 v[186:189], v137
	ds_read_b128 v[190:193], v137 offset:1024
	ds_read_b128 v[194:197], v137 offset:2048
	ds_read_b128 v[198:201], v137 offset:3072
	ds_read_b128 v[202:205], v137 offset:4096
	ds_read_b128 v[206:209], v137 offset:5120
	ds_read_b128 v[210:213], v137 offset:6144
	ds_read_b128 v[214:217], v137 offset:7168
	global_load_lds_dwordx4 v[154:155], off
	v_lshl_add_u64 v[154:155], s[16:17], 0, v[132:133]
	s_add_i32 m0, s24, 0xe000
	s_nop 0
	global_load_lds_dwordx4 v[154:155], off
	s_waitcnt lgkmcnt(8)
	s_setprio 1
	s_barrier
	s_waitcnt lgkmcnt(0)
	v_mfma_f32_16x16x32_bf16 v[124:127], v[138:141], v[186:189], v[124:127]
	v_mfma_f32_16x16x32_bf16 v[120:123], v[146:149], v[186:189], v[120:123]
	v_mfma_f32_16x16x32_bf16 v[116:119], v[138:141], v[194:197], v[116:119]
	v_mfma_f32_16x16x32_bf16 v[112:115], v[146:149], v[194:197], v[112:115]
	v_mfma_f32_16x16x32_bf16 v[100:103], v[138:141], v[202:205], v[100:103]
	v_mfma_f32_16x16x32_bf16 v[96:99], v[146:149], v[202:205], v[96:99]
	v_mfma_f32_16x16x32_bf16 v[84:87], v[138:141], v[210:213], v[84:87]
	v_mfma_f32_16x16x32_bf16 v[80:83], v[146:149], v[210:213], v[80:83]
	v_mfma_f32_16x16x32_bf16 v[124:127], v[142:145], v[190:193], v[124:127]
	v_mfma_f32_16x16x32_bf16 v[120:123], v[150:153], v[190:193], v[120:123]
	v_mfma_f32_16x16x32_bf16 v[116:119], v[142:145], v[198:201], v[116:119]
	v_mfma_f32_16x16x32_bf16 v[112:115], v[150:153], v[198:201], v[112:115]
	v_mfma_f32_16x16x32_bf16 v[100:103], v[142:145], v[206:209], v[100:103]
	v_mfma_f32_16x16x32_bf16 v[96:99], v[150:153], v[206:209], v[96:99]
	v_mfma_f32_16x16x32_bf16 v[84:87], v[142:145], v[214:217], v[84:87]
	v_mfma_f32_16x16x32_bf16 v[80:83], v[150:153], v[214:217], v[80:83]
	s_setprio 0
	s_barrier
	s_add_i32 s40, 0, 0x14000
	v_add_u32_e32 v154, s40, v135
	s_add_i32 s37, s37, s23
	ds_read_b128 v[226:229], v154
	ds_read_b128 v[230:233], v154 offset:1024
	ds_read_b128 v[234:237], v154 offset:2048
	ds_read_b128 v[238:241], v154 offset:3072
	v_lshl_add_u64 v[154:155], s[18:19], 0, v[158:159]
	s_mov_b32 m0, s37
	v_lshl_add_u64 v[218:219], s[18:19], 0, v[128:129]
	global_load_lds_dwordx4 v[154:155], off
	s_add_i32 m0, s37, 0x2000
	s_nop 0
	global_load_lds_dwordx4 v[218:219], off
	s_waitcnt lgkmcnt(0)
	s_setprio 1
	s_barrier
	v_mfma_f32_16x16x32_bf16 v[108:111], v[226:229], v[186:189], v[108:111]
	v_mfma_f32_16x16x32_bf16 v[104:107], v[234:237], v[186:189], v[104:107]
	v_mfma_f32_16x16x32_bf16 v[92:95], v[226:229], v[194:197], v[92:95]
	v_mfma_f32_16x16x32_bf16 v[88:91], v[234:237], v[194:197], v[88:91]
	v_mfma_f32_16x16x32_bf16 v[76:79], v[226:229], v[202:205], v[76:79]
	v_mfma_f32_16x16x32_bf16 v[72:75], v[234:237], v[202:205], v[72:75]
	v_mfma_f32_16x16x32_bf16 v[68:71], v[226:229], v[210:213], v[68:71]
	v_mfma_f32_16x16x32_bf16 v[64:67], v[234:237], v[210:213], v[64:67]
	v_mfma_f32_16x16x32_bf16 v[108:111], v[230:233], v[190:193], v[108:111]
	v_mfma_f32_16x16x32_bf16 v[104:107], v[238:241], v[190:193], v[104:107]
	v_mfma_f32_16x16x32_bf16 v[92:95], v[230:233], v[198:201], v[92:95]
	v_mfma_f32_16x16x32_bf16 v[88:91], v[238:241], v[198:201], v[88:91]
	v_mfma_f32_16x16x32_bf16 v[76:79], v[230:233], v[206:209], v[76:79]
	v_mfma_f32_16x16x32_bf16 v[72:75], v[238:241], v[206:209], v[72:75]
	v_mfma_f32_16x16x32_bf16 v[68:71], v[230:233], v[214:217], v[68:71]
	v_mfma_f32_16x16x32_bf16 v[64:67], v[238:241], v[214:217], v[64:67]
	s_setprio 0
	s_mov_b32 m0, s24
	v_lshl_add_u64 v[242:243], s[20:21], 0, v[158:159]
	s_barrier
	ds_read_b128 v[186:189], v137 offset:16384
	ds_read_b128 v[190:193], v137 offset:17408
	ds_read_b128 v[194:197], v137 offset:18432
	ds_read_b128 v[198:201], v137 offset:19456
	ds_read_b128 v[202:205], v137 offset:20480
	ds_read_b128 v[206:209], v137 offset:21504
	ds_read_b128 v[210:213], v137 offset:22528
	ds_read_b128 v[214:217], v137 offset:23552
	global_load_lds_dwordx4 v[242:243], off
	v_lshl_add_u64 v[244:245], s[20:21], 0, v[128:129]
	s_mov_b32 m0, s25
	s_nop 0
	global_load_lds_dwordx4 v[244:245], off
	s_waitcnt lgkmcnt(0)
	s_setprio 1
	s_barrier
	v_mfma_f32_16x16x32_bf16 v[60:63], v[138:141], v[186:189], v[60:63]
	v_mfma_f32_16x16x32_bf16 v[56:59], v[146:149], v[186:189], v[56:59]
	v_mfma_f32_16x16x32_bf16 v[52:55], v[138:141], v[194:197], v[52:55]
	v_mfma_f32_16x16x32_bf16 v[48:51], v[146:149], v[194:197], v[48:51]
	v_mfma_f32_16x16x32_bf16 v[36:39], v[138:141], v[202:205], v[36:39]
	v_mfma_f32_16x16x32_bf16 v[32:35], v[146:149], v[202:205], v[32:35]
	v_mfma_f32_16x16x32_bf16 v[20:23], v[138:141], v[210:213], v[20:23]
	v_mfma_f32_16x16x32_bf16 v[16:19], v[146:149], v[210:213], v[16:19]
	v_mfma_f32_16x16x32_bf16 v[60:63], v[142:145], v[190:193], v[60:63]
	v_mfma_f32_16x16x32_bf16 v[56:59], v[150:153], v[190:193], v[56:59]
	v_mfma_f32_16x16x32_bf16 v[52:55], v[142:145], v[198:201], v[52:55]
	v_mfma_f32_16x16x32_bf16 v[48:51], v[150:153], v[198:201], v[48:51]
	v_mfma_f32_16x16x32_bf16 v[36:39], v[142:145], v[206:209], v[36:39]
	v_mfma_f32_16x16x32_bf16 v[32:35], v[150:153], v[206:209], v[32:35]
	v_mfma_f32_16x16x32_bf16 v[20:23], v[142:145], v[214:217], v[20:23]
	v_mfma_f32_16x16x32_bf16 v[16:19], v[150:153], v[214:217], v[16:19]
	s_setprio 0
	s_barrier
; #define PG8_STAGE(bufoff, gbase) do { _Pragma("unroll") for (int _i = 0; _i < 2; ++_i) \
;         __builtin_amdgcn_global_load_lds((const unsigned*)((const char*)(gbase) + voff[_i]), (LAS unsigned*)(lds + (bufoff) + ldsw + _i * 8192), 16, 0, 0); } while (0)
; #define PG8_LDA(dst, b, h) do { _Pragma("unroll") for (int m = 0; m < 4; ++m) _Pragma("unroll") for (int k = 0; k < 2; ++k) dst[m][k] = *(const LAS bf16x8*)(lds + PG8_SA(b, h) + aoff + m * 2048 + k * 1024); } while (0)
; #define PG8_LDB(dst, b, h) do { _Pragma("unroll") for (int n = 0; n < 2; ++n) _Pragma("unroll") for (int k = 0; k < 2; ++k) dst[n][k] = *(const LAS bf16x8*)(lds + PG8_SB(b, h) + boff + n * 2048 + k * 1024); } while (0)
; #define PG8_MMA(ai, bj, At, Bt) do { __builtin_amdgcn_s_setprio(1); _Pragma("unroll") for (int m = 0; m < 4; ++m) _Pragma("unroll") for (int n = 0; n < 2; ++n) _Pragma("unroll") for (int k = 0; k < 2; ++k) \
;         acc[ai][bj][m][n] = __builtin_amdgcn_mfma_f32_16x16x32_bf16(Bt[n][k], At[m][k], acc[ai][bj][m][n], 0, 0, 0); __builtin_amdgcn_s_setprio(0); } while (0)
; #define PG8_WAIT_V(n) asm volatile("s_waitcnt vmcnt(" #n ")" ::: "memory")
; #define PG8_WAIT_L(n) asm volatile("s_waitcnt lgkmcnt(" #n ")" ::: "memory")
; #define PG8_BAR __builtin_amdgcn_s_barrier()
; #define PG8_SCHED __builtin_amdgcn_sched_barrier(0)
; template <class Epi>
; DI void gemm_phase(LAS unsigned char* lds, const Gemm g, const StaticOrder& S, const Epi& E) {
;     ...
;             PG8_BAR; PG8_WAIT_L(0); PG8_MMA(1, 0, At, B0); PG8_BAR; PG8_SCHED;
;             PG8_STAGE(PG8_SB(0, 1), b2 + hstep);
;             PG8_WAIT_V(6); PG8_BAR; PG8_MMA(1, 1, At, B1); PG8_BAR;
;             PG8_LDB(B0, 1, 0); PG8_SCHED; PG8_LDA(At, 1, 0); PG8_STAGE(PG8_SA(0, 1), a2 + hstep);
;             PG8_WAIT_L(8); PG8_BAR; PG8_WAIT_L(0); PG8_MMA(0, 0, At, B0); PG8_BAR; PG8_SCHED;
;             PG8_LDB(B1, 1, 1); PG8_STAGE(PG8_SB(1, 0), b3);
;             PG8_BAR; PG8_WAIT_L(0); PG8_MMA(0, 1, At, B1); PG8_BAR;
;             PG8_LDA(At, 1, 1); PG8_STAGE(PG8_SA(1, 0), a3);
;             PG8_BAR; PG8_WAIT_L(0); PG8_MMA(1, 0, At, B0); PG8_BAR; PG8_SCHED;
	s_add_u32 s38, s18, 0x80000
	s_addc_u32 s39, s19, 0
	s_add_i32 s37, s40, s23
	v_lshl_add_u64 v[138:139], s[38:39], 0, v[158:159]
	s_mov_b32 m0, s37
	s_nop 0
	global_load_lds_dwordx4 v[138:139], off
	v_lshl_add_u64 v[138:139], s[38:39], 0, v[128:129]
	s_add_i32 m0, s37, 0x2000
	s_nop 0
	global_load_lds_dwordx4 v[138:139], off
	s_waitcnt vmcnt(6)
	s_setprio 1
	s_barrier
	v_mfma_f32_16x16x32_bf16 v[44:47], v[226:229], v[186:189], v[44:47]
	v_mfma_f32_16x16x32_bf16 v[40:43], v[234:237], v[186:189], v[40:43]
	v_mfma_f32_16x16x32_bf16 v[28:31], v[226:229], v[194:197], v[28:31]
	v_mfma_f32_16x16x32_bf16 v[24:27], v[234:237], v[194:197], v[24:27]
	v_mfma_f32_16x16x32_bf16 v[12:15], v[226:229], v[202:205], v[12:15]
	v_mfma_f32_16x16x32_bf16 v[8:11], v[234:237], v[202:205], v[8:11]
	v_mfma_f32_16x16x32_bf16 v[4:7], v[226:229], v[210:213], v[4:7]
	v_mfma_f32_16x16x32_bf16 v[0:3], v[234:237], v[210:213], v[0:3]
	v_mfma_f32_16x16x32_bf16 v[44:47], v[230:233], v[190:193], v[44:47]
	v_mfma_f32_16x16x32_bf16 v[40:43], v[238:241], v[190:193], v[40:43]
	v_mfma_f32_16x16x32_bf16 v[28:31], v[230:233], v[198:201], v[28:31]
	v_mfma_f32_16x16x32_bf16 v[24:27], v[238:241], v[198:201], v[24:27]
	v_mfma_f32_16x16x32_bf16 v[12:15], v[230:233], v[206:209], v[12:15]
	v_mfma_f32_16x16x32_bf16 v[8:11], v[238:241], v[206:209], v[8:11]
	v_mfma_f32_16x16x32_bf16 v[4:7], v[230:233], v[214:217], v[4:7]
	v_mfma_f32_16x16x32_bf16 v[0:3], v[238:241], v[214:217], v[0:3]
	s_setprio 0
	s_add_i32 s37, 0, 0x18000
	v_add_u32_e32 v150, s37, v135
	s_barrier
	ds_read_b128 v[138:141], v150
	ds_read_b128 v[142:145], v150 offset:1024
	ds_read_b128 v[146:149], v150 offset:2048
	ds_read_b128 v[150:153], v150 offset:3072
	s_add_u32 s20, s20, 0x80000
	s_addc_u32 s21, s21, 0
	s_mov_b32 m0, s26
	v_lshl_add_u64 v[226:227], s[20:21], 0, v[158:159]
	ds_read_b128 v[186:189], v137 offset:32768
	ds_read_b128 v[190:193], v137 offset:33792
	ds_read_b128 v[194:197], v137 offset:34816
	ds_read_b128 v[198:201], v137 offset:35840
	ds_read_b128 v[202:205], v137 offset:36864
	ds_read_b128 v[206:209], v137 offset:37888
	ds_read_b128 v[210:213], v137 offset:38912
	ds_read_b128 v[214:217], v137 offset:39936
	global_load_lds_dwordx4 v[226:227], off
	v_lshl_add_u64 v[226:227], s[20:21], 0, v[128:129]
	s_mov_b32 m0, s27
	s_nop 0
	global_load_lds_dwordx4 v[226:227], off
	s_waitcnt lgkmcnt(8)
	s_setprio 1
	s_barrier
	s_waitcnt lgkmcnt(0)
	v_mfma_f32_16x16x32_bf16 v[124:127], v[138:141], v[186:189], v[124:127]
	v_mfma_f32_16x16x32_bf16 v[120:123], v[146:149], v[186:189], v[120:123]
	v_mfma_f32_16x16x32_bf16 v[116:119], v[138:141], v[194:197], v[116:119]
	v_mfma_f32_16x16x32_bf16 v[112:115], v[146:149], v[194:197], v[112:115]
	v_mfma_f32_16x16x32_bf16 v[100:103], v[138:141], v[202:205], v[100:103]
	v_mfma_f32_16x16x32_bf16 v[96:99], v[146:149], v[202:205], v[96:99]
	v_mfma_f32_16x16x32_bf16 v[84:87], v[138:141], v[210:213], v[84:87]
	v_mfma_f32_16x16x32_bf16 v[80:83], v[146:149], v[210:213], v[80:83]
	v_mfma_f32_16x16x32_bf16 v[124:127], v[142:145], v[190:193], v[124:127]
	v_mfma_f32_16x16x32_bf16 v[120:123], v[150:153], v[190:193], v[120:123]
	v_mfma_f32_16x16x32_bf16 v[116:119], v[142:145], v[198:201], v[116:119]
	v_mfma_f32_16x16x32_bf16 v[112:115], v[150:153], v[198:201], v[112:115]
	v_mfma_f32_16x16x32_bf16 v[100:103], v[142:145], v[206:209], v[100:103]
	v_mfma_f32_16x16x32_bf16 v[96:99], v[150:153], v[206:209], v[96:99]
	v_mfma_f32_16x16x32_bf16 v[84:87], v[142:145], v[214:217], v[84:87]
	v_mfma_f32_16x16x32_bf16 v[80:83], v[150:153], v[214:217], v[80:83]
	s_setprio 0
	s_barrier
	s_add_i32 s20, 0, 0x1c000
	s_add_i32 s21, s37, s23
	v_add_u32_e32 v220, s20, v135
	v_lshl_add_u64 v[154:155], v[154:155], 0, s[94:95]
	s_mov_b32 m0, s21
	ds_read_b128 v[226:229], v220
	ds_read_b128 v[230:233], v220 offset:1024
	ds_read_b128 v[234:237], v220 offset:2048
	ds_read_b128 v[238:241], v220 offset:3072
	global_load_lds_dwordx4 v[154:155], off
	v_lshl_add_u64 v[154:155], v[218:219], 0, s[94:95]
	s_add_i32 m0, s21, 0x2000
	s_nop 0
	global_load_lds_dwordx4 v[154:155], off
	s_waitcnt lgkmcnt(0)
	s_setprio 1
	s_barrier
	v_mfma_f32_16x16x32_bf16 v[108:111], v[226:229], v[186:189], v[108:111]
	v_mfma_f32_16x16x32_bf16 v[104:107], v[234:237], v[186:189], v[104:107]
	v_mfma_f32_16x16x32_bf16 v[92:95], v[226:229], v[194:197], v[92:95]
	v_mfma_f32_16x16x32_bf16 v[88:91], v[234:237], v[194:197], v[88:91]
	v_mfma_f32_16x16x32_bf16 v[76:79], v[226:229], v[202:205], v[76:79]
	v_mfma_f32_16x16x32_bf16 v[72:75], v[234:237], v[202:205], v[72:75]
	v_mfma_f32_16x16x32_bf16 v[68:71], v[226:229], v[210:213], v[68:71]
	v_mfma_f32_16x16x32_bf16 v[64:67], v[234:237], v[210:213], v[64:67]
	v_mfma_f32_16x16x32_bf16 v[108:111], v[230:233], v[190:193], v[108:111]
	v_mfma_f32_16x16x32_bf16 v[104:107], v[238:241], v[190:193], v[104:107]
	v_mfma_f32_16x16x32_bf16 v[92:95], v[230:233], v[198:201], v[92:95]
	v_mfma_f32_16x16x32_bf16 v[88:91], v[238:241], v[198:201], v[88:91]
	v_mfma_f32_16x16x32_bf16 v[76:79], v[230:233], v[206:209], v[76:79]
	v_mfma_f32_16x16x32_bf16 v[72:75], v[238:241], v[206:209], v[72:75]
	v_mfma_f32_16x16x32_bf16 v[68:71], v[230:233], v[214:217], v[68:71]
	v_mfma_f32_16x16x32_bf16 v[64:67], v[238:241], v[214:217], v[64:67]
	s_setprio 0
	s_mov_b32 m0, s28
	v_lshl_add_u64 v[154:155], v[242:243], 0, s[94:95]
	s_barrier
	ds_read_b128 v[186:189], v137 offset:49152
	ds_read_b128 v[190:193], v137 offset:50176
	ds_read_b128 v[194:197], v137 offset:51200
	ds_read_b128 v[198:201], v137 offset:52224
	ds_read_b128 v[202:205], v137 offset:53248
	ds_read_b128 v[206:209], v137 offset:54272
	ds_read_b128 v[210:213], v137 offset:55296
	ds_read_b128 v[214:217], v137 offset:56320
	global_load_lds_dwordx4 v[154:155], off
	v_lshl_add_u64 v[154:155], v[244:245], 0, s[94:95]
	s_mov_b32 m0, s29
	s_nop 0
	global_load_lds_dwordx4 v[154:155], off
	s_waitcnt lgkmcnt(0)
	s_setprio 1
	s_barrier
; #define PG8_STAGE(bufoff, gbase) do { _Pragma("unroll") for (int _i = 0; _i < 2; ++_i) \
;         __builtin_amdgcn_global_load_lds((const unsigned*)((const char*)(gbase) + voff[_i]), (LAS unsigned*)(lds + (bufoff) + ldsw + _i * 8192), 16, 0, 0); } while (0)
; #define PG8_MMA(ai, bj, At, Bt) do { __builtin_amdgcn_s_setprio(1); _Pragma("unroll") for (int m = 0; m < 4; ++m) _Pragma("unroll") for (int n = 0; n < 2; ++n) _Pragma("unroll") for (int k = 0; k < 2; ++k) \
;         acc[ai][bj][m][n] = __builtin_amdgcn_mfma_f32_16x16x32_bf16(Bt[n][k], At[m][k], acc[ai][bj][m][n], 0, 0, 0); __builtin_amdgcn_s_setprio(0); } while (0)
; #define PG8_WAIT_V(n) asm volatile("s_waitcnt vmcnt(" #n ")" ::: "memory")
; #define PG8_WAIT_L(n) asm volatile("s_waitcnt lgkmcnt(" #n ")" ::: "memory")
; #define PG8_BAR __builtin_amdgcn_s_barrier()
; #define PG8_SCHED __builtin_amdgcn_sched_barrier(0)
; template <class Epi>
; DI void gemm_phase(LAS unsigned char* lds, const Gemm g, const StaticOrder& S, const Epi& E) {
;     ...
;             PG8_BAR; PG8_WAIT_L(0); PG8_MMA(1, 0, At, B0); PG8_BAR; PG8_SCHED;
;             PG8_STAGE(PG8_SB(1, 1), b3 + hstep);
;             PG8_WAIT_V(6); PG8_BAR; PG8_MMA(1, 1, At, B1); PG8_BAR;
	v_mfma_f32_16x16x32_bf16 v[60:63], v[138:141], v[186:189], v[60:63]
	v_mfma_f32_16x16x32_bf16 v[56:59], v[146:149], v[186:189], v[56:59]
	v_mfma_f32_16x16x32_bf16 v[52:55], v[138:141], v[194:197], v[52:55]
	v_mfma_f32_16x16x32_bf16 v[48:51], v[146:149], v[194:197], v[48:51]
	v_mfma_f32_16x16x32_bf16 v[36:39], v[138:141], v[202:205], v[36:39]
	v_mfma_f32_16x16x32_bf16 v[32:35], v[146:149], v[202:205], v[32:35]
	v_mfma_f32_16x16x32_bf16 v[20:23], v[138:141], v[210:213], v[20:23]
	v_mfma_f32_16x16x32_bf16 v[16:19], v[146:149], v[210:213], v[16:19]
	v_mfma_f32_16x16x32_bf16 v[60:63], v[142:145], v[190:193], v[60:63]
	v_mfma_f32_16x16x32_bf16 v[56:59], v[150:153], v[190:193], v[56:59]
	v_mfma_f32_16x16x32_bf16 v[52:55], v[142:145], v[198:201], v[52:55]
	v_mfma_f32_16x16x32_bf16 v[48:51], v[150:153], v[198:201], v[48:51]
	v_mfma_f32_16x16x32_bf16 v[36:39], v[142:145], v[206:209], v[36:39]
	v_mfma_f32_16x16x32_bf16 v[32:35], v[150:153], v[206:209], v[32:35]
	v_mfma_f32_16x16x32_bf16 v[20:23], v[142:145], v[214:217], v[20:23]
	v_mfma_f32_16x16x32_bf16 v[16:19], v[150:153], v[214:217], v[16:19]
	s_setprio 0
	s_barrier
	s_add_u32 s18, s18, 0x80080
	s_addc_u32 s19, s19, 0
	s_add_i32 s20, s20, s23
	v_lshl_add_u64 v[138:139], s[18:19], 0, v[158:159]
	s_mov_b32 m0, s20
	s_nop 0
	global_load_lds_dwordx4 v[138:139], off
	v_lshl_add_u64 v[138:139], s[18:19], 0, v[128:129]
	s_add_i32 m0, s20, 0x2000
	s_nop 0
	global_load_lds_dwordx4 v[138:139], off
	s_waitcnt vmcnt(6)
	s_setprio 1
	s_barrier
	v_mfma_f32_16x16x32_bf16 v[44:47], v[226:229], v[186:189], v[44:47]
	v_mfma_f32_16x16x32_bf16 v[40:43], v[234:237], v[186:189], v[40:43]
	v_mfma_f32_16x16x32_bf16 v[28:31], v[226:229], v[194:197], v[28:31]
	v_mfma_f32_16x16x32_bf16 v[24:27], v[234:237], v[194:197], v[24:27]
	v_mfma_f32_16x16x32_bf16 v[12:15], v[226:229], v[202:205], v[12:15]
	v_mfma_f32_16x16x32_bf16 v[8:11], v[234:237], v[202:205], v[8:11]
	v_mfma_f32_16x16x32_bf16 v[4:7], v[226:229], v[210:213], v[4:7]
	v_mfma_f32_16x16x32_bf16 v[0:3], v[234:237], v[210:213], v[0:3]
	v_mfma_f32_16x16x32_bf16 v[44:47], v[230:233], v[190:193], v[44:47]
	v_mfma_f32_16x16x32_bf16 v[40:43], v[238:241], v[190:193], v[40:43]
	v_mfma_f32_16x16x32_bf16 v[28:31], v[230:233], v[198:201], v[28:31]
	v_mfma_f32_16x16x32_bf16 v[24:27], v[238:241], v[198:201], v[24:27]
	v_mfma_f32_16x16x32_bf16 v[12:15], v[230:233], v[206:209], v[12:15]
	v_mfma_f32_16x16x32_bf16 v[8:11], v[238:241], v[206:209], v[8:11]
	v_mfma_f32_16x16x32_bf16 v[4:7], v[230:233], v[214:217], v[4:7]
	v_mfma_f32_16x16x32_bf16 v[0:3], v[238:241], v[214:217], v[0:3]
	s_setprio 0
	s_add_i32 s36, s36, 2
	s_add_u32 s16, s16, 0x100
	s_addc_u32 s17, s17, 0
	s_add_u32 s34, s34, 0x100
	s_addc_u32 s35, s35, 0
	s_cmp_gt_u32 s36, 29
	s_barrier
	s_cbranch_scc0 .LBB0_231
;     DI void operator()(const f32x4 (&acc)[2][2][4][2], const Unit& u, int wr, int wc, int fr, int fq) const {
;         const int row0 = u.pm * BM + wr * 64 + fr, col0 = u.pn * BM + wc * 32 + 8 * fq;
; #pragma unroll
;         for (int ai = 0; ai < 2; ++ai)
; #pragma unroll
;             for (int m = 0; m < 4; ++m) { u16* rowp = O + (size_t)(row0 + ai * HALF + m * 16) * ldc + col0;
; #pragma unroll
;                 for (int bj = 0; bj < 2; ++bj) { const f32x4 v0 = acc[ai][bj][m][0], v1 = acc[ai][bj][m][1];
;                     *(u32x4*)(rowp + bj * HALF) = (u32x4){pk(v0[0], v0[1]), pk(v0[2], v0[3]), pk(v1[0], v1[1]), pk(v1[2], v1[3])}; } }
;     }
	v_lshl_add_u32 v144, s33, 8, v134
	v_lshl_or_b32 v138, s31, 8, v136
	v_ashrrev_i32_e32 v139, 31, v138
	v_mov_b64_e32 v[140:141], s[50:51]
	s_movk_i32 s9, 0x3000
	v_cvt_pk_bf16_f32 v68, v68, v69
	v_cvt_pk_bf16_f32 v69, v70, v71
	v_cvt_pk_bf16_f32 v70, v64, v65
	v_add_u32_e32 v64, 0x80, v144
	v_mad_i64_i32 v[142:143], s[4:5], v144, s9, v[140:141]
	v_lshlrev_b64 v[138:139], 1, v[138:139]
	v_cvt_pk_bf16_f32 v108, v108, v109
	v_cvt_pk_bf16_f32 v109, v110, v111
	v_cvt_pk_bf16_f32 v110, v104, v105
	v_or_b32_e32 v104, 16, v144
	v_mad_i64_i32 v[64:65], s[4:5], v64, s9, v[140:141]
	v_cvt_pk_bf16_f32 v44, v44, v45
	v_cvt_pk_bf16_f32 v45, v46, v47
	v_cvt_pk_bf16_f32 v46, v40, v41
	v_add_u32_e32 v40, 0x90, v144
	v_lshl_add_u64 v[142:143], v[142:143], 0, v[138:139]
	v_cvt_pk_bf16_f32 v111, v106, v107
	v_mad_i64_i32 v[104:105], s[4:5], v104, s9, v[140:141]
	v_cvt_pk_bf16_f32 v92, v92, v93
	v_cvt_pk_bf16_f32 v93, v94, v95
	v_cvt_pk_bf16_f32 v94, v88, v89
	v_or_b32_e32 v88, 32, v144
	v_lshl_add_u64 v[64:65], v[64:65], 0, v[138:139]
	v_cvt_pk_bf16_f32 v47, v42, v43
	v_mad_i64_i32 v[40:41], s[4:5], v40, s9, v[140:141]
	v_cvt_pk_bf16_f32 v28, v28, v29
	v_cvt_pk_bf16_f32 v29, v30, v31
	v_cvt_pk_bf16_f32 v30, v24, v25
	v_add_u32_e32 v24, 0xa0, v144
	global_store_dwordx4 v[142:143], v[108:111], off offset:256
	v_cvt_pk_bf16_f32 v95, v90, v91
	v_mad_i64_i32 v[88:89], s[4:5], v88, s9, v[140:141]
	v_lshl_add_u64 v[108:109], v[104:105], 0, v[138:139]
	v_cvt_pk_bf16_f32 v76, v76, v77
	v_cvt_pk_bf16_f32 v77, v78, v79
	v_cvt_pk_bf16_f32 v78, v72, v73
	v_or_b32_e32 v72, 48, v144
	global_store_dwordx4 v[64:65], v[44:47], off offset:256
	v_cvt_pk_bf16_f32 v31, v26, v27
	v_mad_i64_i32 v[24:25], s[4:5], v24, s9, v[140:141]
	v_lshl_add_u64 v[44:45], v[40:41], 0, v[138:139]
	v_cvt_pk_bf16_f32 v12, v12, v13
	v_cvt_pk_bf16_f32 v13, v14, v15
	v_cvt_pk_bf16_f32 v14, v8, v9
	v_add_u32_e32 v8, 0xb0, v144
	global_store_dwordx4 v[108:109], v[92:95], off offset:256
	v_cvt_pk_bf16_f32 v79, v74, v75
	v_mad_i64_i32 v[72:73], s[4:5], v72, s9, v[140:141]
	v_lshl_add_u64 v[92:93], v[88:89], 0, v[138:139]
	global_store_dwordx4 v[44:45], v[28:31], off offset:256
	v_cvt_pk_bf16_f32 v15, v10, v11
	v_mad_i64_i32 v[8:9], s[4:5], v8, s9, v[140:141]
	v_lshl_add_u64 v[28:29], v[24:25], 0, v[138:139]
	v_cvt_pk_bf16_f32 v124, v124, v125
	v_cvt_pk_bf16_f32 v125, v126, v127
	v_cvt_pk_bf16_f32 v126, v120, v121
	v_cvt_pk_bf16_f32 v127, v122, v123
	v_cvt_pk_bf16_f32 v104, v116, v117
	v_cvt_pk_bf16_f32 v105, v118, v119
	v_cvt_pk_bf16_f32 v106, v112, v113
	v_cvt_pk_bf16_f32 v107, v114, v115
	v_cvt_pk_bf16_f32 v88, v100, v101
	v_cvt_pk_bf16_f32 v89, v102, v103
	v_cvt_pk_bf16_f32 v90, v96, v97
	v_cvt_pk_bf16_f32 v91, v98, v99
	global_store_dwordx4 v[92:93], v[76:79], off offset:256
	v_cvt_pk_bf16_f32 v74, v80, v81
	v_cvt_pk_bf16_f32 v75, v82, v83
	v_lshl_add_u64 v[76:77], v[72:73], 0, v[138:139]
	v_cvt_pk_bf16_f32 v72, v84, v85
	v_cvt_pk_bf16_f32 v73, v86, v87
	v_cvt_pk_bf16_f32 v71, v66, v67
	v_cvt_pk_bf16_f32 v60, v60, v61
	v_cvt_pk_bf16_f32 v61, v62, v63
	v_cvt_pk_bf16_f32 v62, v56, v57
	v_cvt_pk_bf16_f32 v63, v58, v59
	v_cvt_pk_bf16_f32 v40, v52, v53
	v_cvt_pk_bf16_f32 v41, v54, v55
	v_cvt_pk_bf16_f32 v42, v48, v49
	v_cvt_pk_bf16_f32 v43, v50, v51
	v_cvt_pk_bf16_f32 v24, v36, v37
	v_cvt_pk_bf16_f32 v25, v38, v39
	v_cvt_pk_bf16_f32 v26, v32, v33
	v_cvt_pk_bf16_f32 v27, v34, v35
	global_store_dwordx4 v[28:29], v[12:15], off offset:256
	v_cvt_pk_bf16_f32 v10, v16, v17
	v_cvt_pk_bf16_f32 v11, v18, v19
	v_lshl_add_u64 v[12:13], v[8:9], 0, v[138:139]
	v_cvt_pk_bf16_f32 v8, v20, v21
	v_cvt_pk_bf16_f32 v9, v22, v23
	v_cvt_pk_bf16_f32 v4, v4, v5
	v_cvt_pk_bf16_f32 v5, v6, v7
	v_cvt_pk_bf16_f32 v6, v0, v1
	v_cvt_pk_bf16_f32 v7, v2, v3
	s_and_b64 vcc, exec, s[6:7]
	s_mov_b32 s31, s8
	s_mov_b32 s33, s10
	s_mov_b64 s[18:19], s[14:15]
	s_mov_b64 s[16:17], s[12:13]
	global_store_dwordx4 v[142:143], v[124:127], off
	global_store_dwordx4 v[108:109], v[104:107], off
	global_store_dwordx4 v[92:93], v[88:91], off
	global_store_dwordx4 v[76:77], v[72:75], off
	global_store_dwordx4 v[76:77], v[68:71], off offset:256
	global_store_dwordx4 v[64:65], v[60:63], off
	global_store_dwordx4 v[44:45], v[40:43], off
	global_store_dwordx4 v[28:29], v[24:27], off
	global_store_dwordx4 v[12:13], v[8:11], off
	global_store_dwordx4 v[12:13], v[4:7], off offset:256
	s_cbranch_vccz .LBB0_228
	s_waitcnt vmcnt(0)
	s_cmpk_gt_u32 s2, 0xff
	s_cbranch_scc1 .LBB0_235
	s_barrier

; #define PG8_STAGE(bufoff, gbase) do { _Pragma("unroll") for (int _i = 0; _i < 2; ++_i) \
;         __builtin_amdgcn_global_load_lds((const unsigned*)((const char*)(gbase) + voff[_i]), (LAS unsigned*)(lds + (bufoff) + ldsw + _i * 8192), 16, 0, 0); } while (0)
; #define PG8_LDA(dst, b, h) do { _Pragma("unroll") for (int m = 0; m < 4; ++m) _Pragma("unroll") for (int k = 0; k < 2; ++k) dst[m][k] = *(const LAS bf16x8*)(lds + PG8_SA(b, h) + aoff + m * 2048 + k * 1024); } while (0)
; #define PG8_LDB(dst, b, h) do { _Pragma("unroll") for (int n = 0; n < 2; ++n) _Pragma("unroll") for (int k = 0; k < 2; ++k) dst[n][k] = *(const LAS bf16x8*)(lds + PG8_SB(b, h) + boff + n * 2048 + k * 1024); } while (0)
; #define PG8_MMA(ai, bj, At, Bt) do { __builtin_amdgcn_s_setprio(1); _Pragma("unroll") for (int m = 0; m < 4; ++m) _Pragma("unroll") for (int n = 0; n < 2; ++n) _Pragma("unroll") for (int k = 0; k < 2; ++k) \
;         acc[ai][bj][m][n] = __builtin_amdgcn_mfma_f32_16x16x32_bf16(Bt[n][k], At[m][k], acc[ai][bj][m][n], 0, 0, 0); __builtin_amdgcn_s_setprio(0); } while (0)
; #define PG8_WAIT_L(n) asm volatile("s_waitcnt lgkmcnt(" #n ")" ::: "memory")
; #define PG8_BAR __builtin_amdgcn_s_barrier()
; #define PG8_SCHED __builtin_amdgcn_sched_barrier(0)
; template <class Epi>
; DI void gemm_phase(LAS unsigned char* lds, const Gemm g, const StaticOrder& S, const Epi& E) {
;     ...
;         for (int t = 0; t < nt; t += 2) {
;             const bool last = (t == nt - 2);
;             const char* a1 = cA + (size_t)(t + 1) * kstep;
;             const char* a2 = last ? nA : cA + (size_t)(t + 2) * kstep; const char* b2 = last ? nB : cB + (size_t)(t + 2) * kstep;
;             const char* a3 = a2 + kstep; const char* b3 = b2 + kstep;
;             PG8_LDB(B0, 0, 0); PG8_SCHED; PG8_LDA(At, 0, 0); PG8_STAGE(PG8_SA(1, 1), a1 + hstep);
;             PG8_WAIT_L(8); PG8_BAR; PG8_WAIT_L(0); PG8_MMA(0, 0, At, B0); PG8_BAR; PG8_SCHED;
;             PG8_LDB(B1, 0, 1); PG8_STAGE(PG8_SB(0, 0), b2);
;             PG8_BAR; PG8_WAIT_L(0); PG8_MMA(0, 1, At, B1); PG8_BAR;
;             PG8_LDA(At, 0, 1); PG8_STAGE(PG8_SA(0, 0), a2);
;             PG8_BAR; PG8_WAIT_L(0); PG8_MMA(1, 0, At, B0); PG8_BAR; PG8_SCHED;
.LBB0_320:
	s_add_u32 s26, s24, 0x100
	s_addc_u32 s27, s25, 0
	s_add_i32 s47, 0, 0x10000
	v_add_u32_e32 v140, s47, v226
	ds_read_b128 v[128:131], v140
	ds_read_b128 v[132:135], v140 offset:1024
	ds_read_b128 v[136:139], v140 offset:2048
	ds_read_b128 v[140:143], v140 offset:3072
	s_cmp_eq_u32 s46, 28
	s_cselect_b32 s31, s4, s27
	s_cselect_b32 s30, s5, s26
	s_cselect_b32 s29, s9, s45
	s_cselect_b32 s28, s11, s33
	v_lshl_add_u64 v[214:215], s[24:25], 0, v[190:191]
	s_add_i32 m0, s38, 0xc000
	ds_read_b128 v[144:147], v228
	ds_read_b128 v[148:151], v228 offset:1024
	ds_read_b128 v[152:155], v228 offset:2048
	ds_read_b128 v[194:197], v228 offset:3072
	ds_read_b128 v[198:201], v228 offset:4096
	ds_read_b128 v[202:205], v228 offset:5120
	ds_read_b128 v[206:209], v228 offset:6144
	ds_read_b128 v[210:213], v228 offset:7168
	global_load_lds_dwordx4 v[214:215], off
	v_lshl_add_u64 v[214:215], s[24:25], 0, v[192:193]
	s_add_i32 m0, s38, 0xe000
	s_nop 0
	global_load_lds_dwordx4 v[214:215], off
	s_waitcnt lgkmcnt(8)
	s_setprio 1
	s_barrier
	s_waitcnt lgkmcnt(0)
	v_mfma_f32_16x16x32_bf16 v[124:127], v[128:131], v[144:147], v[124:127]
	v_mfma_f32_16x16x32_bf16 v[120:123], v[136:139], v[144:147], v[120:123]
	v_mfma_f32_16x16x32_bf16 v[116:119], v[128:131], v[152:155], v[116:119]
	v_mfma_f32_16x16x32_bf16 v[112:115], v[136:139], v[152:155], v[112:115]
	v_mfma_f32_16x16x32_bf16 v[108:111], v[128:131], v[198:201], v[108:111]
	v_mfma_f32_16x16x32_bf16 v[104:107], v[136:139], v[198:201], v[104:107]
	v_mfma_f32_16x16x32_bf16 v[100:103], v[128:131], v[206:209], v[100:103]
	v_mfma_f32_16x16x32_bf16 v[96:99], v[136:139], v[206:209], v[96:99]
	v_mfma_f32_16x16x32_bf16 v[124:127], v[132:135], v[148:151], v[124:127]
	v_mfma_f32_16x16x32_bf16 v[120:123], v[140:143], v[148:151], v[120:123]
	v_mfma_f32_16x16x32_bf16 v[116:119], v[132:135], v[194:197], v[116:119]
	v_mfma_f32_16x16x32_bf16 v[112:115], v[140:143], v[194:197], v[112:115]
	v_mfma_f32_16x16x32_bf16 v[108:111], v[132:135], v[202:205], v[108:111]
	v_mfma_f32_16x16x32_bf16 v[104:107], v[140:143], v[202:205], v[104:107]
	v_mfma_f32_16x16x32_bf16 v[100:103], v[132:135], v[210:213], v[100:103]
	v_mfma_f32_16x16x32_bf16 v[96:99], v[140:143], v[210:213], v[96:99]
	s_setprio 0
	s_barrier
	s_add_i32 s48, 0, 0x14000
	s_add_i32 s24, s47, s37
	v_add_u32_e32 v158, s48, v226
	v_lshl_add_u64 v[218:219], s[28:29], 0, v[188:189]
	s_mov_b32 m0, s24
	ds_read_b128 v[214:217], v158
	ds_read_b128 v[230:233], v158 offset:1024
	ds_read_b128 v[234:237], v158 offset:2048
	ds_read_b128 v[238:241], v158 offset:3072
	global_load_lds_dwordx4 v[218:219], off
	v_lshl_add_u64 v[220:221], s[28:29], 0, v[186:187]
	s_add_i32 m0, s24, 0x2000
	s_nop 0
	global_load_lds_dwordx4 v[220:221], off
	s_waitcnt lgkmcnt(0)
	s_setprio 1
	s_barrier
	v_mfma_f32_16x16x32_bf16 v[60:63], v[214:217], v[144:147], v[60:63]
	v_mfma_f32_16x16x32_bf16 v[56:59], v[234:237], v[144:147], v[56:59]
	v_mfma_f32_16x16x32_bf16 v[52:55], v[214:217], v[152:155], v[52:55]
	v_mfma_f32_16x16x32_bf16 v[48:51], v[234:237], v[152:155], v[48:51]
	v_mfma_f32_16x16x32_bf16 v[44:47], v[214:217], v[198:201], v[44:47]
	v_mfma_f32_16x16x32_bf16 v[40:43], v[234:237], v[198:201], v[40:43]
	v_mfma_f32_16x16x32_bf16 v[36:39], v[214:217], v[206:209], v[36:39]
	v_mfma_f32_16x16x32_bf16 v[32:35], v[234:237], v[206:209], v[32:35]
	v_mfma_f32_16x16x32_bf16 v[60:63], v[230:233], v[148:151], v[60:63]
	v_mfma_f32_16x16x32_bf16 v[56:59], v[238:241], v[148:151], v[56:59]
	v_mfma_f32_16x16x32_bf16 v[52:55], v[230:233], v[194:197], v[52:55]
	v_mfma_f32_16x16x32_bf16 v[48:51], v[238:241], v[194:197], v[48:51]
	v_mfma_f32_16x16x32_bf16 v[44:47], v[230:233], v[202:205], v[44:47]
	v_mfma_f32_16x16x32_bf16 v[40:43], v[238:241], v[202:205], v[40:43]
	v_mfma_f32_16x16x32_bf16 v[36:39], v[230:233], v[210:213], v[36:39]
	v_mfma_f32_16x16x32_bf16 v[32:35], v[238:241], v[210:213], v[32:35]
	s_setprio 0
	s_mov_b32 m0, s38
	v_lshl_add_u64 v[242:243], s[30:31], 0, v[188:189]
	s_barrier
	ds_read_b128 v[144:147], v228 offset:16384
	ds_read_b128 v[148:151], v228 offset:17408
	ds_read_b128 v[152:155], v228 offset:18432
	ds_read_b128 v[194:197], v228 offset:19456
	ds_read_b128 v[198:201], v228 offset:20480
	ds_read_b128 v[202:205], v228 offset:21504
	ds_read_b128 v[206:209], v228 offset:22528
	ds_read_b128 v[210:213], v228 offset:23552
	global_load_lds_dwordx4 v[242:243], off
	v_lshl_add_u64 v[244:245], s[30:31], 0, v[186:187]
	s_mov_b32 m0, s39
	s_nop 0
	global_load_lds_dwordx4 v[244:245], off
	s_waitcnt lgkmcnt(0)
	s_setprio 1
	s_barrier
	v_mfma_f32_16x16x32_bf16 v[92:95], v[128:131], v[144:147], v[92:95]
	v_mfma_f32_16x16x32_bf16 v[88:91], v[136:139], v[144:147], v[88:91]
	v_mfma_f32_16x16x32_bf16 v[84:87], v[128:131], v[152:155], v[84:87]
	v_mfma_f32_16x16x32_bf16 v[80:83], v[136:139], v[152:155], v[80:83]
	v_mfma_f32_16x16x32_bf16 v[76:79], v[128:131], v[198:201], v[76:79]
	v_mfma_f32_16x16x32_bf16 v[72:75], v[136:139], v[198:201], v[72:75]
	v_mfma_f32_16x16x32_bf16 v[68:71], v[128:131], v[206:209], v[68:71]
	v_mfma_f32_16x16x32_bf16 v[64:67], v[136:139], v[206:209], v[64:67]
	v_mfma_f32_16x16x32_bf16 v[92:95], v[132:135], v[148:151], v[92:95]
	v_mfma_f32_16x16x32_bf16 v[88:91], v[140:143], v[148:151], v[88:91]
	v_mfma_f32_16x16x32_bf16 v[84:87], v[132:135], v[194:197], v[84:87]
	v_mfma_f32_16x16x32_bf16 v[80:83], v[140:143], v[194:197], v[80:83]
	v_mfma_f32_16x16x32_bf16 v[76:79], v[132:135], v[202:205], v[76:79]
	v_mfma_f32_16x16x32_bf16 v[72:75], v[140:143], v[202:205], v[72:75]
	v_mfma_f32_16x16x32_bf16 v[68:71], v[132:135], v[210:213], v[68:71]
	v_mfma_f32_16x16x32_bf16 v[64:67], v[140:143], v[210:213], v[64:67]
	s_setprio 0
	s_barrier
; #define PG8_STAGE(bufoff, gbase) do { _Pragma("unroll") for (int _i = 0; _i < 2; ++_i) \
;         __builtin_amdgcn_global_load_lds((const unsigned*)((const char*)(gbase) + voff[_i]), (LAS unsigned*)(lds + (bufoff) + ldsw + _i * 8192), 16, 0, 0); } while (0)
; #define PG8_LDA(dst, b, h) do { _Pragma("unroll") for (int m = 0; m < 4; ++m) _Pragma("unroll") for (int k = 0; k < 2; ++k) dst[m][k] = *(const LAS bf16x8*)(lds + PG8_SA(b, h) + aoff + m * 2048 + k * 1024); } while (0)
; #define PG8_LDB(dst, b, h) do { _Pragma("unroll") for (int n = 0; n < 2; ++n) _Pragma("unroll") for (int k = 0; k < 2; ++k) dst[n][k] = *(const LAS bf16x8*)(lds + PG8_SB(b, h) + boff + n * 2048 + k * 1024); } while (0)
; #define PG8_MMA(ai, bj, At, Bt) do { __builtin_amdgcn_s_setprio(1); _Pragma("unroll") for (int m = 0; m < 4; ++m) _Pragma("unroll") for (int n = 0; n < 2; ++n) _Pragma("unroll") for (int k = 0; k < 2; ++k) \
;         acc[ai][bj][m][n] = __builtin_amdgcn_mfma_f32_16x16x32_bf16(Bt[n][k], At[m][k], acc[ai][bj][m][n], 0, 0, 0); __builtin_amdgcn_s_setprio(0); } while (0)
; #define PG8_WAIT_V(n) asm volatile("s_waitcnt vmcnt(" #n ")" ::: "memory")
; #define PG8_WAIT_L(n) asm volatile("s_waitcnt lgkmcnt(" #n ")" ::: "memory")
; #define PG8_BAR __builtin_amdgcn_s_barrier()
; #define PG8_SCHED __builtin_amdgcn_sched_barrier(0)
; template <class Epi>
; DI void gemm_phase(LAS unsigned char* lds, const Gemm g, const StaticOrder& S, const Epi& E) {
;     ...
;             PG8_BAR; PG8_WAIT_L(0); PG8_MMA(1, 0, At, B0); PG8_BAR; PG8_SCHED;
;             PG8_STAGE(PG8_SB(0, 1), b2 + hstep);
;             PG8_WAIT_V(6); PG8_BAR; PG8_MMA(1, 1, At, B1); PG8_BAR;
;             PG8_LDB(B0, 1, 0); PG8_SCHED; PG8_LDA(At, 1, 0); PG8_STAGE(PG8_SA(0, 1), a2 + hstep);
;             PG8_WAIT_L(8); PG8_BAR; PG8_WAIT_L(0); PG8_MMA(0, 0, At, B0); PG8_BAR; PG8_SCHED;
;             PG8_LDB(B1, 1, 1); PG8_STAGE(PG8_SB(1, 0), b3);
;             PG8_BAR; PG8_WAIT_L(0); PG8_MMA(0, 1, At, B1); PG8_BAR;
;             PG8_LDA(At, 1, 1); PG8_STAGE(PG8_SA(1, 0), a3);
;             PG8_BAR; PG8_WAIT_L(0); PG8_MMA(1, 0, At, B0); PG8_BAR; PG8_SCHED;
	s_add_u32 s24, s28, 0x80000
	s_addc_u32 s25, s29, 0
	s_add_i32 s47, s48, s37
	v_lshl_add_u64 v[128:129], s[24:25], 0, v[188:189]
	s_mov_b32 m0, s47
	s_nop 0
	global_load_lds_dwordx4 v[128:129], off
	v_lshl_add_u64 v[128:129], s[24:25], 0, v[186:187]
	s_add_i32 m0, s47, 0x2000
	s_nop 0
	global_load_lds_dwordx4 v[128:129], off
	s_waitcnt vmcnt(6)
	s_setprio 1
	s_barrier
	v_mfma_f32_16x16x32_bf16 v[28:31], v[214:217], v[144:147], v[28:31]
	v_mfma_f32_16x16x32_bf16 v[24:27], v[234:237], v[144:147], v[24:27]
	v_mfma_f32_16x16x32_bf16 v[20:23], v[214:217], v[152:155], v[20:23]
	v_mfma_f32_16x16x32_bf16 v[16:19], v[234:237], v[152:155], v[16:19]
	v_mfma_f32_16x16x32_bf16 v[12:15], v[214:217], v[198:201], v[12:15]
	v_mfma_f32_16x16x32_bf16 v[8:11], v[234:237], v[198:201], v[8:11]
	v_mfma_f32_16x16x32_bf16 v[4:7], v[214:217], v[206:209], v[4:7]
	v_mfma_f32_16x16x32_bf16 v[0:3], v[234:237], v[206:209], v[0:3]
	v_mfma_f32_16x16x32_bf16 v[28:31], v[230:233], v[148:151], v[28:31]
	v_mfma_f32_16x16x32_bf16 v[24:27], v[238:241], v[148:151], v[24:27]
	v_mfma_f32_16x16x32_bf16 v[20:23], v[230:233], v[194:197], v[20:23]
	v_mfma_f32_16x16x32_bf16 v[16:19], v[238:241], v[194:197], v[16:19]
	v_mfma_f32_16x16x32_bf16 v[12:15], v[230:233], v[202:205], v[12:15]
	v_mfma_f32_16x16x32_bf16 v[8:11], v[238:241], v[202:205], v[8:11]
	v_mfma_f32_16x16x32_bf16 v[4:7], v[230:233], v[210:213], v[4:7]
	v_mfma_f32_16x16x32_bf16 v[0:3], v[238:241], v[210:213], v[0:3]
	s_setprio 0
	s_add_i32 s47, 0, 0x18000
	v_add_u32_e32 v140, s47, v226
	s_barrier
	ds_read_b128 v[128:131], v140
	ds_read_b128 v[132:135], v140 offset:1024
	ds_read_b128 v[136:139], v140 offset:2048
	ds_read_b128 v[140:143], v140 offset:3072
	s_add_u32 s24, s30, 0x80000
	s_addc_u32 s25, s31, 0
	s_mov_b32 m0, s40
	v_lshl_add_u64 v[214:215], s[24:25], 0, v[188:189]
	ds_read_b128 v[144:147], v228 offset:32768
	ds_read_b128 v[148:151], v228 offset:33792
	ds_read_b128 v[152:155], v228 offset:34816
	ds_read_b128 v[194:197], v228 offset:35840
	ds_read_b128 v[198:201], v228 offset:36864
	ds_read_b128 v[202:205], v228 offset:37888
	ds_read_b128 v[206:209], v228 offset:38912
	ds_read_b128 v[210:213], v228 offset:39936
	global_load_lds_dwordx4 v[214:215], off
	v_lshl_add_u64 v[214:215], s[24:25], 0, v[186:187]
	s_mov_b32 m0, s41
	s_nop 0
	global_load_lds_dwordx4 v[214:215], off
	s_waitcnt lgkmcnt(8)
	s_setprio 1
	s_barrier
	s_waitcnt lgkmcnt(0)
	v_mfma_f32_16x16x32_bf16 v[124:127], v[128:131], v[144:147], v[124:127]
	v_mfma_f32_16x16x32_bf16 v[120:123], v[136:139], v[144:147], v[120:123]
	v_mfma_f32_16x16x32_bf16 v[116:119], v[128:131], v[152:155], v[116:119]
	v_mfma_f32_16x16x32_bf16 v[112:115], v[136:139], v[152:155], v[112:115]
	v_mfma_f32_16x16x32_bf16 v[108:111], v[128:131], v[198:201], v[108:111]
	v_mfma_f32_16x16x32_bf16 v[104:107], v[136:139], v[198:201], v[104:107]
	v_mfma_f32_16x16x32_bf16 v[100:103], v[128:131], v[206:209], v[100:103]
	v_mfma_f32_16x16x32_bf16 v[96:99], v[136:139], v[206:209], v[96:99]
	v_mfma_f32_16x16x32_bf16 v[124:127], v[132:135], v[148:151], v[124:127]
	v_mfma_f32_16x16x32_bf16 v[120:123], v[140:143], v[148:151], v[120:123]
	v_mfma_f32_16x16x32_bf16 v[116:119], v[132:135], v[194:197], v[116:119]
	v_mfma_f32_16x16x32_bf16 v[112:115], v[140:143], v[194:197], v[112:115]
	v_mfma_f32_16x16x32_bf16 v[108:111], v[132:135], v[202:205], v[108:111]
	v_mfma_f32_16x16x32_bf16 v[104:107], v[140:143], v[202:205], v[104:107]
	v_mfma_f32_16x16x32_bf16 v[100:103], v[132:135], v[210:213], v[100:103]
	v_mfma_f32_16x16x32_bf16 v[96:99], v[140:143], v[210:213], v[96:99]
	s_setprio 0
	s_barrier
	s_add_i32 s30, 0, 0x1c000
	s_add_i32 s24, s47, s37
	v_add_u32_e32 v158, s30, v226
	v_lshl_add_u64 v[218:219], v[218:219], 0, s[94:95]
	s_mov_b32 m0, s24
	ds_read_b128 v[214:217], v158
	ds_read_b128 v[230:233], v158 offset:1024
	ds_read_b128 v[234:237], v158 offset:2048
	ds_read_b128 v[238:241], v158 offset:3072
	global_load_lds_dwordx4 v[218:219], off
	v_lshl_add_u64 v[218:219], v[220:221], 0, s[94:95]
	s_add_i32 m0, s24, 0x2000
	s_nop 0
	global_load_lds_dwordx4 v[218:219], off
	s_waitcnt lgkmcnt(0)
	s_setprio 1
	s_barrier
	v_mfma_f32_16x16x32_bf16 v[60:63], v[214:217], v[144:147], v[60:63]
	v_mfma_f32_16x16x32_bf16 v[56:59], v[234:237], v[144:147], v[56:59]
	v_mfma_f32_16x16x32_bf16 v[52:55], v[214:217], v[152:155], v[52:55]
	v_mfma_f32_16x16x32_bf16 v[48:51], v[234:237], v[152:155], v[48:51]
	v_mfma_f32_16x16x32_bf16 v[44:47], v[214:217], v[198:201], v[44:47]
	v_mfma_f32_16x16x32_bf16 v[40:43], v[234:237], v[198:201], v[40:43]
	v_mfma_f32_16x16x32_bf16 v[36:39], v[214:217], v[206:209], v[36:39]
	v_mfma_f32_16x16x32_bf16 v[32:35], v[234:237], v[206:209], v[32:35]
	v_mfma_f32_16x16x32_bf16 v[60:63], v[230:233], v[148:151], v[60:63]
	v_mfma_f32_16x16x32_bf16 v[56:59], v[238:241], v[148:151], v[56:59]
	v_mfma_f32_16x16x32_bf16 v[52:55], v[230:233], v[194:197], v[52:55]
	v_mfma_f32_16x16x32_bf16 v[48:51], v[238:241], v[194:197], v[48:51]
	v_mfma_f32_16x16x32_bf16 v[44:47], v[230:233], v[202:205], v[44:47]
	v_mfma_f32_16x16x32_bf16 v[40:43], v[238:241], v[202:205], v[40:43]
	v_mfma_f32_16x16x32_bf16 v[36:39], v[230:233], v[210:213], v[36:39]
	v_mfma_f32_16x16x32_bf16 v[32:35], v[238:241], v[210:213], v[32:35]
	s_setprio 0
	s_mov_b32 m0, s42
	v_lshl_add_u64 v[218:219], v[242:243], 0, s[94:95]
	s_barrier
	ds_read_b128 v[144:147], v228 offset:49152
	ds_read_b128 v[148:151], v228 offset:50176
	ds_read_b128 v[152:155], v228 offset:51200
	ds_read_b128 v[194:197], v228 offset:52224
	ds_read_b128 v[198:201], v228 offset:53248
	ds_read_b128 v[202:205], v228 offset:54272
	ds_read_b128 v[206:209], v228 offset:55296
	ds_read_b128 v[210:213], v228 offset:56320
	global_load_lds_dwordx4 v[218:219], off
	v_lshl_add_u64 v[218:219], v[244:245], 0, s[94:95]
	s_mov_b32 m0, s43
	s_nop 0
	global_load_lds_dwordx4 v[218:219], off
	s_waitcnt lgkmcnt(0)
	s_setprio 1
	s_barrier
; #define PG8_STAGE(bufoff, gbase) do { _Pragma("unroll") for (int _i = 0; _i < 2; ++_i) \
;         __builtin_amdgcn_global_load_lds((const unsigned*)((const char*)(gbase) + voff[_i]), (LAS unsigned*)(lds + (bufoff) + ldsw + _i * 8192), 16, 0, 0); } while (0)
; #define PG8_LDA(dst, b, h) do { _Pragma("unroll") for (int m = 0; m < 4; ++m) _Pragma("unroll") for (int k = 0; k < 2; ++k) dst[m][k] = *(const LAS bf16x8*)(lds + PG8_SA(b, h) + aoff + m * 2048 + k * 1024); } while (0)
; template <class Epi>
; DI void gemm_phase(LAS unsigned char* lds, const Gemm g, const StaticOrder& S, const Epi& E) {
;     ...
;             PG8_BAR; PG8_WAIT_L(0); PG8_MMA(0, 1, At, B1); PG8_BAR;
;             PG8_LDA(At, 1, 1); PG8_STAGE(PG8_SA(1, 0), a3);
;             PG8_BAR; PG8_WAIT_L(0); PG8_MMA(1, 0, At, B0); PG8_BAR; PG8_SCHED;
;             PG8_STAGE(PG8_SB(1, 1), b3 + hstep);
;             PG8_WAIT_V(6); PG8_BAR; PG8_MMA(1, 1, At, B1); PG8_BAR;
;     template <bool LN, int BJ, int LO, int HI> DI void batch(const f32x4 (&acc)[2][2][4][2], unsigned row0, unsigned col0, const f32x4 (&gv)[2], const f32x4 (&bv)[2]) const {
;         f32x4 r[HI - LO]; float mean[(HI - LO) / 2], rstd[(HI - LO) / 2];
; #pragma unroll
;         for (int i = LO; i < HI; ++i) { const int ai = i >> 3, m = (i >> 1) & 3, n = i & 1; const unsigned row = row0 + ai * HALF + m * 16;
;             if (n == 0) { mean[(i - LO) >> 1] = 0.f; rstd[(i - LO) >> 1] = 1.f;
;                 if (LN) { const float2 st = *(const float2*)(stats + row * 2u); mean[(i - LO) >> 1] = st.x; rstd[(i - LO) >> 1] = st.y; } }
;             r[i - LO] = *(const f32x4*)(src + (row * (unsigned)DM + col0 + BJ * HALF + n * 16)); }
; #pragma unroll
;         for (int i = LO; i < HI; ++i) { const int ai = i >> 3, m = (i >> 1) & 3, n = i & 1; const unsigned row = row0 + ai * HALF + m * 16;
;             *(f32x4*)(Y + (row * (unsigned)DM + col0 + BJ * HALF + n * 16)) = acc[ai][BJ][m][n] + ((r[i - LO] - mean[(i - LO) >> 1]) * rstd[(i - LO) >> 1]) * gv[n] + bv[n]; }
;         __builtin_amdgcn_sched_barrier(0);
;     }
;     template <bool LN, int BJ> DI void load_gb(unsigned col0, f32x4 (&gv)[2], f32x4 (&bv)[2]) const {
; #pragma unroll
;         for (int n = 0; n < 2; ++n) {
;             if (LN) { gv[n] = *(const f32x4*)(gam + col0 + BJ * HALF + n * 16) * ALPHA; bv[n] = *(const f32x4*)(bet + col0 + BJ * HALF + n * 16) * ALPHA; }
	v_mfma_f32_16x16x32_bf16 v[92:95], v[128:131], v[144:147], v[92:95]
	v_mfma_f32_16x16x32_bf16 v[88:91], v[136:139], v[144:147], v[88:91]
	v_mfma_f32_16x16x32_bf16 v[84:87], v[128:131], v[152:155], v[84:87]
	v_mfma_f32_16x16x32_bf16 v[80:83], v[136:139], v[152:155], v[80:83]
	v_mfma_f32_16x16x32_bf16 v[76:79], v[128:131], v[198:201], v[76:79]
	v_mfma_f32_16x16x32_bf16 v[72:75], v[136:139], v[198:201], v[72:75]
	v_mfma_f32_16x16x32_bf16 v[68:71], v[128:131], v[206:209], v[68:71]
	v_mfma_f32_16x16x32_bf16 v[64:67], v[136:139], v[206:209], v[64:67]
	v_mfma_f32_16x16x32_bf16 v[92:95], v[132:135], v[148:151], v[92:95]
	v_mfma_f32_16x16x32_bf16 v[88:91], v[140:143], v[148:151], v[88:91]
	v_mfma_f32_16x16x32_bf16 v[84:87], v[132:135], v[194:197], v[84:87]
	v_mfma_f32_16x16x32_bf16 v[80:83], v[140:143], v[194:197], v[80:83]
	v_mfma_f32_16x16x32_bf16 v[76:79], v[132:135], v[202:205], v[76:79]
	v_mfma_f32_16x16x32_bf16 v[72:75], v[140:143], v[202:205], v[72:75]
	v_mfma_f32_16x16x32_bf16 v[68:71], v[132:135], v[210:213], v[68:71]
	v_mfma_f32_16x16x32_bf16 v[64:67], v[140:143], v[210:213], v[64:67]
	s_setprio 0
	s_barrier
	s_add_u32 s24, s28, 0x80080
	s_addc_u32 s25, s29, 0
	s_add_i32 s28, s30, s37
	v_lshl_add_u64 v[128:129], s[24:25], 0, v[188:189]
	s_mov_b32 m0, s28
	s_nop 0
	global_load_lds_dwordx4 v[128:129], off
	v_lshl_add_u64 v[128:129], s[24:25], 0, v[186:187]
	s_add_i32 m0, s28, 0x2000
	s_nop 0
	global_load_lds_dwordx4 v[128:129], off
	s_waitcnt vmcnt(6)
	s_setprio 1
	s_barrier
	v_mfma_f32_16x16x32_bf16 v[28:31], v[214:217], v[144:147], v[28:31]
	v_mfma_f32_16x16x32_bf16 v[24:27], v[234:237], v[144:147], v[24:27]
	v_mfma_f32_16x16x32_bf16 v[20:23], v[214:217], v[152:155], v[20:23]
	v_mfma_f32_16x16x32_bf16 v[16:19], v[234:237], v[152:155], v[16:19]
	v_mfma_f32_16x16x32_bf16 v[12:15], v[214:217], v[198:201], v[12:15]
	v_mfma_f32_16x16x32_bf16 v[8:11], v[234:237], v[198:201], v[8:11]
	v_mfma_f32_16x16x32_bf16 v[4:7], v[214:217], v[206:209], v[4:7]
	v_mfma_f32_16x16x32_bf16 v[0:3], v[234:237], v[206:209], v[0:3]
	v_mfma_f32_16x16x32_bf16 v[28:31], v[230:233], v[148:151], v[28:31]
	v_mfma_f32_16x16x32_bf16 v[24:27], v[238:241], v[148:151], v[24:27]
	v_mfma_f32_16x16x32_bf16 v[20:23], v[230:233], v[194:197], v[20:23]
	v_mfma_f32_16x16x32_bf16 v[16:19], v[238:241], v[194:197], v[16:19]
	v_mfma_f32_16x16x32_bf16 v[12:15], v[230:233], v[202:205], v[12:15]
	v_mfma_f32_16x16x32_bf16 v[8:11], v[238:241], v[202:205], v[8:11]
	v_mfma_f32_16x16x32_bf16 v[4:7], v[230:233], v[210:213], v[4:7]
	v_mfma_f32_16x16x32_bf16 v[0:3], v[238:241], v[210:213], v[0:3]
	s_setprio 0
	s_add_i32 s46, s46, 2
	s_add_u32 s33, s33, 0x100
	s_addc_u32 s45, s45, 0
	s_cmp_gt_u32 s46, 29
	s_mov_b64 s[24:25], s[26:27]
	s_barrier
	s_cbranch_scc0 .LBB0_320
	v_lshl_add_u32 v206, s3, 8, v225
	v_lshl_or_b32 v158, s2, 8, v227
	v_lshlrev_b32_e32 v232, 11, v206
	s_andn2_b64 vcc, exec, s[14:15]
	v_or_b32_e32 v231, 16, v158
	v_add_u32_e32 v194, v232, v158
	v_or_b32_e32 v230, 0x80, v158
	v_or_b32_e32 v229, 0x90, v158
	s_cbranch_vccnz .LBB0_323
	v_lshlrev_b64 v[132:133], 2, v[158:159]
	v_lshl_add_u64 v[140:141], s[16:17], 0, v[132:133]
	global_load_dwordx4 v[128:131], v[140:141], off
	v_lshl_add_u64 v[142:143], s[18:19], 0, v[132:133]
	v_readlane_b32 s2, v253, 8
	v_mov_b32_e32 v195, v159
	v_lshlrev_b32_e32 v136, 1, v206
	v_mov_b32_e32 v137, v159
	v_readlane_b32 s3, v253, 9
	v_lshlrev_b64 v[212:213], 2, v[194:195]
	v_add_u32_e32 v146, v232, v231
	v_lshl_add_u64 v[144:145], v[136:137], 2, s[2:3]
	v_lshl_add_u64 v[136:137], s[88:89], 0, v[212:213]
	v_mov_b32_e32 v147, v159
	v_lshl_add_u64 v[146:147], v[146:147], 2, s[88:89]
	v_or_b32_e32 v195, 16, v206
	v_mov_b32_e32 v201, v159
	v_mov_b32_e32 v209, v159
	v_lshl_add_u64 v[212:213], s[90:91], 0, v[212:213]
	s_waitcnt vmcnt(0)
	v_pk_mul_f32 v[152:153], v[130:131], s[78:79] op_sel_hi:[1,0]
	v_pk_mul_f32 v[154:155], v[128:129], s[78:79] op_sel_hi:[1,0]
	global_load_dwordx4 v[132:135], v[142:143], off
	global_load_dwordx4 v[128:131], v[140:141], off offset:64
	global_load_dwordx2 v[204:205], v[144:145], off
	global_load_dwordx4 v[196:199], v[146:147], off
	v_lshlrev_b32_e32 v146, 1, v195
	global_load_dwordx4 v[136:139], v[136:137], off
	v_lshlrev_b32_e32 v195, 11, v195
	v_mov_b32_e32 v147, v159
	v_add_u32_e32 v200, v195, v158
	v_lshl_add_u64 v[146:147], v[146:147], 2, s[2:3]
	v_lshl_add_u64 v[200:201], v[200:201], 2, s[88:89]
	global_load_dwordx2 v[214:215], v[146:147], off
	v_add_u32_e32 v208, v195, v231
	global_load_dwordx4 v[200:203], v[200:201], off
	v_lshl_add_u64 v[208:209], v[208:209], 2, s[88:89]
	global_load_dwordx4 v[208:211], v[208:209], off
	s_waitcnt vmcnt(0)
	v_pk_mul_f32 v[148:149], v[130:131], s[78:79] op_sel_hi:[1,0]
	v_pk_mul_f32 v[150:151], v[128:129], s[78:79] op_sel_hi:[1,0]
	global_load_dwordx4 v[128:131], v[142:143], off offset:64
	v_sub_f32_e32 v137, v137, v204
	v_sub_f32_e32 v136, v136, v204
	v_sub_f32_e32 v139, v139, v204
	v_sub_f32_e32 v138, v138, v204
	v_pk_mul_f32 v[138:139], v[204:205], v[138:139] op_sel:[1,0]
	v_pk_mul_f32 v[136:137], v[204:205], v[136:137] op_sel:[1,0]
	v_pk_fma_f32 v[138:139], v[152:153], v[138:139], v[126:127]
	v_pk_fma_f32 v[136:137], v[154:155], v[136:137], v[124:125]
	v_pk_fma_f32 v[138:139], v[134:135], s[78:79], v[138:139] op_sel_hi:[1,0,1]
	v_pk_fma_f32 v[136:137], v[132:133], s[78:79], v[136:137] op_sel_hi:[1,0,1]
	global_store_dwordx4 v[212:213], v[136:139], off
	s_nop 1
	v_sub_f32_e32 v137, v197, v204
	v_sub_f32_e32 v136, v196, v204
	v_sub_f32_e32 v139, v199, v204
	v_sub_f32_e32 v138, v198, v204
	v_pk_mul_f32 v[138:139], v[204:205], v[138:139] op_sel:[1,0]
	v_pk_mul_f32 v[136:137], v[204:205], v[136:137] op_sel:[1,0]
	v_pk_fma_f32 v[138:139], v[148:149], v[138:139], v[122:123]
	v_pk_fma_f32 v[136:137], v[150:151], v[136:137], v[120:121]
	v_or_b32_e32 v196, 16, v194
	v_mov_b32_e32 v197, v159
	v_lshl_add_u64 v[196:197], v[196:197], 2, s[90:91]
	s_waitcnt vmcnt(0)
;     template <bool LN, int BJ, int LO, int HI> DI void batch(const f32x4 (&acc)[2][2][4][2], unsigned row0, unsigned col0, const f32x4 (&gv)[2], const f32x4 (&bv)[2]) const {
;         f32x4 r[HI - LO]; float mean[(HI - LO) / 2], rstd[(HI - LO) / 2];
; #pragma unroll
;         for (int i = LO; i < HI; ++i) { const int ai = i >> 3, m = (i >> 1) & 3, n = i & 1; const unsigned row = row0 + ai * HALF + m * 16;
;             if (n == 0) { mean[(i - LO) >> 1] = 0.f; rstd[(i - LO) >> 1] = 1.f;
;                 if (LN) { const float2 st = *(const float2*)(stats + row * 2u); mean[(i - LO) >> 1] = st.x; rstd[(i - LO) >> 1] = st.y; } }
;             r[i - LO] = *(const f32x4*)(src + (row * (unsigned)DM + col0 + BJ * HALF + n * 16)); }
; #pragma unroll
;         for (int i = LO; i < HI; ++i) { const int ai = i >> 3, m = (i >> 1) & 3, n = i & 1; const unsigned row = row0 + ai * HALF + m * 16;
;             *(f32x4*)(Y + (row * (unsigned)DM + col0 + BJ * HALF + n * 16)) = acc[ai][BJ][m][n] + ((r[i - LO] - mean[(i - LO) >> 1]) * rstd[(i - LO) >> 1]) * gv[n] + bv[n]; }
	v_pk_fma_f32 v[138:139], v[130:131], s[78:79], v[138:139] op_sel_hi:[1,0,1]
	v_pk_fma_f32 v[136:137], v[128:129], s[78:79], v[136:137] op_sel_hi:[1,0,1]
	global_store_dwordx4 v[196:197], v[136:139], off
	v_add_u32_e32 v196, 0x8000, v194
	v_mov_b32_e32 v197, v159
	v_sub_f32_e32 v137, v201, v214
	v_sub_f32_e32 v136, v200, v214
	v_sub_f32_e32 v139, v203, v214
	v_sub_f32_e32 v138, v202, v214
	v_pk_mul_f32 v[138:139], v[214:215], v[138:139] op_sel:[1,0]
	v_pk_mul_f32 v[136:137], v[214:215], v[136:137] op_sel:[1,0]
	v_pk_fma_f32 v[138:139], v[152:153], v[138:139], v[118:119]
	v_pk_fma_f32 v[136:137], v[154:155], v[136:137], v[116:117]
	v_pk_fma_f32 v[138:139], v[134:135], s[78:79], v[138:139] op_sel_hi:[1,0,1]
	v_pk_fma_f32 v[136:137], v[132:133], s[78:79], v[136:137] op_sel_hi:[1,0,1]
	v_lshl_add_u64 v[196:197], v[196:197], 2, s[90:91]
	global_store_dwordx4 v[196:197], v[136:139], off
	v_add_u32_e32 v196, 0x8010, v194
	v_mov_b32_e32 v197, v159
	v_sub_f32_e32 v137, v209, v214
	v_sub_f32_e32 v136, v208, v214
	v_sub_f32_e32 v139, v211, v214
	v_sub_f32_e32 v138, v210, v214
	v_pk_mul_f32 v[138:139], v[214:215], v[138:139] op_sel:[1,0]
	v_pk_mul_f32 v[136:137], v[214:215], v[136:137] op_sel:[1,0]
	v_pk_fma_f32 v[138:139], v[148:149], v[138:139], v[114:115]
	v_pk_fma_f32 v[136:137], v[150:151], v[136:137], v[112:113]
	v_pk_fma_f32 v[138:139], v[130:131], s[78:79], v[138:139] op_sel_hi:[1,0,1]
	v_pk_fma_f32 v[136:137], v[128:129], s[78:79], v[136:137] op_sel_hi:[1,0,1]
	v_lshl_add_u64 v[196:197], v[196:197], 2, s[90:91]
	global_store_dwordx4 v[196:197], v[136:139], off
	s_nop 1
	v_or_b32_e32 v138, 32, v206
	v_lshlrev_b32_e32 v136, 1, v138
	v_mov_b32_e32 v137, v159
	v_lshlrev_b32_e32 v236, 11, v138
	v_lshl_add_u64 v[200:201], v[136:137], 2, s[2:3]
	v_add_u32_e32 v136, v236, v158
	v_lshl_add_u64 v[136:137], v[136:137], 2, s[88:89]
	global_load_dwordx2 v[204:205], v[200:201], off
	v_add_u32_e32 v196, v236, v231
	global_load_dwordx4 v[136:139], v[136:137], off
	v_mov_b32_e32 v197, v159
	v_lshl_add_u64 v[196:197], v[196:197], 2, s[88:89]
	global_load_dwordx4 v[196:199], v[196:197], off
	v_or_b32_e32 v207, 48, v206
	v_lshlrev_b32_e32 v235, 11, v207
	v_lshlrev_b32_e32 v202, 1, v207
	v_mov_b32_e32 v203, v159
	v_add_u32_e32 v208, v235, v158
	v_mov_b32_e32 v209, v159
	v_lshl_add_u64 v[202:203], v[202:203], 2, s[2:3]
	v_lshl_add_u64 v[208:209], v[208:209], 2, s[88:89]
	global_load_dwordx2 v[216:217], v[202:203], off
	v_add_u32_e32 v212, v235, v231
	global_load_dwordx4 v[208:211], v[208:209], off
	v_mov_b32_e32 v213, v159
	v_lshl_add_u64 v[212:213], v[212:213], 2, s[88:89]
	global_load_dwordx4 v[212:215], v[212:213], off
	v_add_u32_e32 v218, 0x10000, v194
	v_mov_b32_e32 v219, v159
	v_lshl_add_u64 v[218:219], v[218:219], 2, s[90:91]
	s_waitcnt vmcnt(0)
	v_sub_f32_e32 v137, v137, v204
	v_sub_f32_e32 v136, v136, v204
	v_sub_f32_e32 v139, v139, v204
	v_sub_f32_e32 v138, v138, v204
	v_pk_mul_f32 v[138:139], v[204:205], v[138:139] op_sel:[1,0]
	v_pk_mul_f32 v[136:137], v[204:205], v[136:137] op_sel:[1,0]
	v_pk_fma_f32 v[138:139], v[152:153], v[138:139], v[110:111]
	v_pk_fma_f32 v[136:137], v[154:155], v[136:137], v[108:109]
	v_pk_fma_f32 v[138:139], v[134:135], s[78:79], v[138:139] op_sel_hi:[1,0,1]
	v_pk_fma_f32 v[136:137], v[132:133], s[78:79], v[136:137] op_sel_hi:[1,0,1]
	global_store_dwordx4 v[218:219], v[136:139], off
	s_nop 1
	v_sub_f32_e32 v137, v197, v204
	v_sub_f32_e32 v136, v196, v204
	v_sub_f32_e32 v139, v199, v204
	v_sub_f32_e32 v138, v198, v204
	v_pk_mul_f32 v[138:139], v[204:205], v[138:139] op_sel:[1,0]
	v_pk_mul_f32 v[136:137], v[204:205], v[136:137] op_sel:[1,0]
	v_pk_fma_f32 v[138:139], v[148:149], v[138:139], v[106:107]
	v_pk_fma_f32 v[136:137], v[150:151], v[136:137], v[104:105]
	v_add_u32_e32 v196, 0x10010, v194
	v_mov_b32_e32 v197, v159
	v_pk_fma_f32 v[138:139], v[130:131], s[78:79], v[138:139] op_sel_hi:[1,0,1]
	v_pk_fma_f32 v[136:137], v[128:129], s[78:79], v[136:137] op_sel_hi:[1,0,1]
	v_lshl_add_u64 v[196:197], v[196:197], 2, s[90:91]
	global_store_dwordx4 v[196:197], v[136:139], off
	v_add_u32_e32 v196, 0x18000, v194
	v_mov_b32_e32 v197, v159
	v_sub_f32_e32 v137, v209, v216
	v_sub_f32_e32 v136, v208, v216
	v_sub_f32_e32 v139, v211, v216
	v_sub_f32_e32 v138, v210, v216
	v_pk_mul_f32 v[138:139], v[216:217], v[138:139] op_sel:[1,0]
	v_pk_mul_f32 v[136:137], v[216:217], v[136:137] op_sel:[1,0]
	v_pk_fma_f32 v[138:139], v[152:153], v[138:139], v[102:103]
	v_pk_fma_f32 v[136:137], v[154:155], v[136:137], v[100:101]
	v_pk_fma_f32 v[138:139], v[134:135], s[78:79], v[138:139] op_sel_hi:[1,0,1]
	v_pk_fma_f32 v[136:137], v[132:133], s[78:79], v[136:137] op_sel_hi:[1,0,1]
	v_lshl_add_u64 v[196:197], v[196:197], 2, s[90:91]
	global_store_dwordx4 v[196:197], v[136:139], off
	v_add_u32_e32 v196, 0x18010, v194
	v_mov_b32_e32 v197, v159
	v_sub_f32_e32 v137, v213, v216
	v_sub_f32_e32 v136, v212, v216
	v_sub_f32_e32 v139, v215, v216
	v_sub_f32_e32 v138, v214, v216
	v_pk_mul_f32 v[138:139], v[216:217], v[138:139] op_sel:[1,0]
	v_pk_mul_f32 v[136:137], v[216:217], v[136:137] op_sel:[1,0]
	v_pk_fma_f32 v[138:139], v[148:149], v[138:139], v[98:99]
	v_pk_fma_f32 v[136:137], v[150:151], v[136:137], v[96:97]
	v_pk_fma_f32 v[138:139], v[130:131], s[78:79], v[138:139] op_sel_hi:[1,0,1]
	v_pk_fma_f32 v[136:137], v[128:129], s[78:79], v[136:137] op_sel_hi:[1,0,1]
	v_lshl_add_u64 v[196:197], v[196:197], 2, s[90:91]
	global_store_dwordx4 v[196:197], v[136:139], off
	s_nop 1
	v_add_u32_e32 v138, 0x80, v206
	v_lshlrev_b32_e32 v136, 1, v138
	v_mov_b32_e32 v137, v159
	v_lshlrev_b32_e32 v233, 11, v138
	v_lshl_add_u64 v[196:197], v[136:137], 2, s[2:3]
	v_add_u32_e32 v136, v233, v158
	v_lshl_add_u64 v[136:137], v[136:137], 2, s[88:89]
	global_load_dwordx2 v[204:205], v[196:197], off
	v_add_u32_e32 v198, v233, v231
	global_load_dwordx4 v[136:139], v[136:137], off
	v_mov_b32_e32 v199, v159
	v_add_u32_e32 v207, 0x90, v206
	v_lshl_add_u64 v[198:199], v[198:199], 2, s[88:89]
	v_lshlrev_b32_e32 v234, 11, v207
	global_load_dwordx4 v[208:211], v[198:199], off
	v_add_u32_e32 v212, v234, v158
	v_mov_b32_e32 v213, v159
	v_lshl_add_u64 v[212:213], v[212:213], 2, s[88:89]
	global_load_dwordx4 v[212:215], v[212:213], off
	v_lshlrev_b32_e32 v198, 1, v207
	v_mov_b32_e32 v199, v159
	v_lshl_add_u64 v[198:199], v[198:199], 2, s[2:3]
	global_load_dwordx2 v[238:239], v[198:199], off
	v_add_u32_e32 v216, v234, v231
	v_mov_b32_e32 v217, v159
	v_lshl_add_u64 v[216:217], v[216:217], 2, s[88:89]
	global_load_dwordx4 v[216:219], v[216:217], off
	v_add_u32_e32 v240, 0x40000, v194
	v_mov_b32_e32 v241, v159
	v_lshl_add_u64 v[240:241], v[240:241], 2, s[90:91]
	s_waitcnt vmcnt(0)
;     template <bool LN, int BJ, int LO, int HI> DI void batch(const f32x4 (&acc)[2][2][4][2], unsigned row0, unsigned col0, const f32x4 (&gv)[2], const f32x4 (&bv)[2]) const {
;         f32x4 r[HI - LO]; float mean[(HI - LO) / 2], rstd[(HI - LO) / 2];
; #pragma unroll
;         for (int i = LO; i < HI; ++i) { const int ai = i >> 3, m = (i >> 1) & 3, n = i & 1; const unsigned row = row0 + ai * HALF + m * 16;
;             if (n == 0) { mean[(i - LO) >> 1] = 0.f; rstd[(i - LO) >> 1] = 1.f;
;                 if (LN) { const float2 st = *(const float2*)(stats + row * 2u); mean[(i - LO) >> 1] = st.x; rstd[(i - LO) >> 1] = st.y; } }
;             r[i - LO] = *(const f32x4*)(src + (row * (unsigned)DM + col0 + BJ * HALF + n * 16)); }
; #pragma unroll
;         for (int i = LO; i < HI; ++i) { const int ai = i >> 3, m = (i >> 1) & 3, n = i & 1; const unsigned row = row0 + ai * HALF + m * 16;
;             *(f32x4*)(Y + (row * (unsigned)DM + col0 + BJ * HALF + n * 16)) = acc[ai][BJ][m][n] + ((r[i - LO] - mean[(i - LO) >> 1]) * rstd[(i - LO) >> 1]) * gv[n] + bv[n]; }
	v_sub_f32_e32 v137, v137, v204
	v_sub_f32_e32 v136, v136, v204
	v_sub_f32_e32 v139, v139, v204
	v_sub_f32_e32 v138, v138, v204
	v_pk_mul_f32 v[138:139], v[204:205], v[138:139] op_sel:[1,0]
	v_pk_mul_f32 v[136:137], v[204:205], v[136:137] op_sel:[1,0]
	v_pk_fma_f32 v[138:139], v[152:153], v[138:139], v[94:95]
	v_pk_fma_f32 v[136:137], v[154:155], v[136:137], v[92:93]
	v_pk_fma_f32 v[138:139], v[134:135], s[78:79], v[138:139] op_sel_hi:[1,0,1]
	v_pk_fma_f32 v[136:137], v[132:133], s[78:79], v[136:137] op_sel_hi:[1,0,1]
	global_store_dwordx4 v[240:241], v[136:139], off
	s_nop 1
	v_sub_f32_e32 v137, v209, v204
	v_sub_f32_e32 v136, v208, v204
	v_sub_f32_e32 v139, v211, v204
	v_sub_f32_e32 v138, v210, v204
	v_pk_mul_f32 v[138:139], v[204:205], v[138:139] op_sel:[1,0]
	v_pk_mul_f32 v[136:137], v[204:205], v[136:137] op_sel:[1,0]
	v_pk_fma_f32 v[138:139], v[148:149], v[138:139], v[90:91]
	v_pk_fma_f32 v[136:137], v[150:151], v[136:137], v[88:89]
	v_add_u32_e32 v204, 0x40010, v194
	v_mov_b32_e32 v205, v159
	v_pk_fma_f32 v[138:139], v[130:131], s[78:79], v[138:139] op_sel_hi:[1,0,1]
	v_pk_fma_f32 v[136:137], v[128:129], s[78:79], v[136:137] op_sel_hi:[1,0,1]
	v_lshl_add_u64 v[204:205], v[204:205], 2, s[90:91]
	global_store_dwordx4 v[204:205], v[136:139], off
	v_add_u32_e32 v204, 0x48000, v194
	v_mov_b32_e32 v205, v159
	v_sub_f32_e32 v137, v213, v238
	v_sub_f32_e32 v136, v212, v238
	v_sub_f32_e32 v139, v215, v238
	v_sub_f32_e32 v138, v214, v238
	v_pk_mul_f32 v[138:139], v[238:239], v[138:139] op_sel:[1,0]
	v_pk_mul_f32 v[136:137], v[238:239], v[136:137] op_sel:[1,0]
	v_pk_fma_f32 v[138:139], v[152:153], v[138:139], v[86:87]
	v_pk_fma_f32 v[136:137], v[154:155], v[136:137], v[84:85]
	v_pk_fma_f32 v[138:139], v[134:135], s[78:79], v[138:139] op_sel_hi:[1,0,1]
	v_pk_fma_f32 v[136:137], v[132:133], s[78:79], v[136:137] op_sel_hi:[1,0,1]
	v_lshl_add_u64 v[204:205], v[204:205], 2, s[90:91]
	global_store_dwordx4 v[204:205], v[136:139], off
	v_add_u32_e32 v204, 0x48010, v194
	v_mov_b32_e32 v205, v159
	v_sub_f32_e32 v137, v217, v238
	v_sub_f32_e32 v136, v216, v238
	v_sub_f32_e32 v139, v219, v238
	v_sub_f32_e32 v138, v218, v238
	v_pk_mul_f32 v[138:139], v[238:239], v[138:139] op_sel:[1,0]
	v_pk_mul_f32 v[136:137], v[238:239], v[136:137] op_sel:[1,0]
	v_pk_fma_f32 v[138:139], v[148:149], v[138:139], v[82:83]
	v_pk_fma_f32 v[136:137], v[150:151], v[136:137], v[80:81]
	v_pk_fma_f32 v[138:139], v[130:131], s[78:79], v[138:139] op_sel_hi:[1,0,1]
	v_pk_fma_f32 v[136:137], v[128:129], s[78:79], v[136:137] op_sel_hi:[1,0,1]
	v_lshl_add_u64 v[204:205], v[204:205], 2, s[90:91]
	global_store_dwordx4 v[204:205], v[136:139], off
	s_nop 1
	v_add_u32_e32 v138, 0xa0, v206
	v_lshlrev_b32_e32 v136, 1, v138
	v_mov_b32_e32 v137, v159
	v_lshlrev_b32_e32 v237, 11, v138
	v_lshl_add_u64 v[204:205], v[136:137], 2, s[2:3]
	v_add_u32_e32 v136, v237, v158
	v_lshl_add_u64 v[136:137], v[136:137], 2, s[88:89]
	global_load_dwordx2 v[240:241], v[204:205], off
	v_add_u32_e32 v208, v237, v231
	global_load_dwordx4 v[136:139], v[136:137], off
	v_mov_b32_e32 v209, v159
	v_lshl_add_u64 v[208:209], v[208:209], 2, s[88:89]
	global_load_dwordx4 v[212:215], v[208:209], off
	v_add_u32_e32 v208, 0xb0, v206
	v_lshlrev_b32_e32 v206, 1, v208
	v_mov_b32_e32 v207, v159
	v_lshlrev_b32_e32 v238, 11, v208
	v_lshl_add_u64 v[210:211], v[206:207], 2, s[2:3]
	v_add_u32_e32 v206, v238, v158
	v_lshl_add_u64 v[206:207], v[206:207], 2, s[88:89]
	global_load_dwordx2 v[242:243], v[210:211], off
	v_add_u32_e32 v216, v238, v231
	global_load_dwordx4 v[206:209], v[206:207], off
	v_mov_b32_e32 v217, v159
	v_lshl_add_u64 v[216:217], v[216:217], 2, s[88:89]
	global_load_dwordx4 v[216:219], v[216:217], off
	v_add_u32_e32 v244, 0x50000, v194
	v_mov_b32_e32 v245, v159
	v_lshl_add_u64 v[244:245], v[244:245], 2, s[90:91]
	s_waitcnt vmcnt(0)
	v_sub_f32_e32 v137, v137, v240
	v_sub_f32_e32 v136, v136, v240
	v_sub_f32_e32 v139, v139, v240
	v_sub_f32_e32 v138, v138, v240
	v_pk_mul_f32 v[138:139], v[240:241], v[138:139] op_sel:[1,0]
	v_pk_mul_f32 v[136:137], v[240:241], v[136:137] op_sel:[1,0]
	v_pk_fma_f32 v[138:139], v[152:153], v[138:139], v[78:79]
	v_pk_fma_f32 v[136:137], v[154:155], v[136:137], v[76:77]
	v_pk_fma_f32 v[138:139], v[134:135], s[78:79], v[138:139] op_sel_hi:[1,0,1]
	v_pk_fma_f32 v[136:137], v[132:133], s[78:79], v[136:137] op_sel_hi:[1,0,1]
	global_store_dwordx4 v[244:245], v[136:139], off
	s_nop 1
	v_sub_f32_e32 v137, v213, v240
	v_sub_f32_e32 v136, v212, v240
	v_sub_f32_e32 v139, v215, v240
	v_sub_f32_e32 v138, v214, v240
	v_pk_mul_f32 v[138:139], v[240:241], v[138:139] op_sel:[1,0]
	v_pk_mul_f32 v[136:137], v[240:241], v[136:137] op_sel:[1,0]
	v_pk_fma_f32 v[138:139], v[148:149], v[138:139], v[74:75]
	v_pk_fma_f32 v[136:137], v[150:151], v[136:137], v[72:73]
	v_add_u32_e32 v212, 0x50010, v194
	v_mov_b32_e32 v213, v159
	v_pk_fma_f32 v[138:139], v[130:131], s[78:79], v[138:139] op_sel_hi:[1,0,1]
	v_pk_fma_f32 v[136:137], v[128:129], s[78:79], v[136:137] op_sel_hi:[1,0,1]
	v_lshl_add_u64 v[212:213], v[212:213], 2, s[90:91]
	global_store_dwordx4 v[212:213], v[136:139], off
	s_nop 1
	v_sub_f32_e32 v137, v207, v242
	v_sub_f32_e32 v136, v206, v242
	v_sub_f32_e32 v139, v209, v242
	v_sub_f32_e32 v138, v208, v242
	v_pk_mul_f32 v[136:137], v[242:243], v[136:137] op_sel:[1,0]
	v_pk_mul_f32 v[138:139], v[242:243], v[138:139] op_sel:[1,0]
	v_pk_fma_f32 v[136:137], v[154:155], v[136:137], v[68:69]
	v_pk_fma_f32 v[138:139], v[152:153], v[138:139], v[70:71]
	v_pk_fma_f32 v[132:133], v[132:133], s[78:79], v[136:137] op_sel_hi:[1,0,1]
	v_add_u32_e32 v136, 0x58000, v194
	v_mov_b32_e32 v137, v159
	v_pk_fma_f32 v[134:135], v[134:135], s[78:79], v[138:139] op_sel_hi:[1,0,1]
	v_lshl_add_u64 v[136:137], v[136:137], 2, s[90:91]
	global_store_dwordx4 v[136:137], v[132:135], off
	s_nop 1
	v_sub_f32_e32 v133, v217, v242
	v_sub_f32_e32 v132, v216, v242
	v_sub_f32_e32 v135, v219, v242
	v_sub_f32_e32 v134, v218, v242
	v_pk_mul_f32 v[132:133], v[242:243], v[132:133] op_sel:[1,0]
	v_pk_mul_f32 v[134:135], v[242:243], v[134:135] op_sel:[1,0]
	v_pk_fma_f32 v[132:133], v[150:151], v[132:133], v[64:65]
	v_pk_fma_f32 v[134:135], v[148:149], v[134:135], v[66:67]
	v_pk_fma_f32 v[128:129], v[128:129], s[78:79], v[132:133] op_sel_hi:[1,0,1]
	v_add_u32_e32 v132, 0x58010, v194
	v_mov_b32_e32 v133, v159
	v_pk_fma_f32 v[130:131], v[130:131], s[78:79], v[134:135] op_sel_hi:[1,0,1]
	v_lshl_add_u64 v[132:133], v[132:133], 2, s[90:91]
	global_store_dwordx4 v[132:133], v[128:131], off
	global_load_dwordx4 v[128:131], v[140:141], off offset:512
	v_add_u32_e32 v136, v232, v230
	v_mov_b32_e32 v137, v159
	v_lshl_add_u64 v[136:137], v[136:137], 2, s[88:89]
	s_waitcnt vmcnt(0)
;     template <bool LN, int BJ, int LO, int HI> DI void batch(const f32x4 (&acc)[2][2][4][2], unsigned row0, unsigned col0, const f32x4 (&gv)[2], const f32x4 (&bv)[2]) const {
;         f32x4 r[HI - LO]; float mean[(HI - LO) / 2], rstd[(HI - LO) / 2];
; #pragma unroll
;         for (int i = LO; i < HI; ++i) { const int ai = i >> 3, m = (i >> 1) & 3, n = i & 1; const unsigned row = row0 + ai * HALF + m * 16;
;             if (n == 0) { mean[(i - LO) >> 1] = 0.f; rstd[(i - LO) >> 1] = 1.f;
;                 if (LN) { const float2 st = *(const float2*)(stats + row * 2u); mean[(i - LO) >> 1] = st.x; rstd[(i - LO) >> 1] = st.y; } }
;             r[i - LO] = *(const f32x4*)(src + (row * (unsigned)DM + col0 + BJ * HALF + n * 16)); }
; #pragma unroll
;         for (int i = LO; i < HI; ++i) { const int ai = i >> 3, m = (i >> 1) & 3, n = i & 1; const unsigned row = row0 + ai * HALF + m * 16;
;             *(f32x4*)(Y + (row * (unsigned)DM + col0 + BJ * HALF + n * 16)) = acc[ai][BJ][m][n] + ((r[i - LO] - mean[(i - LO) >> 1]) * rstd[(i - LO) >> 1]) * gv[n] + bv[n]; }
;         __builtin_amdgcn_sched_barrier(0);
;     }
;     template <bool LN, int BJ> DI void load_gb(unsigned col0, f32x4 (&gv)[2], f32x4 (&bv)[2]) const {
; #pragma unroll
;         for (int n = 0; n < 2; ++n) {
;             if (LN) { gv[n] = *(const f32x4*)(gam + col0 + BJ * HALF + n * 16) * ALPHA; bv[n] = *(const f32x4*)(bet + col0 + BJ * HALF + n * 16) * ALPHA; }
;             else { gv[n] = (f32x4){ALPHA, ALPHA, ALPHA, ALPHA}; bv[n] = (f32x4){0.f, 0.f, 0.f, 0.f}; }
;         }
;     }
	v_pk_mul_f32 v[212:213], v[130:131], s[78:79] op_sel_hi:[1,0]
	v_pk_mul_f32 v[214:215], v[128:129], s[78:79] op_sel_hi:[1,0]
	global_load_dwordx4 v[132:135], v[142:143], off offset:512
	global_load_dwordx4 v[128:131], v[140:141], off offset:576
	s_waitcnt vmcnt(0)
	v_pk_mul_f32 v[206:207], v[130:131], s[78:79] op_sel_hi:[1,0]
	v_pk_mul_f32 v[208:209], v[128:129], s[78:79] op_sel_hi:[1,0]
	global_load_dwordx4 v[128:131], v[142:143], off offset:576
	global_load_dwordx2 v[220:221], v[144:145], off
	global_load_dwordx4 v[240:243], v[136:137], off
	v_add_u32_e32 v136, v232, v229
	v_mov_b32_e32 v137, v159
	v_lshl_add_u64 v[136:137], v[136:137], 2, s[88:89]
	global_load_dwordx4 v[244:247], v[136:137], off
	global_load_dwordx2 v[218:219], v[146:147], off
	v_add_u32_e32 v136, v195, v230
	v_mov_b32_e32 v137, v159
	v_lshl_add_u64 v[136:137], v[136:137], 2, s[88:89]
	global_load_dwordx4 v[248:251], v[136:137], off
	v_add_u32_e32 v136, v195, v229
	v_mov_b32_e32 v137, v159
	v_lshl_add_u64 v[136:137], v[136:137], 2, s[88:89]
	global_load_dwordx4 v[152:155], v[136:137], off
	global_load_dwordx2 v[216:217], v[200:201], off
	v_add_u32_e32 v136, v236, v230
	v_mov_b32_e32 v137, v159
	v_lshl_add_u64 v[136:137], v[136:137], 2, s[88:89]
	global_load_dwordx4 v[148:151], v[136:137], off
	v_add_u32_e32 v136, v236, v229
	v_mov_b32_e32 v137, v159
	v_lshl_add_u64 v[136:137], v[136:137], 2, s[88:89]
	global_load_dwordx4 v[144:147], v[136:137], off
	global_load_dwordx2 v[200:201], v[202:203], off
	v_add_u32_e32 v136, v235, v230
	v_mov_b32_e32 v137, v159
	v_lshl_add_u64 v[136:137], v[136:137], 2, s[88:89]
	global_load_dwordx4 v[140:143], v[136:137], off
	v_add_u32_e32 v136, v235, v229
	v_mov_b32_e32 v137, v159
	v_lshl_add_u64 v[136:137], v[136:137], 2, s[88:89]
	global_load_dwordx4 v[136:139], v[136:137], off
	v_add_u32_e32 v202, 0x80, v194
	v_mov_b32_e32 v203, v159
	v_lshl_add_u64 v[202:203], v[202:203], 2, s[90:91]
	s_waitcnt vmcnt(0)
	v_sub_f32_e32 v241, v241, v220
	v_sub_f32_e32 v240, v240, v220
	v_sub_f32_e32 v243, v243, v220
	v_sub_f32_e32 v242, v242, v220
	v_pk_mul_f32 v[242:243], v[220:221], v[242:243] op_sel:[1,0]
	v_pk_mul_f32 v[240:241], v[220:221], v[240:241] op_sel:[1,0]
	v_pk_fma_f32 v[242:243], v[212:213], v[242:243], v[62:63]
	v_pk_fma_f32 v[240:241], v[214:215], v[240:241], v[60:61]
	v_pk_fma_f32 v[242:243], v[134:135], s[78:79], v[242:243] op_sel_hi:[1,0,1]
	v_pk_fma_f32 v[240:241], v[132:133], s[78:79], v[240:241] op_sel_hi:[1,0,1]
	global_store_dwordx4 v[202:203], v[240:243], off
	v_sub_f32_e32 v203, v245, v220
	v_sub_f32_e32 v202, v244, v220
	v_sub_f32_e32 v241, v247, v220
	v_sub_f32_e32 v240, v246, v220
	v_pk_mul_f32 v[202:203], v[220:221], v[202:203] op_sel:[1,0]
	v_pk_mul_f32 v[240:241], v[220:221], v[240:241] op_sel:[1,0]
	v_pk_fma_f32 v[202:203], v[208:209], v[202:203], v[56:57]
	v_pk_fma_f32 v[220:221], v[206:207], v[240:241], v[58:59]
	v_pk_fma_f32 v[240:241], v[128:129], s[78:79], v[202:203] op_sel_hi:[1,0,1]
	v_add_u32_e32 v202, 0x90, v194
	v_mov_b32_e32 v203, v159
	v_pk_fma_f32 v[242:243], v[130:131], s[78:79], v[220:221] op_sel_hi:[1,0,1]
	v_lshl_add_u64 v[202:203], v[202:203], 2, s[90:91]
	global_store_dwordx4 v[202:203], v[240:243], off
	v_sub_f32_e32 v203, v249, v218
	v_sub_f32_e32 v202, v248, v218
	v_sub_f32_e32 v221, v251, v218
	v_sub_f32_e32 v220, v250, v218
	v_pk_mul_f32 v[202:203], v[218:219], v[202:203] op_sel:[1,0]
	v_pk_mul_f32 v[220:221], v[218:219], v[220:221] op_sel:[1,0]
	v_pk_fma_f32 v[202:203], v[214:215], v[202:203], v[52:53]
	v_pk_fma_f32 v[220:221], v[212:213], v[220:221], v[54:55]
	v_pk_fma_f32 v[240:241], v[132:133], s[78:79], v[202:203] op_sel_hi:[1,0,1]
	v_add_u32_e32 v202, 0x8080, v194
	v_mov_b32_e32 v203, v159
	v_sub_f32_e32 v153, v153, v218
	v_sub_f32_e32 v152, v152, v218
	v_sub_f32_e32 v155, v155, v218
	v_sub_f32_e32 v154, v154, v218
	v_pk_fma_f32 v[242:243], v[134:135], s[78:79], v[220:221] op_sel_hi:[1,0,1]
	v_lshl_add_u64 v[202:203], v[202:203], 2, s[90:91]
	v_pk_mul_f32 v[154:155], v[218:219], v[154:155] op_sel:[1,0]
	v_pk_mul_f32 v[152:153], v[218:219], v[152:153] op_sel:[1,0]
	global_store_dwordx4 v[202:203], v[240:243], off
	v_pk_fma_f32 v[152:153], v[208:209], v[152:153], v[48:49]
	v_pk_fma_f32 v[154:155], v[206:207], v[154:155], v[50:51]
	v_add_u32_e32 v202, 0x8090, v194
	v_mov_b32_e32 v203, v159
	v_sub_f32_e32 v149, v149, v216
	v_sub_f32_e32 v148, v148, v216
	v_sub_f32_e32 v151, v151, v216
	v_sub_f32_e32 v150, v150, v216
	v_pk_fma_f32 v[154:155], v[130:131], s[78:79], v[154:155] op_sel_hi:[1,0,1]
	v_pk_fma_f32 v[152:153], v[128:129], s[78:79], v[152:153] op_sel_hi:[1,0,1]
	v_lshl_add_u64 v[202:203], v[202:203], 2, s[90:91]
	v_pk_mul_f32 v[150:151], v[216:217], v[150:151] op_sel:[1,0]
	v_pk_mul_f32 v[148:149], v[216:217], v[148:149] op_sel:[1,0]
	global_store_dwordx4 v[202:203], v[152:155], off
	v_pk_fma_f32 v[148:149], v[214:215], v[148:149], v[44:45]
	v_pk_fma_f32 v[150:151], v[212:213], v[150:151], v[46:47]
	v_add_u32_e32 v152, 0x10080, v194
	v_mov_b32_e32 v153, v159
	v_sub_f32_e32 v145, v145, v216
	v_sub_f32_e32 v144, v144, v216
	v_sub_f32_e32 v147, v147, v216
	v_sub_f32_e32 v146, v146, v216
	v_pk_fma_f32 v[150:151], v[134:135], s[78:79], v[150:151] op_sel_hi:[1,0,1]
	v_pk_fma_f32 v[148:149], v[132:133], s[78:79], v[148:149] op_sel_hi:[1,0,1]
	v_lshl_add_u64 v[152:153], v[152:153], 2, s[90:91]
	v_pk_mul_f32 v[146:147], v[216:217], v[146:147] op_sel:[1,0]
	v_pk_mul_f32 v[144:145], v[216:217], v[144:145] op_sel:[1,0]
	global_store_dwordx4 v[152:153], v[148:151], off
	v_pk_fma_f32 v[144:145], v[208:209], v[144:145], v[40:41]
	v_pk_fma_f32 v[146:147], v[206:207], v[146:147], v[42:43]
;     template <bool LN, int BJ, int LO, int HI> DI void batch(const f32x4 (&acc)[2][2][4][2], unsigned row0, unsigned col0, const f32x4 (&gv)[2], const f32x4 (&bv)[2]) const {
;         f32x4 r[HI - LO]; float mean[(HI - LO) / 2], rstd[(HI - LO) / 2];
; #pragma unroll
;         for (int i = LO; i < HI; ++i) { const int ai = i >> 3, m = (i >> 1) & 3, n = i & 1; const unsigned row = row0 + ai * HALF + m * 16;
;             if (n == 0) { mean[(i - LO) >> 1] = 0.f; rstd[(i - LO) >> 1] = 1.f;
;                 if (LN) { const float2 st = *(const float2*)(stats + row * 2u); mean[(i - LO) >> 1] = st.x; rstd[(i - LO) >> 1] = st.y; } }
;             r[i - LO] = *(const f32x4*)(src + (row * (unsigned)DM + col0 + BJ * HALF + n * 16)); }
; #pragma unroll
;         for (int i = LO; i < HI; ++i) { const int ai = i >> 3, m = (i >> 1) & 3, n = i & 1; const unsigned row = row0 + ai * HALF + m * 16;
;             *(f32x4*)(Y + (row * (unsigned)DM + col0 + BJ * HALF + n * 16)) = acc[ai][BJ][m][n] + ((r[i - LO] - mean[(i - LO) >> 1]) * rstd[(i - LO) >> 1]) * gv[n] + bv[n]; }
	v_add_u32_e32 v148, 0x10090, v194
	v_mov_b32_e32 v149, v159
	v_sub_f32_e32 v141, v141, v200
	v_sub_f32_e32 v140, v140, v200
	v_sub_f32_e32 v143, v143, v200
	v_sub_f32_e32 v142, v142, v200
	v_pk_fma_f32 v[146:147], v[130:131], s[78:79], v[146:147] op_sel_hi:[1,0,1]
	v_pk_fma_f32 v[144:145], v[128:129], s[78:79], v[144:145] op_sel_hi:[1,0,1]
	v_lshl_add_u64 v[148:149], v[148:149], 2, s[90:91]
	v_pk_mul_f32 v[142:143], v[200:201], v[142:143] op_sel:[1,0]
	v_pk_mul_f32 v[140:141], v[200:201], v[140:141] op_sel:[1,0]
	global_store_dwordx4 v[148:149], v[144:147], off
	v_pk_fma_f32 v[140:141], v[214:215], v[140:141], v[36:37]
	v_pk_fma_f32 v[142:143], v[212:213], v[142:143], v[38:39]
	v_add_u32_e32 v144, 0x18080, v194
	v_mov_b32_e32 v145, v159
	v_sub_f32_e32 v137, v137, v200
	v_sub_f32_e32 v136, v136, v200
	v_sub_f32_e32 v139, v139, v200
	v_sub_f32_e32 v138, v138, v200
	v_pk_fma_f32 v[142:143], v[134:135], s[78:79], v[142:143] op_sel_hi:[1,0,1]
	v_pk_fma_f32 v[140:141], v[132:133], s[78:79], v[140:141] op_sel_hi:[1,0,1]
	v_lshl_add_u64 v[144:145], v[144:145], 2, s[90:91]
	v_pk_mul_f32 v[138:139], v[200:201], v[138:139] op_sel:[1,0]
	v_pk_mul_f32 v[136:137], v[200:201], v[136:137] op_sel:[1,0]
	global_store_dwordx4 v[144:145], v[140:143], off
	v_pk_fma_f32 v[136:137], v[208:209], v[136:137], v[32:33]
	v_pk_fma_f32 v[138:139], v[206:207], v[138:139], v[34:35]
	v_add_u32_e32 v140, 0x18090, v194
	v_mov_b32_e32 v141, v159
	v_pk_fma_f32 v[138:139], v[130:131], s[78:79], v[138:139] op_sel_hi:[1,0,1]
	v_pk_fma_f32 v[136:137], v[128:129], s[78:79], v[136:137] op_sel_hi:[1,0,1]
	v_lshl_add_u64 v[140:141], v[140:141], 2, s[90:91]
	global_store_dwordx4 v[140:141], v[136:139], off
	s_nop 1
	v_add_u32_e32 v136, v233, v230
	v_mov_b32_e32 v137, v159
	v_lshl_add_u64 v[136:137], v[136:137], 2, s[88:89]
	global_load_dwordx2 v[220:221], v[196:197], off
	global_load_dwordx4 v[216:219], v[136:137], off
	v_add_u32_e32 v136, v233, v229
	v_mov_b32_e32 v137, v159
	v_lshl_add_u64 v[136:137], v[136:137], 2, s[88:89]
	global_load_dwordx4 v[240:243], v[136:137], off
	global_load_dwordx2 v[200:201], v[198:199], off
	v_add_u32_e32 v136, v234, v230
	v_mov_b32_e32 v137, v159
	v_lshl_add_u64 v[136:137], v[136:137], 2, s[88:89]
	global_load_dwordx4 v[244:247], v[136:137], off
	v_add_u32_e32 v136, v234, v229
	v_mov_b32_e32 v137, v159
	v_lshl_add_u64 v[136:137], v[136:137], 2, s[88:89]
	global_load_dwordx4 v[152:155], v[136:137], off
	global_load_dwordx2 v[198:199], v[204:205], off
	v_add_u32_e32 v136, v237, v230
	v_mov_b32_e32 v137, v159
	v_lshl_add_u64 v[136:137], v[136:137], 2, s[88:89]
	global_load_dwordx4 v[148:151], v[136:137], off
	v_add_u32_e32 v136, v237, v229
	v_mov_b32_e32 v137, v159
	v_lshl_add_u64 v[136:137], v[136:137], 2, s[88:89]
	global_load_dwordx4 v[144:147], v[136:137], off
	global_load_dwordx2 v[196:197], v[210:211], off
	v_add_u32_e32 v136, v238, v230
	v_mov_b32_e32 v137, v159
	v_lshl_add_u64 v[136:137], v[136:137], 2, s[88:89]
	global_load_dwordx4 v[140:143], v[136:137], off
	v_add_u32_e32 v136, v238, v229
	v_mov_b32_e32 v137, v159
	v_lshl_add_u64 v[136:137], v[136:137], 2, s[88:89]
	global_load_dwordx4 v[136:139], v[136:137], off
	v_add_u32_e32 v210, 0x40080, v194
	v_mov_b32_e32 v211, v159
	v_lshl_add_u64 v[210:211], v[210:211], 2, s[90:91]
	s_waitcnt vmcnt(0)
;     template <bool LN, int BJ, int LO, int HI> DI void batch(const f32x4 (&acc)[2][2][4][2], unsigned row0, unsigned col0, const f32x4 (&gv)[2], const f32x4 (&bv)[2]) const {
;         f32x4 r[HI - LO]; float mean[(HI - LO) / 2], rstd[(HI - LO) / 2];
; #pragma unroll
;         for (int i = LO; i < HI; ++i) { const int ai = i >> 3, m = (i >> 1) & 3, n = i & 1; const unsigned row = row0 + ai * HALF + m * 16;
;             if (n == 0) { mean[(i - LO) >> 1] = 0.f; rstd[(i - LO) >> 1] = 1.f;
;                 if (LN) { const float2 st = *(const float2*)(stats + row * 2u); mean[(i - LO) >> 1] = st.x; rstd[(i - LO) >> 1] = st.y; } }
;             r[i - LO] = *(const f32x4*)(src + (row * (unsigned)DM + col0 + BJ * HALF + n * 16)); }
; #pragma unroll
;         for (int i = LO; i < HI; ++i) { const int ai = i >> 3, m = (i >> 1) & 3, n = i & 1; const unsigned row = row0 + ai * HALF + m * 16;
;             *(f32x4*)(Y + (row * (unsigned)DM + col0 + BJ * HALF + n * 16)) = acc[ai][BJ][m][n] + ((r[i - LO] - mean[(i - LO) >> 1]) * rstd[(i - LO) >> 1]) * gv[n] + bv[n]; }
	v_sub_f32_e32 v203, v217, v220
	v_sub_f32_e32 v202, v216, v220
	v_sub_f32_e32 v205, v219, v220
	v_sub_f32_e32 v204, v218, v220
	v_pk_mul_f32 v[204:205], v[220:221], v[204:205] op_sel:[1,0]
	v_pk_mul_f32 v[202:203], v[220:221], v[202:203] op_sel:[1,0]
	v_pk_fma_f32 v[204:205], v[212:213], v[204:205], v[30:31]
	v_pk_fma_f32 v[202:203], v[214:215], v[202:203], v[28:29]
	v_pk_fma_f32 v[204:205], v[134:135], s[78:79], v[204:205] op_sel_hi:[1,0,1]
	v_pk_fma_f32 v[202:203], v[132:133], s[78:79], v[202:203] op_sel_hi:[1,0,1]
	global_store_dwordx4 v[210:211], v[202:205], off
	v_add_u32_e32 v210, 0x40090, v194
	v_mov_b32_e32 v211, v159
	v_sub_f32_e32 v203, v241, v220
	v_sub_f32_e32 v202, v240, v220
	v_sub_f32_e32 v205, v243, v220
	v_sub_f32_e32 v204, v242, v220
	v_pk_mul_f32 v[204:205], v[220:221], v[204:205] op_sel:[1,0]
	v_pk_mul_f32 v[202:203], v[220:221], v[202:203] op_sel:[1,0]
	v_pk_fma_f32 v[204:205], v[206:207], v[204:205], v[26:27]
	v_pk_fma_f32 v[202:203], v[208:209], v[202:203], v[24:25]
	v_pk_fma_f32 v[204:205], v[130:131], s[78:79], v[204:205] op_sel_hi:[1,0,1]
	v_pk_fma_f32 v[202:203], v[128:129], s[78:79], v[202:203] op_sel_hi:[1,0,1]
	v_lshl_add_u64 v[210:211], v[210:211], 2, s[90:91]
	global_store_dwordx4 v[210:211], v[202:205], off
	v_sub_f32_e32 v149, v149, v198
	v_sub_f32_e32 v148, v148, v198
	v_sub_f32_e32 v203, v245, v200
	v_sub_f32_e32 v202, v244, v200
	v_sub_f32_e32 v141, v141, v196
	v_sub_f32_e32 v140, v140, v196
	v_sub_f32_e32 v205, v247, v200
	v_sub_f32_e32 v204, v246, v200
	v_pk_mul_f32 v[202:203], v[200:201], v[202:203] op_sel:[1,0]
	v_sub_f32_e32 v151, v151, v198
	v_sub_f32_e32 v150, v150, v198
	v_pk_mul_f32 v[148:149], v[198:199], v[148:149] op_sel:[1,0]
	v_sub_f32_e32 v143, v143, v196
	v_sub_f32_e32 v142, v142, v196
	v_pk_mul_f32 v[140:141], v[196:197], v[140:141] op_sel:[1,0]
	v_pk_mul_f32 v[204:205], v[200:201], v[204:205] op_sel:[1,0]
	v_pk_fma_f32 v[202:203], v[214:215], v[202:203], v[20:21]
	v_sub_f32_e32 v153, v153, v200
	v_sub_f32_e32 v152, v152, v200
	v_sub_f32_e32 v155, v155, v200
	v_sub_f32_e32 v154, v154, v200
	v_pk_mul_f32 v[150:151], v[198:199], v[150:151] op_sel:[1,0]
	v_pk_fma_f32 v[148:149], v[214:215], v[148:149], v[12:13]
	v_pk_mul_f32 v[142:143], v[196:197], v[142:143] op_sel:[1,0]
	v_pk_fma_f32 v[140:141], v[214:215], v[140:141], v[4:5]
	v_pk_fma_f32 v[204:205], v[212:213], v[204:205], v[22:23]
	v_pk_fma_f32 v[202:203], v[132:133], s[78:79], v[202:203] op_sel_hi:[1,0,1]
	v_pk_mul_f32 v[154:155], v[200:201], v[154:155] op_sel:[1,0]
	v_pk_mul_f32 v[152:153], v[200:201], v[152:153] op_sel:[1,0]
	v_pk_fma_f32 v[150:151], v[212:213], v[150:151], v[14:15]
	v_pk_fma_f32 v[148:149], v[132:133], s[78:79], v[148:149] op_sel_hi:[1,0,1]
	v_pk_fma_f32 v[142:143], v[212:213], v[142:143], v[6:7]
	v_pk_fma_f32 v[132:133], v[132:133], s[78:79], v[140:141] op_sel_hi:[1,0,1]
	v_add_u32_e32 v140, 0x58080, v194
	v_mov_b32_e32 v141, v159
	v_pk_fma_f32 v[204:205], v[134:135], s[78:79], v[204:205] op_sel_hi:[1,0,1]
	v_pk_fma_f32 v[152:153], v[208:209], v[152:153], v[16:17]
	v_pk_fma_f32 v[154:155], v[206:207], v[154:155], v[18:19]
	v_add_u32_e32 v200, 0x48090, v194
	v_mov_b32_e32 v201, v159
	v_pk_fma_f32 v[150:151], v[134:135], s[78:79], v[150:151] op_sel_hi:[1,0,1]
	v_pk_fma_f32 v[134:135], v[134:135], s[78:79], v[142:143] op_sel_hi:[1,0,1]
	v_lshl_add_u64 v[140:141], v[140:141], 2, s[90:91]
	v_pk_fma_f32 v[154:155], v[130:131], s[78:79], v[154:155] op_sel_hi:[1,0,1]
	v_pk_fma_f32 v[152:153], v[128:129], s[78:79], v[152:153] op_sel_hi:[1,0,1]
	v_lshl_add_u64 v[200:201], v[200:201], 2, s[90:91]
	v_sub_f32_e32 v145, v145, v198
	v_sub_f32_e32 v144, v144, v198
	global_store_dwordx4 v[140:141], v[132:135], off
	global_store_dwordx4 v[200:201], v[152:155], off
	v_sub_f32_e32 v147, v147, v198
	v_sub_f32_e32 v133, v137, v196
	v_sub_f32_e32 v132, v136, v196
	v_add_u32_e32 v152, 0x50080, v194
	v_mov_b32_e32 v153, v159
	v_sub_f32_e32 v146, v146, v198
	v_pk_mul_f32 v[144:145], v[198:199], v[144:145] op_sel:[1,0]
	v_sub_f32_e32 v135, v139, v196
	v_sub_f32_e32 v134, v138, v196
	v_pk_mul_f32 v[132:133], v[196:197], v[132:133] op_sel:[1,0]
	v_lshl_add_u64 v[152:153], v[152:153], 2, s[90:91]
	v_pk_mul_f32 v[146:147], v[198:199], v[146:147] op_sel:[1,0]
	v_pk_fma_f32 v[144:145], v[208:209], v[144:145], v[8:9]
	v_pk_mul_f32 v[134:135], v[196:197], v[134:135] op_sel:[1,0]
	v_pk_fma_f32 v[132:133], v[208:209], v[132:133], v[0:1]
	v_add_u32_e32 v210, 0x48080, v194
	v_mov_b32_e32 v211, v159
	global_store_dwordx4 v[152:153], v[148:151], off
	v_pk_fma_f32 v[146:147], v[206:207], v[146:147], v[10:11]
	v_pk_fma_f32 v[144:145], v[128:129], s[78:79], v[144:145] op_sel_hi:[1,0,1]
	v_add_u32_e32 v148, 0x50090, v194
	v_mov_b32_e32 v149, v159
	v_pk_fma_f32 v[134:135], v[206:207], v[134:135], v[2:3]
	v_pk_fma_f32 v[128:129], v[128:129], s[78:79], v[132:133] op_sel_hi:[1,0,1]
	v_add_u32_e32 v132, 0x58090, v194
	v_mov_b32_e32 v133, v159
	v_lshl_add_u64 v[210:211], v[210:211], 2, s[90:91]
	v_pk_fma_f32 v[146:147], v[130:131], s[78:79], v[146:147] op_sel_hi:[1,0,1]
	v_lshl_add_u64 v[148:149], v[148:149], 2, s[90:91]
	v_pk_fma_f32 v[130:131], v[130:131], s[78:79], v[134:135] op_sel_hi:[1,0,1]
	v_lshl_add_u64 v[132:133], v[132:133], 2, s[90:91]
	global_store_dwordx4 v[210:211], v[202:205], off
	global_store_dwordx4 v[148:149], v[144:147], off
	global_store_dwordx4 v[132:133], v[128:131], off
	s_mov_b64 s[24:25], 0
	s_branch .LBB0_324
